# rg select folded into one multiply; hazard padding extended to MFMA result WAW and SrcC WAR
# baseline (speedup 1.0000x reference)
.LBB0_266:
	s_waitcnt vmcnt(0)
	v_cmp_gt_u32_e64 s[98:99], s45, v204
	v_mul_f32_e32 v240, 0xc1000000, v92
	v_mul_f32_e32 v241, 0xc1000000, v93
	v_mul_f32_e32 v242, 0xc1000000, v94
	v_mul_f32_e32 v243, 0xc1000000, v95
	v_mul_f32_e32 v244, 0xc1000000, v96
	v_mul_f32_e32 v245, 0xc1000000, v97
	v_mul_f32_e32 v246, 0xc1000000, v98
	v_mul_f32_e32 v247, 0xc1000000, v99
	v_cndmask_b32_e64 v240, 1.0, v240, s[98:99]
	v_cndmask_b32_e64 v241, 1.0, v241, s[98:99]
	v_cndmask_b32_e64 v242, 1.0, v242, s[98:99]
	v_cndmask_b32_e64 v243, 1.0, v243, s[98:99]
	v_cndmask_b32_e64 v244, 1.0, v244, s[98:99]
	v_cndmask_b32_e64 v245, 1.0, v245, s[98:99]
	v_cndmask_b32_e64 v246, 1.0, v246, s[98:99]
	v_cndmask_b32_e64 v247, 1.0, v247, s[98:99]
	v_mov_b32_e32 v68, 0
	s_mov_b32 s10, s94
	s_mov_b32 s11, s3
	s_mov_b32 s69, s97
	v_mov_b32_e32 v69, v68
	v_mov_b32_e32 v70, v68
	v_mov_b32_e32 v71, v68
	v_mov_b32_e32 v72, v68
	v_mov_b32_e32 v73, v68
	v_mov_b32_e32 v74, v68
	v_mov_b32_e32 v75, v68
	v_mov_b32_e32 v100, v68
	v_mov_b32_e32 v101, v68
	v_mov_b32_e32 v102, v68
	v_mov_b32_e32 v103, v68
	v_mov_b32_e32 v104, v68
	v_mov_b32_e32 v105, v68
	v_mov_b32_e32 v106, v68
	v_mov_b32_e32 v107, v68
	s_branch .LBB0_269

.LBB0_279:
	v_cndmask_b32_e64 v0, 0, 1, s[30:31]
	v_cmp_ne_u32_e64 s[6:7], 1, v0
	s_andn2_b64 vcc, exec, s[30:31]
	s_cbranch_vccnz .LBB0_281
	s_waitcnt vmcnt(4)
	v_mov_b32_e32 v82, v204
	s_and_b32 s2, s69, 7
	s_lshl_b32 s26, s2, 8
	v_lshlrev_b32_e32 v0, 5, v82
	v_and_b32_e32 v0, 0xe0, v0
	v_or_b32_e32 v0, s26, v0
	v_lshl_add_u64 v[2:3], s[12:13], 0, v[0:1]
	v_add_co_u32_e32 v2, vcc, s1, v2
	v_ashrrev_i32_e32 v60, 7, v82
	global_load_dwordx4 v[4:7], v0, s[12:13] offset:2064
	global_load_dwordx4 v[8:11], v0, s[12:13] offset:2048
	v_addc_co_u32_e32 v3, vcc, 0, v3, vcc
	global_load_dwordx4 v[12:15], v0, s[38:39]
	global_load_dwordx4 v[16:19], v0, s[48:49]
	global_load_dwordx4 v[20:23], v[2:3], off offset:16
	global_load_dwordx4 v[36:39], v[2:3], off offset:2064
	global_load_dwordx4 v[28:31], v0, s[12:13] offset:16
	global_load_dwordx4 v[44:47], v0, s[14:15] offset:16
	global_load_dwordx4 v[32:35], v0, s[12:13]
	global_load_dwordx4 v[48:51], v0, s[14:15]
	v_lshl_or_b32 v2, v60, 3, s2
	v_lshlrev_b32_e32 v60, 11, v60
	v_lshrrev_b32_e32 v0, 1, v82
	v_ashrrev_i32_e32 v3, 31, v2
	v_and_b32_e32 v76, 0x800, v60
	v_mov_b32_e32 v77, v1
	s_waitcnt vmcnt(13)
	v_and_b32_e32 v84, 32, v0
	v_lshlrev_b64 v[2:3], 13, v[2:3]
	v_lshl_add_u64 v[60:61], s[36:37], 0, v[76:77]
	v_lshl_add_u64 v[2:3], s[50:51], 0, v[2:3]
	v_and_b32_e32 v0, 48, v82
	v_lshl_add_u64 v[78:79], v[60:61], 0, s[26:27]
	v_and_or_b32 v60, v82, 15, v84
	v_lshl_add_u64 v[2:3], v[2:3], 0, v[0:1]
	v_lshlrev_b32_e32 v80, 7, v60
	v_mov_b32_e32 v81, v1
	v_lshl_add_u64 v[64:65], v[2:3], 0, v[80:81]
	v_mov_b32_e32 v81, s25
	v_mov_b32_e32 v83, s19
	v_cmp_gt_u32_e32 vcc, s45, v82
	v_mov_b32_e32 v82, s18
	v_lshl_or_b32 v0, v84, 2, v0
	v_cndmask_b32_e32 v83, v81, v83, vcc
	v_mov_b32_e32 v81, s24
	v_cndmask_b32_e32 v82, v81, v82, vcc
	v_lshl_add_u64 v[76:77], v[82:83], 0, v[76:77]
	v_lshl_add_u64 v[76:77], v[76:77], 0, s[26:27]
	s_waitcnt vmcnt(12)
	v_lshl_add_u64 v[88:89], v[76:77], 0, v[0:1]
	s_waitcnt vmcnt(10)
	v_lshl_add_u64 v[96:97], v[78:79], 0, v[0:1]
	v_or_b32_e32 v0, 0x800, v80
	v_lshl_add_u64 v[2:3], v[2:3], 0, v[0:1]
	global_load_dwordx4 v[60:63], v[64:65], off
	s_nop 0
	global_load_dwordx4 v[64:67], v[64:65], off offset:64
	s_nop 0
	global_load_dwordx4 v[76:79], v[2:3], off
	global_load_dwordx4 v[80:83], v[2:3], off offset:64
	global_load_dwordx4 v[84:87], v[88:89], off
	s_nop 0
	global_load_dwordx4 v[88:91], v[88:89], off offset:64
	s_nop 0
	global_load_dwordx4 v[92:95], v[96:97], off
	s_nop 0
	global_load_dwordx4 v[96:99], v[96:97], off offset:64
	s_waitcnt vmcnt(0)
	v_cmp_gt_u32_e64 s[98:99], s45, v204
	v_mul_f32_e32 v240, 0xc1000000, v92
	v_mul_f32_e32 v241, 0xc1000000, v93
	v_mul_f32_e32 v242, 0xc1000000, v94
	v_mul_f32_e32 v243, 0xc1000000, v95
	v_mul_f32_e32 v244, 0xc1000000, v96
	v_mul_f32_e32 v245, 0xc1000000, v97
	v_mul_f32_e32 v246, 0xc1000000, v98
	v_mul_f32_e32 v247, 0xc1000000, v99
	v_cndmask_b32_e64 v240, 1.0, v240, s[98:99]
	v_cndmask_b32_e64 v241, 1.0, v241, s[98:99]
	v_cndmask_b32_e64 v242, 1.0, v242, s[98:99]
	v_cndmask_b32_e64 v243, 1.0, v243, s[98:99]
	v_cndmask_b32_e64 v244, 1.0, v244, s[98:99]
	v_cndmask_b32_e64 v245, 1.0, v245, s[98:99]
	v_cndmask_b32_e64 v246, 1.0, v246, s[98:99]
	v_cndmask_b32_e64 v247, 1.0, v247, s[98:99]
.LBB0_281:
	v_mov_b32_e32 v0, v204
	s_nop 0
	v_and_b32_e32 v3, 0xffff0000, v40
	v_lshlrev_b32_e32 v2, 3, v0
	v_and_b32_e32 v116, 56, v2
	v_lshlrev_b32_e32 v2, 16, v40
	v_pk_fma_f32 v[2:3], v[32:33], v[2:3], v[48:49]
	v_lshlrev_b32_e32 v108, 16, v24
	v_and_b32_e32 v109, 0xffff0000, v24
	v_pk_fma_f32 v[2:3], v[8:9], v[108:109], v[2:3]
	v_lshlrev_b32_e32 v108, 16, v52
	v_and_b32_e32 v109, 0xffff0000, v52
	v_pk_fma_f32 v[2:3], v[12:13], v[108:109], v[2:3]
	v_lshlrev_b32_e32 v108, 16, v56
	v_and_b32_e32 v109, 0xffff0000, v56
	v_pk_fma_f32 v[108:109], v[16:17], v[108:109], v[2:3]
	v_lshlrev_b32_e32 v2, 16, v42
	v_and_b32_e32 v3, 0xffff0000, v42
	v_pk_fma_f32 v[2:3], v[28:29], v[2:3], v[44:45]
	v_lshlrev_b32_e32 v110, 16, v26
	v_and_b32_e32 v111, 0xffff0000, v26
	v_pk_fma_f32 v[2:3], v[4:5], v[110:111], v[2:3]
	v_lshlrev_b32_e32 v110, 16, v54
	v_and_b32_e32 v111, 0xffff0000, v54
	v_pk_fma_f32 v[2:3], v[20:21], v[110:111], v[2:3]
	v_lshlrev_b32_e32 v110, 16, v58
	v_and_b32_e32 v111, 0xffff0000, v58
	v_pk_fma_f32 v[112:113], v[36:37], v[110:111], v[2:3]
	v_lshlrev_b32_e32 v2, 16, v41
	v_and_b32_e32 v3, 0xffff0000, v41
	v_pk_fma_f32 v[2:3], v[34:35], v[2:3], v[50:51]
	v_lshlrev_b32_e32 v110, 16, v25
	v_and_b32_e32 v111, 0xffff0000, v25
	v_pk_fma_f32 v[2:3], v[10:11], v[110:111], v[2:3]
	v_lshlrev_b32_e32 v110, 16, v53
	v_and_b32_e32 v111, 0xffff0000, v53
	v_pk_fma_f32 v[2:3], v[14:15], v[110:111], v[2:3]
	v_lshlrev_b32_e32 v110, 16, v57
	v_and_b32_e32 v111, 0xffff0000, v57
	v_pk_fma_f32 v[110:111], v[18:19], v[110:111], v[2:3]
	v_lshlrev_b32_e32 v2, 16, v43
	v_and_b32_e32 v3, 0xffff0000, v43
	v_pk_fma_f32 v[2:3], v[30:31], v[2:3], v[46:47]
	v_lshlrev_b32_e32 v114, 16, v27
	v_and_b32_e32 v115, 0xffff0000, v27
	v_pk_fma_f32 v[2:3], v[6:7], v[114:115], v[2:3]
	v_lshlrev_b32_e32 v114, 16, v55
	v_and_b32_e32 v115, 0xffff0000, v55
	v_pk_fma_f32 v[2:3], v[22:23], v[114:115], v[2:3]
	v_lshlrev_b32_e32 v114, 16, v59
	v_and_b32_e32 v115, 0xffff0000, v59
	v_pk_fma_f32 v[114:115], v[38:39], v[114:115], v[2:3]
	v_ashrrev_i32_e32 v3, 3, v0
	v_lshl_add_u32 v117, v3, 8, 0
	v_lshl_add_u32 v118, v116, 2, v117
	ds_write_b128 v118, v[108:111]
	ds_write_b128 v118, v[112:115] offset:16
	v_cvt_pk_bf16_f32 v108, v108, v109
	v_cvt_pk_bf16_f32 v109, v110, v111
	v_cvt_pk_bf16_f32 v110, v112, v113
	v_mul_lo_u32 v3, v3, s67
	v_lshlrev_b32_e32 v112, 1, v116
	v_and_b32_e32 v127, 15, v0
	v_cvt_pk_bf16_f32 v111, v114, v115
	v_add3_u32 v3, v117, v3, v112
	v_and_b32_e32 v2, 48, v0
	ds_write_b128 v3, v[108:111] offset:16384
	v_mul_u32_u24_e32 v3, 0x90, v127
	v_add3_u32 v3, 0, v2, v3
	s_waitcnt lgkmcnt(0)
	s_barrier
	ds_read_b128 v[108:111], v3 offset:16384
	ds_read_b128 v[112:115], v3 offset:16448
	ds_read_b128 v[120:123], v3 offset:18688
	ds_read_b128 v[128:131], v3 offset:18752
	s_waitcnt lgkmcnt(1)
	v_mfma_f32_16x16x32_bf16 v[132:135], v[60:63], v[120:123], 0
	s_add_i32 s2, 0, 0xe400
	v_cmp_gt_u32_e32 vcc, s45, v0
	v_lshlrev_b32_e32 v127, 8, v127
	v_mfma_f32_16x16x32_bf16 v[136:139], v[76:79], v[120:123], 0
	ds_read_b128 v[120:123], v3 offset:20992
	ds_read_b128 v[140:143], v3 offset:21056
	v_mfma_f32_16x16x32_bf16 v[116:119], v[60:63], v[108:111], 0
	v_mfma_f32_16x16x32_bf16 v[108:111], v[76:79], v[108:111], 0
	s_waitcnt lgkmcnt(1)
	v_mfma_f32_16x16x32_bf16 v[144:147], v[60:63], v[120:123], 0
	v_mfma_f32_16x16x32_bf16 v[148:151], v[76:79], v[120:123], 0
	ds_read_b128 v[120:123], v3 offset:23296
	ds_read_b128 v[154:157], v3 offset:23360
	v_mov_b32_e32 v3, s2
	v_mfma_f32_16x16x32_bf16 v[166:169], v[64:67], v[112:115], v[116:119]
	s_waitcnt lgkmcnt(1)
	v_mfma_f32_16x16x32_bf16 v[158:161], v[60:63], v[120:123], 0
	v_mfma_f32_16x16x32_bf16 v[162:165], v[76:79], v[120:123], 0
	v_mfma_f32_16x16x32_bf16 v[120:123], v[80:83], v[112:115], v[108:111]
	v_mfma_f32_16x16x32_bf16 v[132:135], v[64:67], v[128:131], v[132:135]
	v_mfma_f32_16x16x32_bf16 v[116:119], v[80:83], v[128:131], v[136:139]
	s_nop 5
	v_add_f32_e32 v122, v90, v122
	v_mul_f32_e32 v122, 0xbfb8aa3b, v122
	v_exp_f32_e32 v122, v122
	v_mfma_f32_16x16x32_bf16 v[128:131], v[64:67], v[140:143], v[144:147]
	v_add_f32_e32 v123, v91, v123
	v_mul_f32_e32 v123, 0xbfb8aa3b, v123
	v_exp_f32_e32 v123, v123
	v_mfma_f32_16x16x32_bf16 v[112:115], v[80:83], v[140:143], v[148:151]
	v_mov_b32_e32 v140, s73
	v_cndmask_b32_e32 v3, v3, v140, vcc
	v_lshlrev_b32_e32 v140, 7, v0
	v_and_b32_e32 v140, 0x4000, v140
	v_add3_u32 v3, v3, v140, v127
	v_add_f32_e32 v140, v84, v166
	v_mul_f32_e32 v140, 0xbfb8aa3b, v140
	v_add_f32_e32 v141, v85, v167
	v_exp_f32_e32 v140, v140
	v_mul_f32_e32 v141, 0xbfb8aa3b, v141
	v_exp_f32_e32 v141, v141
	v_lshlrev_b32_e32 v127, 1, v0
	v_and_b32_e32 v127, 0x80, v127
	v_add_f32_e32 v140, 1.0, v140
	v_rcp_f32_e32 v140, v140
	v_add3_u32 v2, v3, v127, v2
	v_add_f32_e32 v3, 1.0, v141
	v_add_f32_e32 v141, v86, v168
	v_mul_f32_e32 v141, 0xbfb8aa3b, v141
	v_rcp_f32_e32 v3, v3
	v_exp_f32_e32 v141, v141
	v_add_f32_e32 v142, v87, v169
	v_mul_f32_e32 v142, 0xbfb8aa3b, v142

	v_exp_f32_e32 v142, v142

	v_mul_f32_e32 v140, v240, v140

	v_add_f32_e32 v141, 1.0, v141

	v_rcp_f32_e32 v143, v141
	v_mul_f32_e32 v141, v241, v3
	v_add_f32_e32 v3, 1.0, v142
	v_rcp_f32_e32 v3, v3


	v_mul_f32_e32 v142, v242, v143


	v_mul_f32_e32 v143, v243, v3
	v_add_f32_e32 v3, v84, v132
	v_mul_f32_e32 v3, 0xbfb8aa3b, v3
	v_exp_f32_e32 v3, v3
	v_add_f32_e32 v127, v85, v133
	v_mul_f32_e32 v127, 0xbfb8aa3b, v127
	v_exp_f32_e32 v127, v127
	v_add_f32_e32 v3, 1.0, v3
	v_rcp_f32_e32 v3, v3
	v_add_f32_e32 v133, v86, v134
	v_add_f32_e32 v127, 1.0, v127
	v_mul_f32_e32 v133, 0xbfb8aa3b, v133
	v_rcp_f32_e32 v127, v127
	v_exp_f32_e32 v133, v133
	v_add_f32_e32 v134, v87, v135
	v_mul_f32_e32 v134, 0xbfb8aa3b, v134

	v_exp_f32_e32 v134, v134

	v_mul_f32_e32 v132, v240, v3

	v_add_f32_e32 v133, 1.0, v133

	v_rcp_f32_e32 v135, v133
	v_mul_f32_e32 v133, v241, v127
	v_add_f32_e32 v3, 1.0, v134
	v_rcp_f32_e32 v3, v3


	v_mul_f32_e32 v134, v242, v135


	v_mul_f32_e32 v135, v243, v3
	v_add_f32_e32 v3, v84, v128
	v_mul_f32_e32 v3, 0xbfb8aa3b, v3
	v_exp_f32_e32 v3, v3
	v_add_f32_e32 v127, v85, v129
	v_mul_f32_e32 v127, 0xbfb8aa3b, v127
	v_exp_f32_e32 v127, v127
	v_add_f32_e32 v3, 1.0, v3
	v_rcp_f32_e32 v3, v3
	v_add_f32_e32 v129, v86, v130
	v_add_f32_e32 v127, 1.0, v127
	v_mul_f32_e32 v129, 0xbfb8aa3b, v129
	v_rcp_f32_e32 v127, v127
	v_exp_f32_e32 v129, v129
	v_add_f32_e32 v130, v87, v131
	v_mul_f32_e32 v130, 0xbfb8aa3b, v130

	v_exp_f32_e32 v130, v130

	v_mul_f32_e32 v128, v240, v3

	v_add_f32_e32 v129, 1.0, v129

	v_rcp_f32_e32 v131, v129
	v_mul_f32_e32 v129, v241, v127
	v_add_f32_e32 v3, 1.0, v130
	v_rcp_f32_e32 v3, v3
	s_waitcnt lgkmcnt(0)
	v_mfma_f32_16x16x32_bf16 v[136:139], v[64:67], v[154:157], v[158:161]


	v_mul_f32_e32 v130, v242, v131


	v_mul_f32_e32 v131, v243, v3
	s_nop 1
	s_nop 3
	v_add_f32_e32 v3, v84, v136
	v_mul_f32_e32 v3, 0xbfb8aa3b, v3
	v_exp_f32_e32 v3, v3
	v_add_f32_e32 v127, v85, v137
	v_mul_f32_e32 v127, 0xbfb8aa3b, v127
	v_exp_f32_e32 v127, v127
	v_add_f32_e32 v3, 1.0, v3
	v_rcp_f32_e32 v3, v3
	ds_write_b128 v2, v[128:131] offset:8192
	v_add_f32_e32 v129, v86, v138
	v_add_f32_e32 v127, 1.0, v127
	v_mul_f32_e32 v129, 0xbfb8aa3b, v129
	v_rcp_f32_e32 v127, v127
	v_exp_f32_e32 v129, v129
	v_add_f32_e32 v130, v87, v139
	v_mul_f32_e32 v130, 0xbfb8aa3b, v130

	v_exp_f32_e32 v130, v130

	v_mul_f32_e32 v128, v240, v3

	v_add_f32_e32 v129, 1.0, v129

	v_rcp_f32_e32 v131, v129
	v_mul_f32_e32 v129, v241, v127
	v_add_f32_e32 v3, 1.0, v130
	v_rcp_f32_e32 v3, v3


	v_mul_f32_e32 v130, v242, v131


	v_mul_f32_e32 v131, v243, v3
	v_add_f32_e32 v3, v88, v120
	v_mul_f32_e32 v3, 0xbfb8aa3b, v3
	v_exp_f32_e32 v3, v3
	v_add_f32_e32 v120, v89, v121
	v_mul_f32_e32 v120, 0xbfb8aa3b, v120
	v_exp_f32_e32 v120, v120
	v_add_f32_e32 v3, 1.0, v3
	v_rcp_f32_e32 v3, v3
	v_add_f32_e32 v122, 1.0, v122
	v_add_f32_e32 v120, 1.0, v120
	v_rcp_f32_e32 v121, v120


	v_mul_f32_e32 v120, v244, v3


	v_rcp_f32_e32 v122, v122
	v_mul_f32_e32 v121, v245, v121
	v_add_f32_e32 v3, 1.0, v123
	v_rcp_f32_e32 v3, v3


	v_mul_f32_e32 v122, v246, v122


	v_mul_f32_e32 v123, v247, v3
	v_add_f32_e32 v3, v88, v116
	v_mul_f32_e32 v3, 0xbfb8aa3b, v3
	v_exp_f32_e32 v3, v3
	v_add_f32_e32 v116, v89, v117
	v_mul_f32_e32 v116, 0xbfb8aa3b, v116
	v_exp_f32_e32 v116, v116
	v_add_f32_e32 v3, 1.0, v3
	v_rcp_f32_e32 v3, v3
	v_add_f32_e32 v118, v90, v118
	v_add_f32_e32 v116, 1.0, v116
	v_mul_f32_e32 v118, 0xbfb8aa3b, v118
	v_rcp_f32_e32 v117, v116
	v_exp_f32_e32 v118, v118
	v_add_f32_e32 v119, v91, v119
	v_mul_f32_e32 v119, 0xbfb8aa3b, v119

	v_exp_f32_e32 v119, v119

	v_mul_f32_e32 v116, v244, v3

	v_add_f32_e32 v118, 1.0, v118

	v_rcp_f32_e32 v118, v118
	v_mul_f32_e32 v117, v245, v117
	v_add_f32_e32 v3, 1.0, v119
	v_rcp_f32_e32 v3, v3


	v_mul_f32_e32 v118, v246, v118


	v_mul_f32_e32 v119, v247, v3
	v_add_f32_e32 v3, v88, v112
	v_mul_f32_e32 v3, 0xbfb8aa3b, v3
	v_exp_f32_e32 v3, v3
	v_add_f32_e32 v112, v89, v113
	v_mul_f32_e32 v112, 0xbfb8aa3b, v112
	v_exp_f32_e32 v112, v112
	v_add_f32_e32 v3, 1.0, v3
	v_rcp_f32_e32 v3, v3
	v_add_f32_e32 v114, v90, v114
	v_add_f32_e32 v112, 1.0, v112
	v_mul_f32_e32 v114, 0xbfb8aa3b, v114
	v_rcp_f32_e32 v113, v112
	v_exp_f32_e32 v114, v114
	v_add_f32_e32 v115, v91, v115
	v_mul_f32_e32 v115, 0xbfb8aa3b, v115

	v_exp_f32_e32 v115, v115

	v_mul_f32_e32 v112, v244, v3

	v_add_f32_e32 v114, 1.0, v114

	v_rcp_f32_e32 v114, v114
	v_mul_f32_e32 v113, v245, v113
	v_add_f32_e32 v3, 1.0, v115
	v_rcp_f32_e32 v3, v3
	v_mfma_f32_16x16x32_bf16 v[108:111], v[80:83], v[154:157], v[162:165]


	v_mul_f32_e32 v114, v246, v114


	v_mul_f32_e32 v115, v247, v3
	s_nop 1
	s_nop 3
	v_add_f32_e32 v3, v88, v108
	v_mul_f32_e32 v3, 0xbfb8aa3b, v3
	v_exp_f32_e32 v3, v3
	v_add_f32_e32 v108, v89, v109
	v_mul_f32_e32 v108, 0xbfb8aa3b, v108
	v_exp_f32_e32 v108, v108
	v_add_f32_e32 v3, 1.0, v3
	v_rcp_f32_e32 v3, v3
	v_add_f32_e32 v110, v90, v110
	v_add_f32_e32 v108, 1.0, v108
	v_mul_f32_e32 v110, 0xbfb8aa3b, v110
	v_rcp_f32_e32 v109, v108
	v_exp_f32_e32 v110, v110
	v_add_f32_e32 v111, v91, v111
	v_mul_f32_e32 v111, 0xbfb8aa3b, v111

	v_exp_f32_e32 v111, v111

	v_mul_f32_e32 v108, v244, v3

	v_add_f32_e32 v110, 1.0, v110

	v_rcp_f32_e32 v110, v110
	v_mul_f32_e32 v109, v245, v109
	v_add_f32_e32 v3, 1.0, v111
	v_rcp_f32_e32 v3, v3


	v_mul_f32_e32 v110, v246, v110


	v_mul_f32_e32 v111, v247, v3
	ds_write_b128 v2, v[108:111] offset:12352
	v_lshlrev_b32_e32 v3, 2, v0
	v_lshlrev_b32_e32 v108, 4, v0
	ds_write_b128 v2, v[140:143]
	ds_write_b128 v2, v[132:135] offset:4096
	ds_write_b128 v2, v[128:131] offset:12288
	ds_write_b128 v2, v[120:123] offset:64
	ds_write_b128 v2, v[116:119] offset:4160
	ds_write_b128 v2, v[112:115] offset:8256
	v_and_b32_e32 v2, 60, v3
	v_and_b32_e32 v109, 0xffffc000, v108
	v_lshlrev_b32_e32 v2, 2, v2
	v_add_u32_e32 v109, 0, v109
	v_and_b32_e32 v108, 0x3f00, v108
	v_add3_u32 v128, v109, v108, v2
	s_waitcnt lgkmcnt(0)
	s_barrier
	ds_read_b128 v[120:123], v128 offset:25600
	ds_read_b128 v[112:115], v128 offset:58368
	v_add_u32_e32 v127, 0, v2
	v_add_u32_e32 v129, v127, v108
	ds_read_b128 v[116:119], v129
	s_waitcnt lgkmcnt(2)
	v_mul_f32_e32 v108, 0x3fb8aa3b, v120
	v_exp_f32_e32 v108, v108
	v_add_f32_e32 v109, v120, v120
	v_cmp_nlt_f32_e32 vcc, s75, v109
	s_and_saveexec_b64 s[8:9], vcc
	s_xor_b64 s[8:9], exec, s[8:9]
	v_fma_f32 v120, -v108, v108, 1.0
	s_andn2_saveexec_b64 s[8:9], s[8:9]
	v_fmamk_f32 v110, v109, 0x3c088889, v125
	v_fmaak_f32 v110, v109, v110, 0x3e2aaaab
	v_fma_f32 v110, v109, v110, 0.5
	v_fma_f32 v110, v109, v110, 1.0
	v_mul_f32_e64 v120, v110, -v109
	s_or_b64 exec, exec, s[8:9]
	v_mul_f32_e32 v109, 0x3fb8aa3b, v121
	v_exp_f32_e32 v109, v109
	v_add_f32_e32 v110, v121, v121
	v_cmp_nlt_f32_e32 vcc, s75, v110
	s_and_saveexec_b64 s[8:9], vcc
	s_xor_b64 s[8:9], exec, s[8:9]
	v_fma_f32 v121, -v109, v109, 1.0
	s_andn2_saveexec_b64 s[8:9], s[8:9]
	v_fmamk_f32 v111, v110, 0x3c088889, v125
	v_fmaak_f32 v111, v110, v111, 0x3e2aaaab
	v_fma_f32 v111, v110, v111, 0.5
	v_fma_f32 v111, v110, v111, 1.0
	v_mul_f32_e64 v121, v111, -v110
	s_or_b64 exec, exec, s[8:9]
	v_mul_f32_e32 v110, 0x3fb8aa3b, v122
	v_exp_f32_e32 v110, v110
	v_add_f32_e32 v111, v122, v122
	v_cmp_nlt_f32_e32 vcc, s75, v111
	s_and_saveexec_b64 s[8:9], vcc
	s_xor_b64 s[8:9], exec, s[8:9]
	v_fma_f32 v122, -v110, v110, 1.0
	s_andn2_saveexec_b64 s[8:9], s[8:9]
	v_fmamk_f32 v122, v111, 0x3c088889, v125
	v_fmaak_f32 v122, v111, v122, 0x3e2aaaab
	v_fma_f32 v122, v111, v122, 0.5
	v_fma_f32 v122, v111, v122, 1.0
	v_mul_f32_e64 v122, v122, -v111
	s_or_b64 exec, exec, s[8:9]
	v_mul_f32_e32 v111, 0x3fb8aa3b, v123
	v_exp_f32_e32 v111, v111
	v_add_f32_e32 v130, v123, v123
	v_cmp_nlt_f32_e32 vcc, s75, v130
	s_and_saveexec_b64 s[8:9], vcc
	s_xor_b64 s[8:9], exec, s[8:9]
	v_fma_f32 v123, -v111, v111, 1.0
	s_andn2_saveexec_b64 s[8:9], s[8:9]
	v_fmamk_f32 v123, v130, 0x3c088889, v125
	v_fmaak_f32 v123, v130, v123, 0x3e2aaaab
	v_fma_f32 v123, v130, v123, 0.5
	v_fma_f32 v123, v130, v123, 1.0
	v_mul_f32_e64 v123, v123, -v130
	s_or_b64 exec, exec, s[8:9]
	v_max_f32_e32 v120, v120, v120
	v_max_f32_e32 v120, 0, v120
	v_sqrt_f32_e32 v120, v120
	v_max_f32_e32 v121, v121, v121
	v_max_f32_e32 v121, 0, v121
	v_sqrt_f32_e32 v121, v121
	s_waitcnt lgkmcnt(1)
	v_mul_f32_e32 v112, v112, v120
	s_waitcnt lgkmcnt(0)
	v_mul_f32_e32 v112, v116, v112
	v_max_f32_e32 v116, v122, v122
	v_max_f32_e32 v120, v123, v123
	v_max_f32_e32 v116, 0, v116
	v_max_f32_e32 v120, 0, v120
	v_sqrt_f32_e32 v116, v116
	v_sqrt_f32_e32 v120, v120
	v_mul_f32_e32 v113, v113, v121
	v_mul_f32_e32 v113, v117, v113
	v_mul_f32_e32 v114, v114, v116
	v_mul_f32_e32 v115, v115, v120
	v_mul_f32_e32 v114, v118, v114
	v_mul_f32_e32 v115, v119, v115
	ds_write_b128 v128, v[108:111] offset:25600
	ds_write_b128 v128, v[112:115] offset:58368
	v_add_u32_e32 v108, 0x800, v3
	v_and_b32_e32 v109, 0x3ffff000, v108
	v_and_b32_e32 v108, 0xfc0, v108
	v_lshl_add_u32 v109, v109, 2, 0
	v_lshlrev_b32_e32 v108, 2, v108
	v_add3_u32 v130, v109, v108, v2
	ds_read_b128 v[120:123], v130 offset:25600
	ds_read_b128 v[112:115], v130 offset:58368
	v_add_u32_e32 v108, v127, v108
	ds_read_b128 v[116:119], v108
	s_waitcnt lgkmcnt(2)
	v_mul_f32_e32 v108, 0x3fb8aa3b, v120
	v_exp_f32_e32 v108, v108
	v_add_f32_e32 v109, v120, v120
	v_cmp_nlt_f32_e32 vcc, s75, v109
	s_and_saveexec_b64 s[8:9], vcc
	s_xor_b64 s[8:9], exec, s[8:9]
	v_fma_f32 v120, -v108, v108, 1.0
	s_andn2_saveexec_b64 s[8:9], s[8:9]
	v_fmamk_f32 v110, v109, 0x3c088889, v125
	v_fmaak_f32 v110, v109, v110, 0x3e2aaaab
	v_fma_f32 v110, v109, v110, 0.5
	v_fma_f32 v110, v109, v110, 1.0
	v_mul_f32_e64 v120, v110, -v109
	s_or_b64 exec, exec, s[8:9]
	v_mul_f32_e32 v109, 0x3fb8aa3b, v121
	v_exp_f32_e32 v109, v109
	v_add_f32_e32 v110, v121, v121
	v_cmp_nlt_f32_e32 vcc, s75, v110
	s_and_saveexec_b64 s[8:9], vcc
	s_xor_b64 s[8:9], exec, s[8:9]
	v_fma_f32 v121, -v109, v109, 1.0
	s_andn2_saveexec_b64 s[8:9], s[8:9]
	v_fmamk_f32 v111, v110, 0x3c088889, v125
	v_fmaak_f32 v111, v110, v111, 0x3e2aaaab
	v_fma_f32 v111, v110, v111, 0.5
	v_fma_f32 v111, v110, v111, 1.0
	v_mul_f32_e64 v121, v111, -v110
	s_or_b64 exec, exec, s[8:9]
	v_mul_f32_e32 v110, 0x3fb8aa3b, v122
	v_exp_f32_e32 v110, v110
	v_add_f32_e32 v111, v122, v122
	v_cmp_nlt_f32_e32 vcc, s75, v111
	s_and_saveexec_b64 s[8:9], vcc
	s_xor_b64 s[8:9], exec, s[8:9]
	v_fma_f32 v122, -v110, v110, 1.0
	s_andn2_saveexec_b64 s[8:9], s[8:9]
	v_fmamk_f32 v122, v111, 0x3c088889, v125
	v_fmaak_f32 v122, v111, v122, 0x3e2aaaab
	v_fma_f32 v122, v111, v122, 0.5
	v_fma_f32 v122, v111, v122, 1.0
	v_mul_f32_e64 v122, v122, -v111
	s_or_b64 exec, exec, s[8:9]
	v_mul_f32_e32 v111, 0x3fb8aa3b, v123
	v_exp_f32_e32 v111, v111
	v_add_f32_e32 v131, v123, v123
	v_cmp_nlt_f32_e32 vcc, s75, v131
	s_and_saveexec_b64 s[8:9], vcc
	s_xor_b64 s[8:9], exec, s[8:9]
	v_fma_f32 v123, -v111, v111, 1.0
	s_andn2_saveexec_b64 s[8:9], s[8:9]
	v_fmamk_f32 v123, v131, 0x3c088889, v125
	v_fmaak_f32 v123, v131, v123, 0x3e2aaaab
	v_fma_f32 v123, v131, v123, 0.5
	v_fma_f32 v123, v131, v123, 1.0
	v_mul_f32_e64 v123, v123, -v131
	s_or_b64 exec, exec, s[8:9]
	v_max_f32_e32 v120, v120, v120
	v_max_f32_e32 v120, 0, v120
	v_sqrt_f32_e32 v120, v120
	v_max_f32_e32 v121, v121, v121
	v_max_f32_e32 v121, 0, v121
	v_sqrt_f32_e32 v121, v121
	s_waitcnt lgkmcnt(1)
	v_mul_f32_e32 v112, v112, v120
	s_waitcnt lgkmcnt(0)
	v_mul_f32_e32 v112, v116, v112
	v_max_f32_e32 v116, v122, v122
	v_max_f32_e32 v120, v123, v123
	v_max_f32_e32 v116, 0, v116
	v_max_f32_e32 v120, 0, v120
	v_sqrt_f32_e32 v116, v116
	v_sqrt_f32_e32 v120, v120
	v_mul_f32_e32 v113, v113, v121
	v_mul_f32_e32 v113, v117, v113
	v_mul_f32_e32 v114, v114, v116
	v_mul_f32_e32 v115, v115, v120
	v_mul_f32_e32 v114, v118, v114
	v_mul_f32_e32 v115, v119, v115
	ds_write_b128 v130, v[108:111] offset:25600
	ds_write_b128 v130, v[112:115] offset:58368
	ds_read_b128 v[120:123], v128 offset:41984
	v_add_u32_e32 v130, 0xe400, v128
	ds_read_b128 v[112:115], v130 offset:16384
	ds_read_b128 v[116:119], v129
	s_waitcnt lgkmcnt(2)
	v_mul_f32_e32 v108, 0x3fb8aa3b, v120
	v_exp_f32_e32 v108, v108
	v_add_f32_e32 v109, v120, v120
	v_cmp_nlt_f32_e32 vcc, s75, v109
	s_and_saveexec_b64 s[8:9], vcc
	s_xor_b64 s[8:9], exec, s[8:9]
	v_fma_f32 v120, -v108, v108, 1.0
	s_andn2_saveexec_b64 s[8:9], s[8:9]
	v_fmamk_f32 v110, v109, 0x3c088889, v125
	v_fmaak_f32 v110, v109, v110, 0x3e2aaaab
	v_fma_f32 v110, v109, v110, 0.5
	v_fma_f32 v110, v109, v110, 1.0
	v_mul_f32_e64 v120, v110, -v109
	s_or_b64 exec, exec, s[8:9]
	v_mul_f32_e32 v109, 0x3fb8aa3b, v121
	v_exp_f32_e32 v109, v109
	v_add_f32_e32 v110, v121, v121
	v_cmp_nlt_f32_e32 vcc, s75, v110
	s_and_saveexec_b64 s[8:9], vcc
	s_xor_b64 s[8:9], exec, s[8:9]
	v_fma_f32 v121, -v109, v109, 1.0
	s_andn2_saveexec_b64 s[8:9], s[8:9]
	v_fmamk_f32 v111, v110, 0x3c088889, v125
	v_fmaak_f32 v111, v110, v111, 0x3e2aaaab
	v_fma_f32 v111, v110, v111, 0.5
	v_fma_f32 v111, v110, v111, 1.0
	v_mul_f32_e64 v121, v111, -v110
	s_or_b64 exec, exec, s[8:9]
	v_mul_f32_e32 v110, 0x3fb8aa3b, v122
	v_exp_f32_e32 v110, v110
	v_add_f32_e32 v111, v122, v122
	v_cmp_nlt_f32_e32 vcc, s75, v111
	s_and_saveexec_b64 s[8:9], vcc
	s_xor_b64 s[8:9], exec, s[8:9]
	v_fma_f32 v122, -v110, v110, 1.0
	s_andn2_saveexec_b64 s[8:9], s[8:9]
	v_fmamk_f32 v122, v111, 0x3c088889, v125
	v_fmaak_f32 v122, v111, v122, 0x3e2aaaab
	v_fma_f32 v122, v111, v122, 0.5
	v_fma_f32 v122, v111, v122, 1.0
	v_mul_f32_e64 v122, v122, -v111
	s_or_b64 exec, exec, s[8:9]
	v_mul_f32_e32 v111, 0x3fb8aa3b, v123
	v_exp_f32_e32 v111, v111
	v_add_f32_e32 v129, v123, v123
	v_cmp_nlt_f32_e32 vcc, s75, v129
	s_and_saveexec_b64 s[8:9], vcc
	s_xor_b64 s[8:9], exec, s[8:9]
	v_fma_f32 v123, -v111, v111, 1.0
	s_andn2_saveexec_b64 s[8:9], s[8:9]
	v_fmamk_f32 v123, v129, 0x3c088889, v125
	v_fmaak_f32 v123, v129, v123, 0x3e2aaaab
	v_fma_f32 v123, v129, v123, 0.5
	v_fma_f32 v123, v129, v123, 1.0
	v_mul_f32_e64 v123, v123, -v129
	s_or_b64 exec, exec, s[8:9]
	v_max_f32_e32 v120, v120, v120
	v_max_f32_e32 v120, 0, v120
	v_sqrt_f32_e32 v120, v120
	v_max_f32_e32 v121, v121, v121
	v_max_f32_e32 v121, 0, v121
	v_sqrt_f32_e32 v121, v121
	s_waitcnt lgkmcnt(1)
	v_mul_f32_e32 v112, v112, v120
	s_waitcnt lgkmcnt(0)
	v_mul_f32_e32 v112, v116, v112
	v_max_f32_e32 v116, v122, v122
	v_max_f32_e32 v120, v123, v123
	v_max_f32_e32 v116, 0, v116
	v_max_f32_e32 v120, 0, v120
	v_sqrt_f32_e32 v116, v116
	v_sqrt_f32_e32 v120, v120
	v_mul_f32_e32 v113, v113, v121
	v_add_u32_e32 v3, 0x1800, v3
	v_mul_f32_e32 v114, v114, v116
	v_mul_f32_e32 v115, v115, v120
	v_mul_f32_e32 v113, v117, v113
	v_mul_f32_e32 v114, v118, v114
	v_mul_f32_e32 v115, v119, v115
	ds_write_b128 v128, v[108:111] offset:41984
	ds_write_b128 v130, v[112:115] offset:16384
	v_and_b32_e32 v108, 0x3ffff000, v3
	v_and_b32_e32 v3, 0xfc0, v3
	v_lshl_add_u32 v108, v108, 2, 0
	v_lshlrev_b32_e32 v3, 2, v3
	v_add3_u32 v2, v108, v3, v2
	ds_read_b128 v[120:123], v2 offset:25600
	ds_read_b128 v[112:115], v2 offset:58368
	v_add_u32_e32 v3, v127, v3
	ds_read_b128 v[116:119], v3
	s_waitcnt lgkmcnt(2)
	v_mul_f32_e32 v3, 0x3fb8aa3b, v120
	v_exp_f32_e32 v108, v3
	v_add_f32_e32 v109, v120, v120
	v_cmp_nlt_f32_e32 vcc, s75, v109
	s_and_saveexec_b64 s[8:9], vcc
	s_xor_b64 s[8:9], exec, s[8:9]
	v_fma_f32 v3, -v108, v108, 1.0
	s_andn2_saveexec_b64 s[8:9], s[8:9]
	v_fmamk_f32 v3, v109, 0x3c088889, v125
	v_fmaak_f32 v3, v109, v3, 0x3e2aaaab
	v_fma_f32 v3, v109, v3, 0.5
	v_fma_f32 v3, v109, v3, 1.0
	v_mul_f32_e64 v3, v3, -v109
	s_or_b64 exec, exec, s[8:9]
	v_mul_f32_e32 v109, 0x3fb8aa3b, v121
	v_exp_f32_e32 v109, v109
	v_add_f32_e32 v110, v121, v121
	v_cmp_nlt_f32_e32 vcc, s75, v110
	s_and_saveexec_b64 s[8:9], vcc
	s_xor_b64 s[8:9], exec, s[8:9]
	v_fma_f32 v121, -v109, v109, 1.0
	s_andn2_saveexec_b64 s[8:9], s[8:9]
	v_fmamk_f32 v111, v110, 0x3c088889, v125
	v_fmaak_f32 v111, v110, v111, 0x3e2aaaab
	v_fma_f32 v111, v110, v111, 0.5
	v_fma_f32 v111, v110, v111, 1.0
	v_mul_f32_e64 v121, v111, -v110
	s_or_b64 exec, exec, s[8:9]
	v_mul_f32_e32 v110, 0x3fb8aa3b, v122
	v_exp_f32_e32 v110, v110
	v_add_f32_e32 v111, v122, v122
	v_cmp_nlt_f32_e32 vcc, s75, v111
	s_and_saveexec_b64 s[8:9], vcc
	s_xor_b64 s[8:9], exec, s[8:9]
	v_fma_f32 v122, -v110, v110, 1.0
	s_andn2_saveexec_b64 s[8:9], s[8:9]
	v_fmamk_f32 v120, v111, 0x3c088889, v125
	v_fmaak_f32 v120, v111, v120, 0x3e2aaaab
	v_fma_f32 v120, v111, v120, 0.5
	v_fma_f32 v120, v111, v120, 1.0
	v_mul_f32_e64 v122, v120, -v111
	s_or_b64 exec, exec, s[8:9]
	v_mul_f32_e32 v111, 0x3fb8aa3b, v123
	v_exp_f32_e32 v111, v111
	v_add_f32_e32 v120, v123, v123
	v_cmp_nlt_f32_e32 vcc, s75, v120
	s_and_saveexec_b64 s[8:9], vcc
	s_xor_b64 s[8:9], exec, s[8:9]
	v_fma_f32 v123, -v111, v111, 1.0
	s_andn2_saveexec_b64 s[8:9], s[8:9]
	v_fmamk_f32 v123, v120, 0x3c088889, v125
	v_fmaak_f32 v123, v120, v123, 0x3e2aaaab
	v_fma_f32 v123, v120, v123, 0.5
	v_fma_f32 v123, v120, v123, 1.0
	v_mul_f32_e64 v123, v123, -v120
	s_or_b64 exec, exec, s[8:9]
	v_max_f32_e32 v3, v3, v3
	v_max_f32_e32 v3, 0, v3
	v_sqrt_f32_e32 v3, v3
	v_max_f32_e32 v121, v121, v121
	v_max_f32_e32 v121, 0, v121
	v_mov_b32_e32 v120, 0
	s_waitcnt lgkmcnt(1)
	v_mul_f32_e32 v3, v112, v3
	v_sqrt_f32_e32 v112, v121
	v_max_f32_e32 v121, v122, v122
	v_max_f32_e32 v121, 0, v121
	v_sqrt_f32_e32 v121, v121
	s_waitcnt lgkmcnt(0)
	v_mul_f32_e32 v116, v116, v3
	v_mul_f32_e32 v3, v113, v112
	v_mul_f32_e32 v117, v117, v3
	v_mul_f32_e32 v3, v114, v121
	v_mul_f32_e32 v118, v118, v3
	v_max_f32_e32 v3, v123, v123
	v_max_f32_e32 v3, 0, v3
	v_sqrt_f32_e32 v3, v3
	v_ashrrev_i32_e32 v114, 7, v0
	v_and_b32_e32 v121, 0x7f, v0
	v_bfe_u32 v113, v0, 6, 1
	v_mul_f32_e32 v3, v115, v3
	v_mul_f32_e32 v119, v119, v3
	ds_write_b128 v2, v[108:111] offset:25600
	ds_write_b128 v2, v[116:119] offset:58368
	v_lshlrev_b32_e32 v2, 4, v114
	v_or_b32_e32 v115, 2, v2
	v_and_b32_e32 v112, 63, v0
	v_cmp_gt_u32_e32 vcc, 64, v121
	v_sub_u32_e32 v116, 63, v115
	v_lshl_or_b32 v3, v113, 12, v112
	v_cndmask_b32_e32 v115, v116, v115, vcc
	v_lshl_add_u32 v115, v115, 6, v3
	v_lshl_add_u32 v115, v115, 2, 0
	s_waitcnt lgkmcnt(0)
	s_barrier
	ds_read2st64_b32 v[116:117], v115 offset0:100 offset1:228
	v_or_b32_e32 v115, 3, v2
	v_sub_u32_e32 v118, 63, v115
	v_cndmask_b32_e32 v115, v118, v115, vcc
	v_lshl_add_u32 v115, v115, 6, v3
	v_lshl_add_u32 v115, v115, 2, 0
	ds_read2st64_b32 v[118:119], v115 offset0:100 offset1:228
	v_or_b32_e32 v115, 4, v2
	v_sub_u32_e32 v122, 63, v115
	v_cndmask_b32_e32 v115, v122, v115, vcc
	v_lshl_add_u32 v115, v115, 6, v3
	v_lshl_add_u32 v115, v115, 2, 0
	ds_read2st64_b32 v[122:123], v115 offset0:100 offset1:228
	v_or_b32_e32 v115, 5, v2
	v_sub_u32_e32 v127, 63, v115
	v_cndmask_b32_e32 v115, v127, v115, vcc
	v_lshl_add_u32 v115, v115, 6, v3
	v_lshl_add_u32 v115, v115, 2, 0
	ds_read2st64_b32 v[128:129], v115 offset0:100 offset1:228
	v_or_b32_e32 v115, 6, v2
	v_sub_u32_e32 v127, 63, v115
	v_cndmask_b32_e32 v115, v127, v115, vcc
	v_lshl_add_u32 v115, v115, 6, v3
	v_lshl_add_u32 v115, v115, 2, 0
	ds_read2st64_b32 v[130:131], v115 offset0:100 offset1:228
	v_or_b32_e32 v115, 7, v2
	v_sub_u32_e32 v127, 63, v115
	v_cndmask_b32_e32 v115, v127, v115, vcc
	v_lshl_add_u32 v115, v115, 6, v3
	v_lshl_add_u32 v115, v115, 2, 0
	ds_read2st64_b32 v[132:133], v115 offset0:100 offset1:228
	v_or_b32_e32 v115, 8, v2
	v_sub_u32_e32 v127, 63, v115
	v_cndmask_b32_e32 v115, v127, v115, vcc
	v_lshl_add_u32 v115, v115, 6, v3
	v_lshl_add_u32 v115, v115, 2, 0
	ds_read2st64_b32 v[134:135], v115 offset0:100 offset1:228
	v_or_b32_e32 v115, 9, v2
	v_sub_u32_e32 v127, 63, v115
	v_cndmask_b32_e32 v115, v127, v115, vcc
	v_lshl_add_u32 v115, v115, 6, v3
	v_lshl_add_u32 v115, v115, 2, 0
	ds_read2st64_b32 v[136:137], v115 offset0:100 offset1:228
	v_or_b32_e32 v115, 10, v2
	v_sub_u32_e32 v127, 63, v115
	v_cndmask_b32_e32 v115, v127, v115, vcc
	v_lshl_add_u32 v115, v115, 6, v3
	v_lshl_add_u32 v115, v115, 2, 0
	ds_read2st64_b32 v[138:139], v115 offset0:100 offset1:228
	v_or_b32_e32 v115, 11, v2
	v_sub_u32_e32 v127, 63, v115
	v_cndmask_b32_e32 v115, v127, v115, vcc
	v_lshl_add_u32 v115, v115, 6, v3
	v_lshl_add_u32 v115, v115, 2, 0
	v_sub_u32_e32 v108, 63, v2
	v_or_b32_e32 v110, 1, v2
	ds_read2st64_b32 v[140:141], v115 offset0:100 offset1:228
	v_or_b32_e32 v115, 12, v2
	v_cndmask_b32_e32 v108, v108, v2, vcc
	v_sub_u32_e32 v111, 63, v110
	v_sub_u32_e32 v127, 63, v115
	v_lshl_add_u32 v108, v108, 6, v3
	v_cndmask_b32_e32 v110, v111, v110, vcc
	v_cndmask_b32_e32 v115, v127, v115, vcc
	v_lshl_add_u32 v108, v108, 2, 0
	v_lshl_add_u32 v110, v110, 6, v3
	v_lshl_add_u32 v115, v115, 6, v3
	ds_read2st64_b32 v[108:109], v108 offset0:100 offset1:228
	v_lshl_add_u32 v110, v110, 2, 0
	v_lshl_add_u32 v115, v115, 2, 0
	ds_read2st64_b32 v[110:111], v110 offset0:100 offset1:228
	ds_read2st64_b32 v[142:143], v115 offset0:100 offset1:228
	v_or_b32_e32 v115, 13, v2
	v_sub_u32_e32 v127, 63, v115
	v_cndmask_b32_e32 v115, v127, v115, vcc
	v_lshl_add_u32 v115, v115, 6, v3
	v_lshl_add_u32 v115, v115, 2, 0
	s_waitcnt lgkmcnt(2)
	v_fma_f32 v109, 0, v108, v109
	ds_read2st64_b32 v[144:145], v115 offset0:100 offset1:228
	v_or_b32_e32 v115, 14, v2
	s_waitcnt lgkmcnt(2)
	v_mul_f32_e32 v108, v108, v110
	v_fmac_f32_e32 v111, v109, v110
	v_sub_u32_e32 v127, 63, v115
	v_mul_f32_e32 v108, v108, v116
	v_fmac_f32_e32 v117, v111, v116
	v_cndmask_b32_e32 v115, v127, v115, vcc
	v_mul_f32_e32 v108, v108, v118
	v_fmac_f32_e32 v119, v117, v118
	v_lshl_add_u32 v115, v115, 6, v3
	v_mul_f32_e32 v108, v108, v122
	v_fmac_f32_e32 v123, v119, v122
	v_lshl_add_u32 v115, v115, 2, 0
	v_or_b32_e32 v2, 15, v2
	v_mul_f32_e32 v108, v108, v128
	v_fmac_f32_e32 v129, v123, v128
	ds_read2st64_b32 v[146:147], v115 offset0:100 offset1:228
	v_sub_u32_e32 v115, 63, v2
	v_mul_f32_e32 v108, v108, v130
	v_fmac_f32_e32 v131, v129, v130
	v_cndmask_b32_e32 v2, v115, v2, vcc
	v_mul_f32_e32 v108, v108, v132
	v_fmac_f32_e32 v133, v131, v132
	v_lshl_add_u32 v2, v2, 6, v3
	v_mul_f32_e32 v108, v108, v134
	v_fmac_f32_e32 v135, v133, v134
	v_lshl_add_u32 v2, v2, 2, 0
	v_mul_f32_e32 v108, v108, v136
	v_fmac_f32_e32 v137, v135, v136
	ds_read2st64_b32 v[2:3], v2 offset0:100 offset1:228
	v_mul_f32_e32 v108, v108, v138
	v_fmac_f32_e32 v139, v137, v138
	v_mul_f32_e32 v108, v108, v140
	v_fmac_f32_e32 v141, v139, v140
	s_waitcnt lgkmcnt(3)
	v_mul_f32_e32 v108, v108, v142
	v_fmac_f32_e32 v143, v141, v142
	s_waitcnt lgkmcnt(2)
	v_mul_f32_e32 v108, v108, v144
	v_fmac_f32_e32 v145, v143, v144
	s_waitcnt lgkmcnt(1)
	v_mul_f32_e32 v108, v108, v146
	v_fmac_f32_e32 v147, v145, v146
	v_lshl_add_u32 v0, v0, 2, 0
	s_waitcnt lgkmcnt(0)
	v_mul_f32_e32 v108, v108, v2
	v_fmac_f32_e32 v3, v147, v2
	v_add_u32_e32 v2, 0x16400, v0
	v_add_u32_e32 v0, 0x16c00, v0
	ds_write_b32 v2, v108
	ds_write_b32 v0, v3
	v_cmp_lt_i32_e32 vcc, 0, v114
	v_mov_b32_e32 v0, 1.0
	v_lshl_add_u32 v2, v121, 2, 0
	s_waitcnt vmcnt(0) lgkmcnt(0)
	s_barrier
	s_and_saveexec_b64 s[8:9], vcc
	s_cbranch_execnz .LBB0_431
	s_or_b64 exec, exec, s[8:9]
	v_cmp_lt_i32_e32 vcc, 1, v114
	s_and_saveexec_b64 s[8:9], vcc
	s_cbranch_execnz .LBB0_432

.LBB0_361:
	s_and_b64 vcc, exec, s[6:7]
	s_cbranch_vccnz .LBB0_363
	v_mov_b32_e32 v82, v204
	s_and_b32 s6, s68, 7
	s_lshl_b32 s26, s6, 8
	v_lshlrev_b32_e32 v0, 5, v82
	v_and_b32_e32 v0, 0xe0, v0
	v_or_b32_e32 v0, s26, v0
	v_lshl_add_u64 v[2:3], s[12:13], 0, v[0:1]
	v_add_co_u32_e32 v2, vcc, s1, v2
	v_ashrrev_i32_e32 v60, 7, v82
	global_load_dwordx4 v[4:7], v0, s[12:13] offset:2064
	global_load_dwordx4 v[8:11], v0, s[12:13] offset:2048
	v_addc_co_u32_e32 v3, vcc, 0, v3, vcc
	global_load_dwordx4 v[12:15], v0, s[38:39]
	global_load_dwordx4 v[16:19], v0, s[48:49]
	global_load_dwordx4 v[20:23], v[2:3], off offset:16
	global_load_dwordx4 v[36:39], v[2:3], off offset:2064
	global_load_dwordx4 v[28:31], v0, s[12:13] offset:16
	global_load_dwordx4 v[44:47], v0, s[14:15] offset:16
	global_load_dwordx4 v[32:35], v0, s[12:13]
	global_load_dwordx4 v[48:51], v0, s[14:15]
	v_lshl_or_b32 v2, v60, 3, s6
	v_lshlrev_b32_e32 v60, 11, v60
	v_lshrrev_b32_e32 v0, 1, v82
	v_ashrrev_i32_e32 v3, 31, v2
	v_and_b32_e32 v76, 0x800, v60
	v_mov_b32_e32 v77, v1
	v_and_b32_e32 v84, 32, v0
	v_lshlrev_b64 v[2:3], 13, v[2:3]
	v_lshl_add_u64 v[60:61], s[36:37], 0, v[76:77]
	v_lshl_add_u64 v[2:3], s[50:51], 0, v[2:3]
	v_and_b32_e32 v0, 48, v82
	v_lshl_add_u64 v[78:79], v[60:61], 0, s[26:27]
	v_and_or_b32 v60, v82, 15, v84
	v_lshl_add_u64 v[2:3], v[2:3], 0, v[0:1]
	v_lshlrev_b32_e32 v80, 7, v60
	v_mov_b32_e32 v81, v1
	v_lshl_add_u64 v[64:65], v[2:3], 0, v[80:81]
	v_mov_b32_e32 v81, s25
	v_mov_b32_e32 v83, s19
	v_cmp_gt_u32_e32 vcc, s45, v82
	v_mov_b32_e32 v82, s18
	v_lshl_or_b32 v0, v84, 2, v0
	v_cndmask_b32_e32 v83, v81, v83, vcc
	v_mov_b32_e32 v81, s24
	v_cndmask_b32_e32 v82, v81, v82, vcc
	v_lshl_add_u64 v[76:77], v[82:83], 0, v[76:77]
	v_lshl_add_u64 v[76:77], v[76:77], 0, s[26:27]
	v_lshl_add_u64 v[88:89], v[76:77], 0, v[0:1]
	v_lshl_add_u64 v[96:97], v[78:79], 0, v[0:1]
	v_or_b32_e32 v0, 0x800, v80
	v_lshl_add_u64 v[2:3], v[2:3], 0, v[0:1]
	global_load_dwordx4 v[60:63], v[64:65], off
	s_nop 0
	global_load_dwordx4 v[64:67], v[64:65], off offset:64
	s_nop 0
	global_load_dwordx4 v[76:79], v[2:3], off
	global_load_dwordx4 v[80:83], v[2:3], off offset:64
	global_load_dwordx4 v[84:87], v[88:89], off
	s_nop 0
	global_load_dwordx4 v[88:91], v[88:89], off offset:64
	s_nop 0
	global_load_dwordx4 v[92:95], v[96:97], off
	s_nop 0
	global_load_dwordx4 v[96:99], v[96:97], off offset:64
	s_waitcnt vmcnt(0)
	v_cmp_gt_u32_e64 s[98:99], s45, v204
	v_mul_f32_e32 v240, 0xc1000000, v92
	v_mul_f32_e32 v241, 0xc1000000, v93
	v_mul_f32_e32 v242, 0xc1000000, v94
	v_mul_f32_e32 v243, 0xc1000000, v95
	v_mul_f32_e32 v244, 0xc1000000, v96
	v_mul_f32_e32 v245, 0xc1000000, v97
	v_mul_f32_e32 v246, 0xc1000000, v98
	v_mul_f32_e32 v247, 0xc1000000, v99
	v_cndmask_b32_e64 v240, 1.0, v240, s[98:99]
	v_cndmask_b32_e64 v241, 1.0, v241, s[98:99]
	v_cndmask_b32_e64 v242, 1.0, v242, s[98:99]
	v_cndmask_b32_e64 v243, 1.0, v243, s[98:99]
	v_cndmask_b32_e64 v244, 1.0, v244, s[98:99]
	v_cndmask_b32_e64 v245, 1.0, v245, s[98:99]
	v_cndmask_b32_e64 v246, 1.0, v246, s[98:99]
	v_cndmask_b32_e64 v247, 1.0, v247, s[98:99]
.LBB0_363:
	v_mov_b32_e32 v0, v204
	v_and_b32_e32 v3, 0xffff0000, v68
	v_lshlrev_b32_e32 v2, 3, v0
	v_and_b32_e32 v116, 56, v2
	v_lshlrev_b32_e32 v2, 16, v68
	s_nop 0
	v_pk_fma_f32 v[2:3], v[32:33], v[2:3], v[48:49]
	v_lshlrev_b32_e32 v108, 16, v72
	v_and_b32_e32 v109, 0xffff0000, v72
	v_pk_fma_f32 v[2:3], v[8:9], v[108:109], v[2:3]
	v_lshlrev_b32_e32 v108, 16, v100
	v_and_b32_e32 v109, 0xffff0000, v100
	v_pk_fma_f32 v[2:3], v[12:13], v[108:109], v[2:3]
	v_lshlrev_b32_e32 v108, 16, v104
	v_and_b32_e32 v109, 0xffff0000, v104
	v_pk_fma_f32 v[108:109], v[16:17], v[108:109], v[2:3]
	v_lshlrev_b32_e32 v2, 16, v70
	v_and_b32_e32 v3, 0xffff0000, v70
	v_pk_fma_f32 v[2:3], v[28:29], v[2:3], v[44:45]
	v_lshlrev_b32_e32 v110, 16, v74
	v_and_b32_e32 v111, 0xffff0000, v74
	v_pk_fma_f32 v[2:3], v[4:5], v[110:111], v[2:3]
	v_lshlrev_b32_e32 v110, 16, v102
	v_and_b32_e32 v111, 0xffff0000, v102
	v_pk_fma_f32 v[2:3], v[20:21], v[110:111], v[2:3]
	v_lshlrev_b32_e32 v110, 16, v106
	v_and_b32_e32 v111, 0xffff0000, v106
	v_pk_fma_f32 v[112:113], v[36:37], v[110:111], v[2:3]
	v_lshlrev_b32_e32 v2, 16, v69
	v_and_b32_e32 v3, 0xffff0000, v69
	v_pk_fma_f32 v[2:3], v[34:35], v[2:3], v[50:51]
	v_lshlrev_b32_e32 v110, 16, v73
	v_and_b32_e32 v111, 0xffff0000, v73
	v_pk_fma_f32 v[2:3], v[10:11], v[110:111], v[2:3]
	v_lshlrev_b32_e32 v110, 16, v101
	v_and_b32_e32 v111, 0xffff0000, v101
	v_pk_fma_f32 v[2:3], v[14:15], v[110:111], v[2:3]
	v_lshlrev_b32_e32 v110, 16, v105
	v_and_b32_e32 v111, 0xffff0000, v105
	v_pk_fma_f32 v[110:111], v[18:19], v[110:111], v[2:3]
	v_lshlrev_b32_e32 v2, 16, v71
	v_and_b32_e32 v3, 0xffff0000, v71
	v_pk_fma_f32 v[2:3], v[30:31], v[2:3], v[46:47]
	v_lshlrev_b32_e32 v114, 16, v75
	v_and_b32_e32 v115, 0xffff0000, v75
	v_pk_fma_f32 v[2:3], v[6:7], v[114:115], v[2:3]
	v_lshlrev_b32_e32 v114, 16, v103
	v_and_b32_e32 v115, 0xffff0000, v103
	v_pk_fma_f32 v[2:3], v[22:23], v[114:115], v[2:3]
	v_lshlrev_b32_e32 v114, 16, v107
	v_and_b32_e32 v115, 0xffff0000, v107
	v_pk_fma_f32 v[114:115], v[38:39], v[114:115], v[2:3]
	v_ashrrev_i32_e32 v3, 3, v0
	v_lshl_add_u32 v117, v3, 8, 0
	v_lshl_add_u32 v118, v116, 2, v117
	ds_write_b128 v118, v[108:111]
	ds_write_b128 v118, v[112:115] offset:16
	v_cvt_pk_bf16_f32 v108, v108, v109
	v_cvt_pk_bf16_f32 v109, v110, v111
	v_cvt_pk_bf16_f32 v110, v112, v113
	v_mul_lo_u32 v3, v3, s67
	v_lshlrev_b32_e32 v112, 1, v116
	v_and_b32_e32 v127, 15, v0
	v_cvt_pk_bf16_f32 v111, v114, v115
	v_add3_u32 v3, v117, v3, v112
	v_and_b32_e32 v2, 48, v0
	ds_write_b128 v3, v[108:111] offset:16384
	v_mul_u32_u24_e32 v3, 0x90, v127
	v_add3_u32 v3, 0, v2, v3
	s_waitcnt lgkmcnt(0)
	s_barrier
	ds_read_b128 v[108:111], v3 offset:16384
	ds_read_b128 v[112:115], v3 offset:16448
	ds_read_b128 v[120:123], v3 offset:18688
	ds_read_b128 v[128:131], v3 offset:18752
	ds_read_b128 v[136:139], v3 offset:20992
	ds_read_b128 v[140:143], v3 offset:21056
	s_waitcnt lgkmcnt(5)
	v_mfma_f32_16x16x32_bf16 v[116:119], v[60:63], v[108:111], 0
	ds_read_b128 v[148:151], v3 offset:23296
	ds_read_b128 v[154:157], v3 offset:23360
	v_mov_b32_e32 v3, s2
	v_cmp_gt_u32_e32 vcc, s45, v0
	s_nop 0
	v_mfma_f32_16x16x32_bf16 v[108:111], v[76:79], v[108:111], 0
	v_lshlrev_b32_e32 v127, 8, v127
	s_waitcnt lgkmcnt(3)
	v_mfma_f32_16x16x32_bf16 v[144:147], v[60:63], v[136:139], 0
	v_mfma_f32_16x16x32_bf16 v[136:139], v[76:79], v[136:139], 0
	v_mfma_f32_16x16x32_bf16 v[162:165], v[64:67], v[112:115], v[116:119]
	s_nop 0
	v_mfma_f32_16x16x32_bf16 v[166:169], v[80:83], v[112:115], v[108:111]
	s_waitcnt lgkmcnt(2)
	v_mfma_f32_16x16x32_bf16 v[112:115], v[80:83], v[140:143], v[136:139]
	s_nop 2
	v_mov_b32_e32 v136, s73
	v_cndmask_b32_e32 v3, v3, v136, vcc
	v_lshlrev_b32_e32 v136, 7, v0
	v_and_b32_e32 v136, 0x4000, v136
	v_add3_u32 v3, v3, v136, v127
	s_nop 0
	v_add_f32_e32 v136, v84, v162
	v_mul_f32_e32 v136, 0xbfb8aa3b, v136
	v_add_f32_e32 v137, v85, v163
	v_exp_f32_e32 v136, v136
	v_mul_f32_e32 v137, 0xbfb8aa3b, v137
	v_exp_f32_e32 v137, v137
	v_lshlrev_b32_e32 v127, 1, v0
	v_and_b32_e32 v127, 0x80, v127
	v_add_f32_e32 v136, 1.0, v136
	v_rcp_f32_e32 v136, v136
	v_add3_u32 v2, v3, v127, v2
	v_add_f32_e32 v3, 1.0, v137
	v_add_f32_e32 v137, v86, v164
	v_mul_f32_e32 v137, 0xbfb8aa3b, v137
	v_rcp_f32_e32 v3, v3
	v_exp_f32_e32 v137, v137
	v_add_f32_e32 v138, v87, v165
	v_mul_f32_e32 v138, 0xbfb8aa3b, v138

	v_exp_f32_e32 v138, v138
	s_nop 0

	v_mul_f32_e32 v136, v240, v136

	v_add_f32_e32 v137, 1.0, v137
	v_mfma_f32_16x16x32_bf16 v[132:135], v[60:63], v[120:123], 0

	v_rcp_f32_e32 v139, v137
	v_mul_f32_e32 v137, v241, v3
	v_add_f32_e32 v3, 1.0, v138
	v_rcp_f32_e32 v3, v3
	s_nop 0
	v_mfma_f32_16x16x32_bf16 v[132:135], v[64:67], v[128:131], v[132:135]


	v_mul_f32_e32 v138, v242, v139


	v_mul_f32_e32 v139, v243, v3
	s_nop 1
	s_nop 3
	v_add_f32_e32 v3, v84, v132
	v_mul_f32_e32 v3, 0xbfb8aa3b, v3
	v_exp_f32_e32 v3, v3
	v_add_f32_e32 v127, v85, v133
	v_mul_f32_e32 v127, 0xbfb8aa3b, v127
	v_exp_f32_e32 v127, v127
	v_add_f32_e32 v3, 1.0, v3
	v_rcp_f32_e32 v3, v3
	v_add_f32_e32 v133, v86, v134
	v_add_f32_e32 v127, 1.0, v127
	v_mul_f32_e32 v133, 0xbfb8aa3b, v133
	v_rcp_f32_e32 v127, v127
	v_exp_f32_e32 v133, v133
	v_add_f32_e32 v134, v87, v135
	v_mul_f32_e32 v134, 0xbfb8aa3b, v134

	v_exp_f32_e32 v134, v134

	v_mul_f32_e32 v132, v240, v3

	v_add_f32_e32 v133, 1.0, v133
	v_mfma_f32_16x16x32_bf16 v[120:123], v[76:79], v[120:123], 0

	v_rcp_f32_e32 v135, v133
	v_mul_f32_e32 v133, v241, v127
	v_add_f32_e32 v3, 1.0, v134
	v_rcp_f32_e32 v3, v3
	s_nop 0
	v_mfma_f32_16x16x32_bf16 v[116:119], v[80:83], v[128:131], v[120:123]


	v_mul_f32_e32 v134, v242, v135
	v_mfma_f32_16x16x32_bf16 v[120:123], v[64:67], v[140:143], v[144:147]


	v_mul_f32_e32 v135, v243, v3
	s_waitcnt lgkmcnt(1)
	v_mfma_f32_16x16x32_bf16 v[158:161], v[60:63], v[148:151], 0
	s_nop 3
	v_add_f32_e32 v118, v90, v118
	s_nop 1
	s_nop 1
	v_add_f32_e32 v3, v84, v120
	v_mul_f32_e32 v3, 0xbfb8aa3b, v3
	v_exp_f32_e32 v3, v3
	v_add_f32_e32 v120, v85, v121
	v_mul_f32_e32 v120, 0xbfb8aa3b, v120
	v_exp_f32_e32 v120, v120
	v_add_f32_e32 v3, 1.0, v3
	v_rcp_f32_e32 v3, v3
	v_add_f32_e32 v122, v86, v122
	v_add_f32_e32 v120, 1.0, v120
	v_mul_f32_e32 v122, 0xbfb8aa3b, v122
	v_rcp_f32_e32 v121, v120
	v_exp_f32_e32 v122, v122
	v_add_f32_e32 v123, v87, v123
	v_mul_f32_e32 v123, 0xbfb8aa3b, v123

	v_exp_f32_e32 v123, v123

	v_mul_f32_e32 v120, v240, v3

	v_add_f32_e32 v122, 1.0, v122

	v_rcp_f32_e32 v122, v122
	v_mul_f32_e32 v121, v241, v121
	v_add_f32_e32 v3, 1.0, v123
	v_rcp_f32_e32 v3, v3
	s_waitcnt lgkmcnt(0)
	v_mfma_f32_16x16x32_bf16 v[128:131], v[64:67], v[154:157], v[158:161]


	v_mul_f32_e32 v122, v242, v122


	v_mul_f32_e32 v123, v243, v3
	s_nop 1
	s_nop 3
	v_add_f32_e32 v3, v84, v128
	v_mul_f32_e32 v3, 0xbfb8aa3b, v3
	v_exp_f32_e32 v3, v3
	v_add_f32_e32 v127, v85, v129
	v_mul_f32_e32 v127, 0xbfb8aa3b, v127
	v_exp_f32_e32 v127, v127
	v_add_f32_e32 v3, 1.0, v3
	v_rcp_f32_e32 v3, v3
	ds_write_b128 v2, v[120:123] offset:8192
	v_add_f32_e32 v122, v86, v130
	v_add_f32_e32 v120, 1.0, v127
	v_mul_f32_e32 v122, 0xbfb8aa3b, v122
	v_rcp_f32_e32 v121, v120
	v_exp_f32_e32 v122, v122
	v_add_f32_e32 v123, v87, v131
	v_mul_f32_e32 v123, 0xbfb8aa3b, v123

	v_exp_f32_e32 v123, v123

	v_mul_f32_e32 v120, v240, v3

	v_add_f32_e32 v122, 1.0, v122

	v_rcp_f32_e32 v122, v122
	v_mul_f32_e32 v121, v241, v121
	v_add_f32_e32 v3, 1.0, v123
	v_rcp_f32_e32 v3, v3


	v_mul_f32_e32 v122, v242, v122


	v_mul_f32_e32 v123, v243, v3
	v_add_f32_e32 v3, v88, v166
	v_mul_f32_e32 v3, 0xbfb8aa3b, v3
	v_exp_f32_e32 v3, v3
	v_add_f32_e32 v127, v89, v167
	v_mul_f32_e32 v127, 0xbfb8aa3b, v127
	v_exp_f32_e32 v127, v127
	v_add_f32_e32 v3, 1.0, v3
	v_rcp_f32_e32 v3, v3
	ds_write_b128 v2, v[120:123] offset:12288
	v_add_f32_e32 v122, v90, v168
	v_add_f32_e32 v120, 1.0, v127
	v_mul_f32_e32 v122, 0xbfb8aa3b, v122
	v_rcp_f32_e32 v121, v120
	v_exp_f32_e32 v122, v122
	v_add_f32_e32 v123, v91, v169
	v_mul_f32_e32 v123, 0xbfb8aa3b, v123

	v_exp_f32_e32 v123, v123
	s_nop 0

	v_mul_f32_e32 v120, v244, v3

	v_add_f32_e32 v122, 1.0, v122

	v_rcp_f32_e32 v122, v122
	v_mul_f32_e32 v121, v245, v121
	v_add_f32_e32 v3, 1.0, v123
	v_rcp_f32_e32 v3, v3


	v_mul_f32_e32 v122, v246, v122


	v_mul_f32_e32 v123, v247, v3
	v_add_f32_e32 v3, v88, v116
	v_mul_f32_e32 v3, 0xbfb8aa3b, v3
	v_exp_f32_e32 v3, v3
	v_add_f32_e32 v116, v89, v117
	v_mul_f32_e32 v116, 0xbfb8aa3b, v116
	v_exp_f32_e32 v116, v116
	v_add_f32_e32 v3, 1.0, v3
	v_rcp_f32_e32 v3, v3
	v_mul_f32_e32 v118, 0xbfb8aa3b, v118
	v_add_f32_e32 v116, 1.0, v116
	v_rcp_f32_e32 v117, v116
	v_exp_f32_e32 v118, v118
	v_add_f32_e32 v119, v91, v119
	v_mul_f32_e32 v119, 0xbfb8aa3b, v119

	v_exp_f32_e32 v119, v119

	v_mul_f32_e32 v116, v244, v3

	v_add_f32_e32 v118, 1.0, v118

	v_rcp_f32_e32 v118, v118
	v_mul_f32_e32 v117, v245, v117
	v_add_f32_e32 v3, 1.0, v119
	v_rcp_f32_e32 v3, v3


	v_mul_f32_e32 v118, v246, v118


	v_mul_f32_e32 v119, v247, v3
	v_add_f32_e32 v3, v88, v112
	v_mul_f32_e32 v3, 0xbfb8aa3b, v3
	v_exp_f32_e32 v3, v3
	v_add_f32_e32 v112, v89, v113
	v_mul_f32_e32 v112, 0xbfb8aa3b, v112
	v_exp_f32_e32 v112, v112
	v_add_f32_e32 v3, 1.0, v3
	v_rcp_f32_e32 v3, v3
	v_add_f32_e32 v114, v90, v114
	v_add_f32_e32 v112, 1.0, v112
	v_mul_f32_e32 v114, 0xbfb8aa3b, v114
	v_rcp_f32_e32 v113, v112
	v_exp_f32_e32 v114, v114
	v_add_f32_e32 v115, v91, v115
	v_mul_f32_e32 v115, 0xbfb8aa3b, v115

	v_exp_f32_e32 v115, v115

	v_mul_f32_e32 v112, v244, v3

	v_add_f32_e32 v114, 1.0, v114
	v_mfma_f32_16x16x32_bf16 v[148:151], v[76:79], v[148:151], 0

	v_rcp_f32_e32 v114, v114
	v_mul_f32_e32 v113, v245, v113
	v_add_f32_e32 v3, 1.0, v115
	v_rcp_f32_e32 v3, v3
	s_nop 0
	v_mfma_f32_16x16x32_bf16 v[108:111], v[80:83], v[154:157], v[148:151]


	v_mul_f32_e32 v114, v246, v114


	v_mul_f32_e32 v115, v247, v3
	s_nop 1
	s_nop 3
	v_add_f32_e32 v3, v88, v108
	v_mul_f32_e32 v3, 0xbfb8aa3b, v3
	v_exp_f32_e32 v3, v3
	v_add_f32_e32 v108, v89, v109
	v_mul_f32_e32 v108, 0xbfb8aa3b, v108
	v_exp_f32_e32 v108, v108
	v_add_f32_e32 v3, 1.0, v3
	v_rcp_f32_e32 v3, v3
	v_add_f32_e32 v110, v90, v110
	v_add_f32_e32 v108, 1.0, v108
	v_mul_f32_e32 v110, 0xbfb8aa3b, v110
	v_rcp_f32_e32 v109, v108
	v_exp_f32_e32 v110, v110
	v_add_f32_e32 v111, v91, v111
	v_mul_f32_e32 v111, 0xbfb8aa3b, v111

	v_exp_f32_e32 v111, v111

	v_mul_f32_e32 v108, v244, v3

	v_add_f32_e32 v110, 1.0, v110

	v_rcp_f32_e32 v110, v110
	v_mul_f32_e32 v109, v245, v109
	v_add_f32_e32 v3, 1.0, v111
	v_rcp_f32_e32 v3, v3


	v_mul_f32_e32 v110, v246, v110


	v_mul_f32_e32 v111, v247, v3
	ds_write_b128 v2, v[108:111] offset:12352
	v_lshlrev_b32_e32 v3, 2, v0
	v_lshlrev_b32_e32 v108, 4, v0
	ds_write_b128 v2, v[136:139]
	ds_write_b128 v2, v[132:135] offset:4096
	ds_write_b128 v2, v[120:123] offset:64
	ds_write_b128 v2, v[116:119] offset:4160
	ds_write_b128 v2, v[112:115] offset:8256
	v_and_b32_e32 v2, 60, v3
	v_and_b32_e32 v109, 0xffffc000, v108
	v_lshlrev_b32_e32 v2, 2, v2
	v_add_u32_e32 v109, 0, v109
	v_and_b32_e32 v108, 0x3f00, v108
	v_add3_u32 v128, v109, v108, v2
	s_waitcnt lgkmcnt(0)
	s_barrier
	ds_read_b128 v[120:123], v128 offset:25600
	ds_read_b128 v[112:115], v128 offset:58368
	v_add_u32_e32 v127, 0, v2
	v_add_u32_e32 v129, v127, v108
	ds_read_b128 v[116:119], v129
	s_waitcnt lgkmcnt(2)
	v_mul_f32_e32 v108, 0x3fb8aa3b, v120
	v_exp_f32_e32 v108, v108
	v_add_f32_e32 v109, v120, v120
	v_cmp_nlt_f32_e32 vcc, s75, v109
	s_and_saveexec_b64 s[6:7], vcc
	s_xor_b64 s[6:7], exec, s[6:7]
	v_fma_f32 v120, -v108, v108, 1.0
	s_andn2_saveexec_b64 s[6:7], s[6:7]
	v_fmamk_f32 v110, v109, 0x3c088889, v125
	v_fmaak_f32 v110, v109, v110, 0x3e2aaaab
	v_fma_f32 v110, v109, v110, 0.5
	v_fma_f32 v110, v109, v110, 1.0
	v_mul_f32_e64 v120, v110, -v109
	s_or_b64 exec, exec, s[6:7]
	v_mul_f32_e32 v109, 0x3fb8aa3b, v121
	v_exp_f32_e32 v109, v109
	v_add_f32_e32 v110, v121, v121
	v_cmp_nlt_f32_e32 vcc, s75, v110
	s_and_saveexec_b64 s[6:7], vcc
	s_xor_b64 s[6:7], exec, s[6:7]
	v_fma_f32 v121, -v109, v109, 1.0
	s_andn2_saveexec_b64 s[6:7], s[6:7]
	v_fmamk_f32 v111, v110, 0x3c088889, v125
	v_fmaak_f32 v111, v110, v111, 0x3e2aaaab
	v_fma_f32 v111, v110, v111, 0.5
	v_fma_f32 v111, v110, v111, 1.0
	v_mul_f32_e64 v121, v111, -v110
	s_or_b64 exec, exec, s[6:7]
	v_mul_f32_e32 v110, 0x3fb8aa3b, v122
	v_exp_f32_e32 v110, v110
	v_add_f32_e32 v111, v122, v122
	v_cmp_nlt_f32_e32 vcc, s75, v111
	s_and_saveexec_b64 s[6:7], vcc
	s_xor_b64 s[6:7], exec, s[6:7]
	v_fma_f32 v122, -v110, v110, 1.0
	s_andn2_saveexec_b64 s[6:7], s[6:7]
	v_fmamk_f32 v122, v111, 0x3c088889, v125
	v_fmaak_f32 v122, v111, v122, 0x3e2aaaab
	v_fma_f32 v122, v111, v122, 0.5
	v_fma_f32 v122, v111, v122, 1.0
	v_mul_f32_e64 v122, v122, -v111
	s_or_b64 exec, exec, s[6:7]
	v_mul_f32_e32 v111, 0x3fb8aa3b, v123
	v_exp_f32_e32 v111, v111
	v_add_f32_e32 v130, v123, v123
	v_cmp_nlt_f32_e32 vcc, s75, v130
	s_and_saveexec_b64 s[6:7], vcc
	s_xor_b64 s[6:7], exec, s[6:7]
	v_fma_f32 v123, -v111, v111, 1.0
	s_andn2_saveexec_b64 s[6:7], s[6:7]
	v_fmamk_f32 v123, v130, 0x3c088889, v125
	v_fmaak_f32 v123, v130, v123, 0x3e2aaaab
	v_fma_f32 v123, v130, v123, 0.5
	v_fma_f32 v123, v130, v123, 1.0
	v_mul_f32_e64 v123, v123, -v130
	s_or_b64 exec, exec, s[6:7]
	v_max_f32_e32 v120, v120, v120
	v_max_f32_e32 v120, 0, v120
	v_sqrt_f32_e32 v120, v120
	v_max_f32_e32 v121, v121, v121
	v_max_f32_e32 v121, 0, v121
	v_sqrt_f32_e32 v121, v121
	s_waitcnt lgkmcnt(1)
	v_mul_f32_e32 v112, v112, v120
	s_waitcnt lgkmcnt(0)
	v_mul_f32_e32 v112, v116, v112
	v_max_f32_e32 v116, v122, v122
	v_max_f32_e32 v120, v123, v123
	v_max_f32_e32 v116, 0, v116
	v_max_f32_e32 v120, 0, v120
	v_sqrt_f32_e32 v116, v116
	v_sqrt_f32_e32 v120, v120
	v_mul_f32_e32 v113, v113, v121
	v_mul_f32_e32 v113, v117, v113
	v_mul_f32_e32 v114, v114, v116
	v_mul_f32_e32 v115, v115, v120
	v_mul_f32_e32 v114, v118, v114
	v_mul_f32_e32 v115, v119, v115
	ds_write_b128 v128, v[108:111] offset:25600
	ds_write_b128 v128, v[112:115] offset:58368
	v_add_u32_e32 v108, 0x800, v3
	v_and_b32_e32 v109, 0x3ffff000, v108
	v_and_b32_e32 v108, 0xfc0, v108
	v_lshl_add_u32 v109, v109, 2, 0
	v_lshlrev_b32_e32 v108, 2, v108
	v_add3_u32 v130, v109, v108, v2
	ds_read_b128 v[120:123], v130 offset:25600
	ds_read_b128 v[112:115], v130 offset:58368
	v_add_u32_e32 v108, v127, v108
	ds_read_b128 v[116:119], v108
	s_waitcnt lgkmcnt(2)
	v_mul_f32_e32 v108, 0x3fb8aa3b, v120
	v_exp_f32_e32 v108, v108
	v_add_f32_e32 v109, v120, v120
	v_cmp_nlt_f32_e32 vcc, s75, v109
	s_and_saveexec_b64 s[6:7], vcc
	s_xor_b64 s[6:7], exec, s[6:7]
	v_fma_f32 v120, -v108, v108, 1.0
	s_andn2_saveexec_b64 s[6:7], s[6:7]
	v_fmamk_f32 v110, v109, 0x3c088889, v125
	v_fmaak_f32 v110, v109, v110, 0x3e2aaaab
	v_fma_f32 v110, v109, v110, 0.5
	v_fma_f32 v110, v109, v110, 1.0
	v_mul_f32_e64 v120, v110, -v109
	s_or_b64 exec, exec, s[6:7]
	v_mul_f32_e32 v109, 0x3fb8aa3b, v121
	v_exp_f32_e32 v109, v109
	v_add_f32_e32 v110, v121, v121
	v_cmp_nlt_f32_e32 vcc, s75, v110
	s_and_saveexec_b64 s[6:7], vcc
	s_xor_b64 s[6:7], exec, s[6:7]
	v_fma_f32 v121, -v109, v109, 1.0
	s_andn2_saveexec_b64 s[6:7], s[6:7]
	v_fmamk_f32 v111, v110, 0x3c088889, v125
	v_fmaak_f32 v111, v110, v111, 0x3e2aaaab
	v_fma_f32 v111, v110, v111, 0.5
	v_fma_f32 v111, v110, v111, 1.0
	v_mul_f32_e64 v121, v111, -v110
	s_or_b64 exec, exec, s[6:7]
	v_mul_f32_e32 v110, 0x3fb8aa3b, v122
	v_exp_f32_e32 v110, v110
	v_add_f32_e32 v111, v122, v122
	v_cmp_nlt_f32_e32 vcc, s75, v111
	s_and_saveexec_b64 s[6:7], vcc
	s_xor_b64 s[6:7], exec, s[6:7]
	v_fma_f32 v122, -v110, v110, 1.0
	s_andn2_saveexec_b64 s[6:7], s[6:7]
	v_fmamk_f32 v122, v111, 0x3c088889, v125
	v_fmaak_f32 v122, v111, v122, 0x3e2aaaab
	v_fma_f32 v122, v111, v122, 0.5
	v_fma_f32 v122, v111, v122, 1.0
	v_mul_f32_e64 v122, v122, -v111
	s_or_b64 exec, exec, s[6:7]
	v_mul_f32_e32 v111, 0x3fb8aa3b, v123
	v_exp_f32_e32 v111, v111
	v_add_f32_e32 v131, v123, v123
	v_cmp_nlt_f32_e32 vcc, s75, v131
	s_and_saveexec_b64 s[6:7], vcc
	s_xor_b64 s[6:7], exec, s[6:7]
	v_fma_f32 v123, -v111, v111, 1.0
	s_andn2_saveexec_b64 s[6:7], s[6:7]
	v_fmamk_f32 v123, v131, 0x3c088889, v125
	v_fmaak_f32 v123, v131, v123, 0x3e2aaaab
	v_fma_f32 v123, v131, v123, 0.5
	v_fma_f32 v123, v131, v123, 1.0
	v_mul_f32_e64 v123, v123, -v131
	s_or_b64 exec, exec, s[6:7]
	v_max_f32_e32 v120, v120, v120
	v_max_f32_e32 v120, 0, v120
	v_sqrt_f32_e32 v120, v120
	v_max_f32_e32 v121, v121, v121
	v_max_f32_e32 v121, 0, v121
	v_sqrt_f32_e32 v121, v121
	s_waitcnt lgkmcnt(1)
	v_mul_f32_e32 v112, v112, v120
	s_waitcnt lgkmcnt(0)
	v_mul_f32_e32 v112, v116, v112
	v_max_f32_e32 v116, v122, v122
	v_max_f32_e32 v120, v123, v123
	v_max_f32_e32 v116, 0, v116
	v_max_f32_e32 v120, 0, v120
	v_sqrt_f32_e32 v116, v116
	v_sqrt_f32_e32 v120, v120
	v_mul_f32_e32 v113, v113, v121
	v_mul_f32_e32 v113, v117, v113
	v_mul_f32_e32 v114, v114, v116
	v_mul_f32_e32 v115, v115, v120
	v_mul_f32_e32 v114, v118, v114
	v_mul_f32_e32 v115, v119, v115
	ds_write_b128 v130, v[108:111] offset:25600
	ds_write_b128 v130, v[112:115] offset:58368
	ds_read_b128 v[120:123], v128 offset:41984
	v_add_u32_e32 v130, 0xe400, v128
	ds_read_b128 v[112:115], v130 offset:16384
	ds_read_b128 v[116:119], v129
	s_waitcnt lgkmcnt(2)
	v_mul_f32_e32 v108, 0x3fb8aa3b, v120
	v_exp_f32_e32 v108, v108
	v_add_f32_e32 v109, v120, v120
	v_cmp_nlt_f32_e32 vcc, s75, v109
	s_and_saveexec_b64 s[6:7], vcc
	s_xor_b64 s[6:7], exec, s[6:7]
	v_fma_f32 v120, -v108, v108, 1.0
	s_andn2_saveexec_b64 s[6:7], s[6:7]
	v_fmamk_f32 v110, v109, 0x3c088889, v125
	v_fmaak_f32 v110, v109, v110, 0x3e2aaaab
	v_fma_f32 v110, v109, v110, 0.5
	v_fma_f32 v110, v109, v110, 1.0
	v_mul_f32_e64 v120, v110, -v109
	s_or_b64 exec, exec, s[6:7]
	v_mul_f32_e32 v109, 0x3fb8aa3b, v121
	v_exp_f32_e32 v109, v109
	v_add_f32_e32 v110, v121, v121
	v_cmp_nlt_f32_e32 vcc, s75, v110
	s_and_saveexec_b64 s[6:7], vcc
	s_xor_b64 s[6:7], exec, s[6:7]
	v_fma_f32 v121, -v109, v109, 1.0
	s_andn2_saveexec_b64 s[6:7], s[6:7]
	v_fmamk_f32 v111, v110, 0x3c088889, v125
	v_fmaak_f32 v111, v110, v111, 0x3e2aaaab
	v_fma_f32 v111, v110, v111, 0.5
	v_fma_f32 v111, v110, v111, 1.0
	v_mul_f32_e64 v121, v111, -v110
	s_or_b64 exec, exec, s[6:7]
	v_mul_f32_e32 v110, 0x3fb8aa3b, v122
	v_exp_f32_e32 v110, v110
	v_add_f32_e32 v111, v122, v122
	v_cmp_nlt_f32_e32 vcc, s75, v111
	s_and_saveexec_b64 s[6:7], vcc
	s_xor_b64 s[6:7], exec, s[6:7]
	v_fma_f32 v122, -v110, v110, 1.0
	s_andn2_saveexec_b64 s[6:7], s[6:7]
	v_fmamk_f32 v122, v111, 0x3c088889, v125
	v_fmaak_f32 v122, v111, v122, 0x3e2aaaab
	v_fma_f32 v122, v111, v122, 0.5
	v_fma_f32 v122, v111, v122, 1.0
	v_mul_f32_e64 v122, v122, -v111
	s_or_b64 exec, exec, s[6:7]
	v_mul_f32_e32 v111, 0x3fb8aa3b, v123
	v_exp_f32_e32 v111, v111
	v_add_f32_e32 v129, v123, v123
	v_cmp_nlt_f32_e32 vcc, s75, v129
	s_and_saveexec_b64 s[6:7], vcc
	s_xor_b64 s[6:7], exec, s[6:7]
	v_fma_f32 v123, -v111, v111, 1.0
	s_andn2_saveexec_b64 s[6:7], s[6:7]
	v_fmamk_f32 v123, v129, 0x3c088889, v125
	v_fmaak_f32 v123, v129, v123, 0x3e2aaaab
	v_fma_f32 v123, v129, v123, 0.5
	v_fma_f32 v123, v129, v123, 1.0
	v_mul_f32_e64 v123, v123, -v129
	s_or_b64 exec, exec, s[6:7]
	v_max_f32_e32 v120, v120, v120
	v_max_f32_e32 v120, 0, v120
	v_sqrt_f32_e32 v120, v120
	v_max_f32_e32 v121, v121, v121
	v_max_f32_e32 v121, 0, v121
	v_sqrt_f32_e32 v121, v121
	s_waitcnt lgkmcnt(1)
	v_mul_f32_e32 v112, v112, v120
	s_waitcnt lgkmcnt(0)
	v_mul_f32_e32 v112, v116, v112
	v_max_f32_e32 v116, v122, v122
	v_max_f32_e32 v120, v123, v123
	v_max_f32_e32 v116, 0, v116
	v_max_f32_e32 v120, 0, v120
	v_sqrt_f32_e32 v116, v116
	v_sqrt_f32_e32 v120, v120
	v_mul_f32_e32 v113, v113, v121
	v_add_u32_e32 v3, 0x1800, v3
	v_mul_f32_e32 v114, v114, v116
	v_mul_f32_e32 v115, v115, v120
	v_mul_f32_e32 v113, v117, v113
	v_mul_f32_e32 v114, v118, v114
	v_mul_f32_e32 v115, v119, v115
	ds_write_b128 v128, v[108:111] offset:41984
	ds_write_b128 v130, v[112:115] offset:16384
	v_and_b32_e32 v108, 0x3ffff000, v3
	v_and_b32_e32 v3, 0xfc0, v3
	v_lshl_add_u32 v108, v108, 2, 0
	v_lshlrev_b32_e32 v3, 2, v3
	v_add3_u32 v2, v108, v3, v2
	ds_read_b128 v[120:123], v2 offset:25600
	ds_read_b128 v[112:115], v2 offset:58368
	v_add_u32_e32 v3, v127, v3
	ds_read_b128 v[116:119], v3
	s_waitcnt lgkmcnt(2)
	v_mul_f32_e32 v3, 0x3fb8aa3b, v120
	v_exp_f32_e32 v108, v3
	v_add_f32_e32 v109, v120, v120
	v_cmp_nlt_f32_e32 vcc, s75, v109
	s_and_saveexec_b64 s[6:7], vcc
	s_xor_b64 s[6:7], exec, s[6:7]
	v_fma_f32 v3, -v108, v108, 1.0
	s_andn2_saveexec_b64 s[6:7], s[6:7]
	v_fmamk_f32 v3, v109, 0x3c088889, v125
	v_fmaak_f32 v3, v109, v3, 0x3e2aaaab
	v_fma_f32 v3, v109, v3, 0.5
	v_fma_f32 v3, v109, v3, 1.0
	v_mul_f32_e64 v3, v3, -v109
	s_or_b64 exec, exec, s[6:7]
	v_mul_f32_e32 v109, 0x3fb8aa3b, v121
	v_exp_f32_e32 v109, v109
	v_add_f32_e32 v110, v121, v121
	v_cmp_nlt_f32_e32 vcc, s75, v110
	s_and_saveexec_b64 s[6:7], vcc
	s_xor_b64 s[6:7], exec, s[6:7]
	v_fma_f32 v121, -v109, v109, 1.0
	s_andn2_saveexec_b64 s[6:7], s[6:7]
	v_fmamk_f32 v111, v110, 0x3c088889, v125
	v_fmaak_f32 v111, v110, v111, 0x3e2aaaab
	v_fma_f32 v111, v110, v111, 0.5
	v_fma_f32 v111, v110, v111, 1.0
	v_mul_f32_e64 v121, v111, -v110
	s_or_b64 exec, exec, s[6:7]
	v_mul_f32_e32 v110, 0x3fb8aa3b, v122
	v_exp_f32_e32 v110, v110
	v_add_f32_e32 v111, v122, v122
	v_cmp_nlt_f32_e32 vcc, s75, v111
	s_and_saveexec_b64 s[6:7], vcc
	s_xor_b64 s[6:7], exec, s[6:7]
	v_fma_f32 v122, -v110, v110, 1.0
	s_andn2_saveexec_b64 s[6:7], s[6:7]
	v_fmamk_f32 v120, v111, 0x3c088889, v125
	v_fmaak_f32 v120, v111, v120, 0x3e2aaaab
	v_fma_f32 v120, v111, v120, 0.5
	v_fma_f32 v120, v111, v120, 1.0
	v_mul_f32_e64 v122, v120, -v111
	s_or_b64 exec, exec, s[6:7]
	v_mul_f32_e32 v111, 0x3fb8aa3b, v123
	v_exp_f32_e32 v111, v111
	v_add_f32_e32 v120, v123, v123
	v_cmp_nlt_f32_e32 vcc, s75, v120
	s_and_saveexec_b64 s[6:7], vcc
	s_xor_b64 s[6:7], exec, s[6:7]
	v_fma_f32 v123, -v111, v111, 1.0
	s_andn2_saveexec_b64 s[6:7], s[6:7]
	v_fmamk_f32 v123, v120, 0x3c088889, v125
	v_fmaak_f32 v123, v120, v123, 0x3e2aaaab
	v_fma_f32 v123, v120, v123, 0.5
	v_fma_f32 v123, v120, v123, 1.0
	v_mul_f32_e64 v123, v123, -v120
	s_or_b64 exec, exec, s[6:7]
	v_max_f32_e32 v3, v3, v3
	v_max_f32_e32 v3, 0, v3
	v_sqrt_f32_e32 v3, v3
	v_max_f32_e32 v121, v121, v121
	v_max_f32_e32 v121, 0, v121
	v_mov_b32_e32 v120, 0
	s_waitcnt lgkmcnt(1)
	v_mul_f32_e32 v3, v112, v3
	v_sqrt_f32_e32 v112, v121
	v_max_f32_e32 v121, v122, v122
	v_max_f32_e32 v121, 0, v121
	v_sqrt_f32_e32 v121, v121
	s_waitcnt lgkmcnt(0)
	v_mul_f32_e32 v116, v116, v3
	v_mul_f32_e32 v3, v113, v112
	v_mul_f32_e32 v117, v117, v3
	v_mul_f32_e32 v3, v114, v121
	v_mul_f32_e32 v118, v118, v3
	v_max_f32_e32 v3, v123, v123
	v_max_f32_e32 v3, 0, v3
	v_sqrt_f32_e32 v3, v3
	v_ashrrev_i32_e32 v114, 7, v0
	v_and_b32_e32 v121, 0x7f, v0
	v_bfe_u32 v113, v0, 6, 1
	v_mul_f32_e32 v3, v115, v3
	v_mul_f32_e32 v119, v119, v3
	ds_write_b128 v2, v[108:111] offset:25600
	ds_write_b128 v2, v[116:119] offset:58368
	v_lshlrev_b32_e32 v2, 4, v114
	v_or_b32_e32 v115, 2, v2
	v_and_b32_e32 v112, 63, v0
	v_cmp_gt_u32_e32 vcc, 64, v121
	v_sub_u32_e32 v116, 63, v115
	v_lshl_or_b32 v3, v113, 12, v112
	v_cndmask_b32_e32 v115, v116, v115, vcc
	v_lshl_add_u32 v115, v115, 6, v3
	v_lshl_add_u32 v115, v115, 2, 0
	s_waitcnt lgkmcnt(0)
	s_barrier
	ds_read2st64_b32 v[116:117], v115 offset0:100 offset1:228
	v_or_b32_e32 v115, 3, v2
	v_sub_u32_e32 v118, 63, v115
	v_cndmask_b32_e32 v115, v118, v115, vcc
	v_lshl_add_u32 v115, v115, 6, v3
	v_lshl_add_u32 v115, v115, 2, 0
	ds_read2st64_b32 v[118:119], v115 offset0:100 offset1:228
	v_or_b32_e32 v115, 4, v2
	v_sub_u32_e32 v122, 63, v115
	v_cndmask_b32_e32 v115, v122, v115, vcc
	v_lshl_add_u32 v115, v115, 6, v3
	v_lshl_add_u32 v115, v115, 2, 0
	ds_read2st64_b32 v[122:123], v115 offset0:100 offset1:228
	v_or_b32_e32 v115, 5, v2
	v_sub_u32_e32 v127, 63, v115
	v_cndmask_b32_e32 v115, v127, v115, vcc
	v_lshl_add_u32 v115, v115, 6, v3
	v_lshl_add_u32 v115, v115, 2, 0
	ds_read2st64_b32 v[128:129], v115 offset0:100 offset1:228
	v_or_b32_e32 v115, 6, v2
	v_sub_u32_e32 v127, 63, v115
	v_cndmask_b32_e32 v115, v127, v115, vcc
	v_lshl_add_u32 v115, v115, 6, v3
	v_lshl_add_u32 v115, v115, 2, 0
	ds_read2st64_b32 v[130:131], v115 offset0:100 offset1:228
	v_or_b32_e32 v115, 7, v2
	v_sub_u32_e32 v127, 63, v115
	v_cndmask_b32_e32 v115, v127, v115, vcc
	v_lshl_add_u32 v115, v115, 6, v3
	v_lshl_add_u32 v115, v115, 2, 0
	ds_read2st64_b32 v[132:133], v115 offset0:100 offset1:228
	v_or_b32_e32 v115, 8, v2
	v_sub_u32_e32 v127, 63, v115
	v_cndmask_b32_e32 v115, v127, v115, vcc
	v_lshl_add_u32 v115, v115, 6, v3
	v_lshl_add_u32 v115, v115, 2, 0
	ds_read2st64_b32 v[134:135], v115 offset0:100 offset1:228
	v_or_b32_e32 v115, 9, v2
	v_sub_u32_e32 v127, 63, v115
	v_cndmask_b32_e32 v115, v127, v115, vcc
	v_lshl_add_u32 v115, v115, 6, v3
	v_lshl_add_u32 v115, v115, 2, 0
	ds_read2st64_b32 v[136:137], v115 offset0:100 offset1:228
	v_or_b32_e32 v115, 10, v2
	v_sub_u32_e32 v127, 63, v115
	v_cndmask_b32_e32 v115, v127, v115, vcc
	v_lshl_add_u32 v115, v115, 6, v3
	v_lshl_add_u32 v115, v115, 2, 0
	ds_read2st64_b32 v[138:139], v115 offset0:100 offset1:228
	v_or_b32_e32 v115, 11, v2
	v_sub_u32_e32 v127, 63, v115
	v_cndmask_b32_e32 v115, v127, v115, vcc
	v_lshl_add_u32 v115, v115, 6, v3
	v_lshl_add_u32 v115, v115, 2, 0
	v_sub_u32_e32 v108, 63, v2
	v_or_b32_e32 v110, 1, v2
	ds_read2st64_b32 v[140:141], v115 offset0:100 offset1:228
	v_or_b32_e32 v115, 12, v2
	v_cndmask_b32_e32 v108, v108, v2, vcc
	v_sub_u32_e32 v111, 63, v110
	v_sub_u32_e32 v127, 63, v115
	v_lshl_add_u32 v108, v108, 6, v3
	v_cndmask_b32_e32 v110, v111, v110, vcc
	v_cndmask_b32_e32 v115, v127, v115, vcc
	v_lshl_add_u32 v108, v108, 2, 0
	v_lshl_add_u32 v110, v110, 6, v3
	v_lshl_add_u32 v115, v115, 6, v3
	ds_read2st64_b32 v[108:109], v108 offset0:100 offset1:228
	v_lshl_add_u32 v110, v110, 2, 0
	v_lshl_add_u32 v115, v115, 2, 0
	ds_read2st64_b32 v[110:111], v110 offset0:100 offset1:228
	ds_read2st64_b32 v[142:143], v115 offset0:100 offset1:228
	v_or_b32_e32 v115, 13, v2
	v_sub_u32_e32 v127, 63, v115
	v_cndmask_b32_e32 v115, v127, v115, vcc
	v_lshl_add_u32 v115, v115, 6, v3
	v_lshl_add_u32 v115, v115, 2, 0
	s_waitcnt lgkmcnt(2)
	v_fma_f32 v109, 0, v108, v109
	ds_read2st64_b32 v[144:145], v115 offset0:100 offset1:228
	v_or_b32_e32 v115, 14, v2
	s_waitcnt lgkmcnt(2)
	v_mul_f32_e32 v108, v108, v110
	v_fmac_f32_e32 v111, v109, v110
	v_sub_u32_e32 v127, 63, v115
	v_mul_f32_e32 v108, v108, v116
	v_fmac_f32_e32 v117, v111, v116
	v_cndmask_b32_e32 v115, v127, v115, vcc
	v_mul_f32_e32 v108, v108, v118
	v_fmac_f32_e32 v119, v117, v118
	v_lshl_add_u32 v115, v115, 6, v3
	v_mul_f32_e32 v108, v108, v122
	v_fmac_f32_e32 v123, v119, v122
	v_lshl_add_u32 v115, v115, 2, 0
	v_or_b32_e32 v2, 15, v2
	v_mul_f32_e32 v108, v108, v128
	v_fmac_f32_e32 v129, v123, v128
	ds_read2st64_b32 v[146:147], v115 offset0:100 offset1:228
	v_sub_u32_e32 v115, 63, v2
	v_mul_f32_e32 v108, v108, v130
	v_fmac_f32_e32 v131, v129, v130
	v_cndmask_b32_e32 v2, v115, v2, vcc
	v_mul_f32_e32 v108, v108, v132
	v_fmac_f32_e32 v133, v131, v132
	v_lshl_add_u32 v2, v2, 6, v3
	v_mul_f32_e32 v108, v108, v134
	v_fmac_f32_e32 v135, v133, v134
	v_lshl_add_u32 v2, v2, 2, 0
	v_mul_f32_e32 v108, v108, v136
	v_fmac_f32_e32 v137, v135, v136
	ds_read2st64_b32 v[2:3], v2 offset0:100 offset1:228
	v_mul_f32_e32 v108, v108, v138
	v_fmac_f32_e32 v139, v137, v138
	v_mul_f32_e32 v108, v108, v140
	v_fmac_f32_e32 v141, v139, v140
	s_waitcnt lgkmcnt(3)
	v_mul_f32_e32 v108, v108, v142
	v_fmac_f32_e32 v143, v141, v142
	s_waitcnt lgkmcnt(2)
	v_mul_f32_e32 v108, v108, v144
	v_fmac_f32_e32 v145, v143, v144
	s_waitcnt lgkmcnt(1)
	v_mul_f32_e32 v108, v108, v146
	v_fmac_f32_e32 v147, v145, v146
	v_lshl_add_u32 v0, v0, 2, 0
	s_waitcnt lgkmcnt(0)
	v_mul_f32_e32 v108, v108, v2
	v_fmac_f32_e32 v3, v147, v2
	v_add_u32_e32 v2, 0x16400, v0
	v_add_u32_e32 v0, 0x16c00, v0
	ds_write_b32 v2, v108
	ds_write_b32 v0, v3
	v_cmp_lt_i32_e32 vcc, 0, v114
	v_mov_b32_e32 v0, 1.0
	v_lshl_add_u32 v2, v121, 2, 0
	s_waitcnt vmcnt(0) lgkmcnt(0)
	s_barrier
	s_and_saveexec_b64 s[6:7], vcc
	s_cbranch_execnz .LBB0_434
	s_or_b64 exec, exec, s[6:7]
	v_cmp_lt_i32_e32 vcc, 1, v114
	s_and_saveexec_b64 s[6:7], vcc
	s_cbranch_execnz .LBB0_435

.LBB0_609:
	s_waitcnt vmcnt(0)
	v_cmp_gt_u32_e64 s[98:99], s49, v204
	v_mul_f32_e32 v240, 0xc1000000, v88
	v_mul_f32_e32 v241, 0xc1000000, v89
	v_mul_f32_e32 v242, 0xc1000000, v90
	v_mul_f32_e32 v243, 0xc1000000, v91
	v_mul_f32_e32 v244, 0xc1000000, v92
	v_mul_f32_e32 v245, 0xc1000000, v93
	v_mul_f32_e32 v246, 0xc1000000, v94
	v_mul_f32_e32 v247, 0xc1000000, v95
	v_cndmask_b32_e64 v240, 1.0, v240, s[98:99]
	v_cndmask_b32_e64 v241, 1.0, v241, s[98:99]
	v_cndmask_b32_e64 v242, 1.0, v242, s[98:99]
	v_cndmask_b32_e64 v243, 1.0, v243, s[98:99]
	v_cndmask_b32_e64 v244, 1.0, v244, s[98:99]
	v_cndmask_b32_e64 v245, 1.0, v245, s[98:99]
	v_cndmask_b32_e64 v246, 1.0, v246, s[98:99]
	v_cndmask_b32_e64 v247, 1.0, v247, s[98:99]
	v_mov_b32_e32 v2, v0
	v_mov_b32_e32 v3, v0
	v_mov_b32_e32 v1, v0
	v_mov_b32_e32 v68, 0
	v_mov_b64_e32 v[114:115], v[2:3]
	v_mov_b32_e32 v150, 0
	v_readlane_b32 s12, v238, 15
	s_mov_b32 s13, s3
	s_mov_b32 s2, s97
	v_mov_b64_e32 v[112:113], v[0:1]
	v_mov_b32_e32 v69, v68
	v_mov_b32_e32 v70, v68
	v_mov_b32_e32 v71, v68
	v_mov_b32_e32 v96, v68
	v_mov_b32_e32 v97, v68
	v_mov_b32_e32 v98, v68
	v_mov_b32_e32 v99, v68
	v_mov_b32_e32 v104, v68
	v_mov_b32_e32 v105, v68
	v_mov_b32_e32 v106, v68
	v_mov_b32_e32 v107, v68
	v_mov_b32_e32 v108, v68
	v_mov_b32_e32 v109, v68
	v_mov_b32_e32 v110, v68
	v_mov_b32_e32 v111, v68
	s_branch .LBB0_612

.LBB0_622:
	v_cndmask_b32_e64 v1, 0, 1, s[30:31]
	v_cmp_ne_u32_e64 s[6:7], 1, v1
	s_andn2_b64 vcc, exec, s[30:31]
	s_cbranch_vccnz .LBB0_624
	v_mov_b32_e32 v1, v204
	s_and_b32 s8, s2, 7
	s_lshl_b32 s62, s8, 8
	v_lshlrev_b32_e32 v2, 5, v1
	v_and_b32_e32 v2, 0xe0, v2
	v_or_b32_e32 v2, s62, v2
	v_mov_b32_e32 v3, v0
	s_waitcnt vmcnt(17)
	v_lshl_add_u64 v[12:13], s[24:25], 0, v[2:3]
	s_waitcnt vmcnt(13)
	v_add_co_u32_e32 v24, vcc, s48, v12
	global_load_dwordx4 v[4:7], v2, s[24:25] offset:2064
	global_load_dwordx4 v[8:11], v2, s[24:25] offset:2048
	v_addc_co_u32_e32 v25, vcc, 0, v13, vcc
	global_load_dwordx4 v[12:15], v2, s[54:55]
	global_load_dwordx4 v[16:19], v2, s[56:57]
	global_load_dwordx4 v[20:23], v[24:25], off offset:16
	global_load_dwordx4 v[32:35], v[24:25], off offset:2064
	s_nop 0
	global_load_dwordx4 v[24:27], v2, s[24:25] offset:16
	global_load_dwordx4 v[44:47], v2, s[26:27] offset:16
	global_load_dwordx4 v[36:39], v2, s[24:25]
	global_load_dwordx4 v[48:51], v2, s[26:27]
	s_waitcnt vmcnt(19)
	v_ashrrev_i32_e32 v56, 7, v1
	v_lshrrev_b32_e32 v2, 1, v1
	s_waitcnt vmcnt(15)
	v_and_b32_e32 v82, 32, v2
	v_lshl_or_b32 v2, v56, 3, s8
	v_lshlrev_b32_e32 v56, 11, v56
	v_ashrrev_i32_e32 v3, 31, v2
	v_and_b32_e32 v74, 0x800, v56
	v_mov_b32_e32 v75, v0
	v_lshlrev_b64 v[2:3], 13, v[2:3]
	v_lshl_add_u64 v[56:57], s[52:53], 0, v[74:75]
	v_lshl_add_u64 v[2:3], s[58:59], 0, v[2:3]
	v_and_b32_e32 v72, 48, v1
	v_mov_b32_e32 v73, v0
	v_lshl_add_u64 v[76:77], v[56:57], 0, s[62:63]
	v_and_or_b32 v56, v1, 15, v82
	v_lshl_add_u64 v[2:3], v[2:3], 0, v[72:73]
	v_lshlrev_b32_e32 v78, 7, v56
	v_mov_b32_e32 v79, v0
	v_lshl_add_u64 v[64:65], v[2:3], 0, v[78:79]
	v_mov_b32_e32 v73, s37
	v_mov_b32_e32 v79, s15
	v_cmp_gt_u32_e32 vcc, s49, v1
	v_mov_b32_e32 v1, s36
	v_lshl_or_b32 v72, v82, 2, v72
	v_cndmask_b32_e32 v81, v73, v79, vcc
	v_mov_b32_e32 v73, s14
	v_cndmask_b32_e32 v80, v1, v73, vcc
	v_lshl_add_u64 v[74:75], v[80:81], 0, v[74:75]
	v_lshl_add_u64 v[74:75], v[74:75], 0, s[62:63]
	v_mov_b32_e32 v73, v0
	s_waitcnt vmcnt(14)
	v_lshl_add_u64 v[84:85], v[74:75], 0, v[72:73]
	s_waitcnt vmcnt(12)
	v_lshl_add_u64 v[92:93], v[76:77], 0, v[72:73]
	v_or_b32_e32 v72, 0x800, v78
	v_lshl_add_u64 v[2:3], v[2:3], 0, v[72:73]
	global_load_dwordx4 v[56:59], v[64:65], off
	s_nop 0
	global_load_dwordx4 v[64:67], v[64:65], off offset:64
	s_nop 0
	global_load_dwordx4 v[72:75], v[2:3], off
	global_load_dwordx4 v[76:79], v[2:3], off offset:64
	global_load_dwordx4 v[80:83], v[84:85], off
	s_nop 0
	global_load_dwordx4 v[84:87], v[84:85], off offset:64
	s_nop 0
	global_load_dwordx4 v[88:91], v[92:93], off
	s_nop 0
	global_load_dwordx4 v[92:95], v[92:93], off offset:64
	s_waitcnt vmcnt(0)
	v_cmp_gt_u32_e64 s[98:99], s49, v204
	v_mul_f32_e32 v240, 0xc1000000, v88
	v_mul_f32_e32 v241, 0xc1000000, v89
	v_mul_f32_e32 v242, 0xc1000000, v90
	v_mul_f32_e32 v243, 0xc1000000, v91
	v_mul_f32_e32 v244, 0xc1000000, v92
	v_mul_f32_e32 v245, 0xc1000000, v93
	v_mul_f32_e32 v246, 0xc1000000, v94
	v_mul_f32_e32 v247, 0xc1000000, v95
	v_cndmask_b32_e64 v240, 1.0, v240, s[98:99]
	v_cndmask_b32_e64 v241, 1.0, v241, s[98:99]
	v_cndmask_b32_e64 v242, 1.0, v242, s[98:99]
	v_cndmask_b32_e64 v243, 1.0, v243, s[98:99]
	v_cndmask_b32_e64 v244, 1.0, v244, s[98:99]
	v_cndmask_b32_e64 v245, 1.0, v245, s[98:99]
	v_cndmask_b32_e64 v246, 1.0, v246, s[98:99]
	v_cndmask_b32_e64 v247, 1.0, v247, s[98:99]
.LBB0_624:
	s_nop 0
	v_lshlrev_b32_e32 v2, 16, v40
	v_and_b32_e32 v3, 0xffff0000, v40
	v_pk_fma_f32 v[2:3], v[36:37], v[2:3], v[48:49]
	v_lshlrev_b32_e32 v116, 16, v28
	v_and_b32_e32 v117, 0xffff0000, v28
	v_pk_fma_f32 v[2:3], v[8:9], v[116:117], v[2:3]
	v_lshlrev_b32_e32 v116, 16, v52
	v_and_b32_e32 v117, 0xffff0000, v52
	v_pk_fma_f32 v[2:3], v[12:13], v[116:117], v[2:3]
	v_lshlrev_b32_e32 v116, 16, v60
	v_and_b32_e32 v117, 0xffff0000, v60
	v_pk_fma_f32 v[116:117], v[16:17], v[116:117], v[2:3]
	v_lshlrev_b32_e32 v2, 16, v42
	v_and_b32_e32 v3, 0xffff0000, v42
	v_pk_fma_f32 v[2:3], v[24:25], v[2:3], v[44:45]
	v_lshlrev_b32_e32 v118, 16, v30
	v_and_b32_e32 v119, 0xffff0000, v30
	v_pk_fma_f32 v[2:3], v[4:5], v[118:119], v[2:3]
	v_lshlrev_b32_e32 v118, 16, v54
	v_and_b32_e32 v119, 0xffff0000, v54
	v_pk_fma_f32 v[2:3], v[20:21], v[118:119], v[2:3]
	v_lshlrev_b32_e32 v118, 16, v62
	v_and_b32_e32 v119, 0xffff0000, v62
	v_pk_fma_f32 v[120:121], v[32:33], v[118:119], v[2:3]
	v_lshlrev_b32_e32 v2, 16, v41
	v_and_b32_e32 v3, 0xffff0000, v41
	v_pk_fma_f32 v[2:3], v[38:39], v[2:3], v[50:51]
	v_lshlrev_b32_e32 v118, 16, v29
	v_and_b32_e32 v119, 0xffff0000, v29
	v_pk_fma_f32 v[2:3], v[10:11], v[118:119], v[2:3]
	v_lshlrev_b32_e32 v118, 16, v53
	v_and_b32_e32 v119, 0xffff0000, v53
	v_pk_fma_f32 v[2:3], v[14:15], v[118:119], v[2:3]
	v_lshlrev_b32_e32 v118, 16, v61
	v_and_b32_e32 v119, 0xffff0000, v61
	v_pk_fma_f32 v[118:119], v[18:19], v[118:119], v[2:3]
	v_lshlrev_b32_e32 v2, 16, v43
	v_and_b32_e32 v3, 0xffff0000, v43
	v_pk_fma_f32 v[2:3], v[26:27], v[2:3], v[46:47]
	v_lshlrev_b32_e32 v122, 16, v31
	v_and_b32_e32 v123, 0xffff0000, v31
	v_pk_fma_f32 v[2:3], v[6:7], v[122:123], v[2:3]
	v_lshlrev_b32_e32 v122, 16, v55
	v_and_b32_e32 v123, 0xffff0000, v55
	v_mov_b32_e32 v152, v204
	v_pk_fma_f32 v[2:3], v[22:23], v[122:123], v[2:3]
	v_lshlrev_b32_e32 v122, 16, v63
	v_and_b32_e32 v123, 0xffff0000, v63
	v_pk_fma_f32 v[122:123], v[34:35], v[122:123], v[2:3]
	v_lshlrev_b32_e32 v1, 3, v152
	v_ashrrev_i32_e32 v2, 3, v152
	v_and_b32_e32 v1, 56, v1
	v_lshl_add_u32 v151, v2, 8, 0
	v_lshl_add_u32 v3, v1, 2, v151
	ds_write_b128 v3, v[116:119]
	ds_write_b128 v3, v[120:123] offset:16
	v_cvt_pk_bf16_f32 v116, v116, v117
	v_cvt_pk_bf16_f32 v117, v118, v119
	v_cvt_pk_bf16_f32 v118, v120, v121
	v_mul_lo_u32 v120, v2, s1
	v_lshlrev_b32_e32 v121, 1, v1
	v_and_b32_e32 v162, 15, v152
	v_cvt_pk_bf16_f32 v119, v122, v123
	v_add3_u32 v120, v151, v120, v121
	v_and_b32_e32 v153, 48, v152
	ds_write_b128 v120, v[116:119] offset:16384
	v_mul_u32_u24_e32 v116, 0x90, v162
	v_add3_u32 v163, 0, v153, v116
	s_waitcnt lgkmcnt(0)
	s_barrier
	ds_read_b128 v[128:131], v163 offset:20992
	s_waitcnt lgkmcnt(0)
	v_mfma_f32_16x16x32_bf16 v[136:139], v[56:59], v[128:131], 0
	ds_read_b128 v[116:119], v163 offset:16384
	ds_read_b128 v[124:127], v163 offset:18688
	s_add_i32 s51, 0, 0xe400
	v_mfma_f32_16x16x32_bf16 v[140:143], v[72:75], v[128:131], 0
	ds_read_b128 v[128:131], v163 offset:23296
	v_cmp_gt_u32_e32 vcc, s49, v152
	s_waitcnt lgkmcnt(0)
	v_mfma_f32_16x16x32_bf16 v[144:147], v[56:59], v[128:131], 0
	v_mfma_f32_16x16x32_bf16 v[154:157], v[72:75], v[128:131], 0
	ds_read_b128 v[128:131], v163 offset:16448
	v_mfma_f32_16x16x32_bf16 v[120:123], v[56:59], v[116:119], 0
	v_mfma_f32_16x16x32_bf16 v[116:119], v[72:75], v[116:119], 0
	s_waitcnt lgkmcnt(0)
	v_mfma_f32_16x16x32_bf16 v[158:161], v[64:67], v[128:131], v[120:123]
	v_mfma_f32_16x16x32_bf16 v[128:131], v[76:79], v[128:131], v[116:119]
	s_nop 4
	ds_read_b128 v[116:119], v163 offset:18752
	v_mfma_f32_16x16x32_bf16 v[132:135], v[56:59], v[124:127], 0
	s_nop 0
	v_add_f32_e32 v128, v84, v128
	v_mul_f32_e32 v128, 0xbfb8aa3b, v128
	v_exp_f32_e32 v128, v128
	v_mfma_f32_16x16x32_bf16 v[124:127], v[72:75], v[124:127], 0
	v_add_f32_e32 v129, v85, v129
	v_mul_f32_e32 v129, 0xbfb8aa3b, v129
	v_exp_f32_e32 v129, v129
	s_waitcnt lgkmcnt(0)
	v_mfma_f32_16x16x32_bf16 v[132:135], v[64:67], v[116:119], v[132:135]
	v_add_f32_e32 v130, v86, v130
	v_mul_f32_e32 v130, 0xbfb8aa3b, v130
	v_add_f32_e32 v128, 1.0, v128
	v_mfma_f32_16x16x32_bf16 v[124:127], v[76:79], v[116:119], v[124:127]
	ds_read_b128 v[116:119], v163 offset:21056
	s_nop 2
	v_add_f32_e32 v132, v80, v132
	v_mul_f32_e32 v132, 0xbfb8aa3b, v132
	s_waitcnt lgkmcnt(0)
	v_mfma_f32_16x16x32_bf16 v[136:139], v[64:67], v[116:119], v[136:139]
	v_exp_f32_e32 v132, v132
	v_add_f32_e32 v133, v81, v133
	v_mul_f32_e32 v133, 0xbfb8aa3b, v133
	v_mfma_f32_16x16x32_bf16 v[120:123], v[76:79], v[116:119], v[140:143]
	ds_read_b128 v[116:119], v163 offset:23360
	v_exp_f32_e32 v133, v133
	v_add_f32_e32 v134, v82, v134
	s_waitcnt lgkmcnt(0)
	v_mfma_f32_16x16x32_bf16 v[140:143], v[64:67], v[116:119], v[144:147]
	v_mul_f32_e32 v134, 0xbfb8aa3b, v134
	s_nop 1
	v_mov_b32_e32 v144, s51
	v_mov_b32_e32 v145, s81
	v_cndmask_b32_e32 v144, v144, v145, vcc
	v_lshlrev_b32_e32 v145, 7, v152
	v_and_b32_e32 v145, 0x4000, v145
	v_lshlrev_b32_e32 v146, 8, v162
	v_add3_u32 v144, v144, v145, v146
	v_add_f32_e32 v146, v80, v158
	v_mul_f32_e32 v146, 0xbfb8aa3b, v146
	v_add_f32_e32 v147, v81, v159
	v_exp_f32_e32 v146, v146
	v_mul_f32_e32 v147, 0xbfb8aa3b, v147
	v_exp_f32_e32 v147, v147
	v_lshlrev_b32_e32 v145, 1, v152
	v_and_b32_e32 v145, 0x80, v145
	v_add_f32_e32 v146, 1.0, v146
	v_rcp_f32_e32 v146, v146
	v_add3_u32 v153, v144, v145, v153
	v_add_f32_e32 v144, 1.0, v147
	v_add_f32_e32 v147, v82, v160
	v_mul_f32_e32 v147, 0xbfb8aa3b, v147
	v_mfma_f32_16x16x32_bf16 v[116:119], v[76:79], v[116:119], v[154:157]
	v_rcp_f32_e32 v145, v144
	v_exp_f32_e32 v147, v147

	s_nop 0
	v_add_f32_e32 v154, v83, v161
	v_mul_f32_e32 v154, 0xbfb8aa3b, v154
	v_exp_f32_e32 v154, v154
	s_nop 0

	v_mul_f32_e32 v144, v240, v146

	v_add_f32_e32 v147, 1.0, v147

	v_rcp_f32_e32 v147, v147
	v_mul_f32_e32 v145, v241, v145
	v_add_f32_e32 v146, 1.0, v154
	v_rcp_f32_e32 v154, v146

	v_add_f32_e32 v132, 1.0, v132
	v_exp_f32_e32 v134, v134
	v_add_f32_e32 v135, v83, v135

	v_rcp_f32_e32 v132, v132
	v_mul_f32_e32 v135, 0xbfb8aa3b, v135
	v_mul_f32_e32 v146, v242, v147

	v_add_f32_e32 v133, 1.0, v133
	v_exp_f32_e32 v135, v135

	v_rcp_f32_e32 v133, v133
	v_mul_f32_e32 v147, v243, v154
	v_add_f32_e32 v134, 1.0, v134
	v_add_f32_e32 v136, v80, v136
	ds_write_b128 v153, v[144:147]

	v_rcp_f32_e32 v134, v134
	v_mul_f32_e32 v136, 0xbfb8aa3b, v136

	v_add_f32_e32 v135, 1.0, v135
	v_exp_f32_e32 v136, v136
	v_mul_f32_e32 v132, v240, v132

	v_rcp_f32_e32 v135, v135

	v_add_f32_e32 v137, v81, v137
	v_mul_f32_e32 v133, v241, v133

	v_mul_f32_e32 v137, 0xbfb8aa3b, v137

	v_exp_f32_e32 v137, v137
	v_add_f32_e32 v136, 1.0, v136
	v_mul_f32_e32 v134, v242, v134

	v_rcp_f32_e32 v136, v136

	v_mul_f32_e32 v135, v243, v135
	ds_write_b128 v153, v[132:135] offset:4096
	v_add_f32_e32 v132, 1.0, v137
	v_rcp_f32_e32 v133, v132

	v_add_f32_e32 v135, v82, v138

	v_mul_f32_e32 v135, 0xbfb8aa3b, v135
	v_mul_f32_e32 v132, v240, v136
	v_exp_f32_e32 v135, v135
	v_add_f32_e32 v136, v83, v139
	v_mul_f32_e32 v136, 0xbfb8aa3b, v136
	v_exp_f32_e32 v136, v136

	v_add_f32_e32 v135, 1.0, v135

	v_rcp_f32_e32 v135, v135
	v_mul_f32_e32 v133, v241, v133
	v_add_f32_e32 v134, 1.0, v136
	v_rcp_f32_e32 v136, v134


	v_mul_f32_e32 v134, v242, v135


	v_mul_f32_e32 v135, v243, v136
	v_add_f32_e32 v136, v80, v140
	v_mul_f32_e32 v136, 0xbfb8aa3b, v136
	v_exp_f32_e32 v136, v136
	v_add_f32_e32 v137, v81, v141
	v_mul_f32_e32 v137, 0xbfb8aa3b, v137
	v_exp_f32_e32 v137, v137
	v_add_f32_e32 v136, 1.0, v136
	v_rcp_f32_e32 v136, v136
	ds_write_b128 v153, v[132:135] offset:8192
	v_add_f32_e32 v132, 1.0, v137
	v_rcp_f32_e32 v133, v132

	v_add_f32_e32 v135, v82, v142

	v_mul_f32_e32 v135, 0xbfb8aa3b, v135
	v_mul_f32_e32 v132, v240, v136
	v_exp_f32_e32 v135, v135
	v_add_f32_e32 v136, v83, v143
	v_mul_f32_e32 v136, 0xbfb8aa3b, v136
	v_exp_f32_e32 v136, v136

	v_add_f32_e32 v135, 1.0, v135

	v_rcp_f32_e32 v135, v135
	v_mul_f32_e32 v133, v241, v133
	v_add_f32_e32 v134, 1.0, v136
	v_rcp_f32_e32 v136, v134

	v_exp_f32_e32 v130, v130
	v_add_f32_e32 v131, v87, v131

	v_rcp_f32_e32 v128, v128
	v_mul_f32_e32 v131, 0xbfb8aa3b, v131
	v_mul_f32_e32 v134, v242, v135

	v_add_f32_e32 v129, 1.0, v129
	v_exp_f32_e32 v131, v131

	v_rcp_f32_e32 v129, v129
	v_add_f32_e32 v124, v84, v124
	v_mul_f32_e32 v135, v243, v136
	v_add_f32_e32 v130, 1.0, v130
	v_mul_f32_e32 v124, 0xbfb8aa3b, v124
	ds_write_b128 v153, v[132:135] offset:12288

	v_rcp_f32_e32 v130, v130
	v_exp_f32_e32 v124, v124
	v_add_f32_e32 v125, v85, v125
	s_nop 0

	v_add_f32_e32 v131, 1.0, v131
	v_mul_f32_e32 v125, 0xbfb8aa3b, v125
	v_mul_f32_e32 v128, v244, v128

	v_rcp_f32_e32 v131, v131
	v_exp_f32_e32 v125, v125
	v_add_f32_e32 v126, v86, v126

	v_mul_f32_e32 v126, 0xbfb8aa3b, v126
	v_mul_f32_e32 v129, v245, v129

	v_add_f32_e32 v124, 1.0, v124
	v_exp_f32_e32 v126, v126
	v_add_f32_e32 v127, v87, v127

	v_rcp_f32_e32 v124, v124
	v_mul_f32_e32 v127, 0xbfb8aa3b, v127
	v_mul_f32_e32 v130, v246, v130

	v_add_f32_e32 v125, 1.0, v125
	v_exp_f32_e32 v127, v127

	v_rcp_f32_e32 v125, v125
	v_add_f32_e32 v120, v84, v120
	v_mul_f32_e32 v131, v247, v131
	v_add_f32_e32 v126, 1.0, v126
	v_mul_f32_e32 v120, 0xbfb8aa3b, v120
	ds_write_b128 v153, v[128:131] offset:64

	v_rcp_f32_e32 v126, v126
	v_exp_f32_e32 v120, v120
	v_add_f32_e32 v121, v85, v121

	v_add_f32_e32 v127, 1.0, v127
	v_mul_f32_e32 v121, 0xbfb8aa3b, v121
	v_mul_f32_e32 v124, v244, v124

	v_rcp_f32_e32 v127, v127
	v_exp_f32_e32 v121, v121
	v_add_f32_e32 v122, v86, v122

	v_mul_f32_e32 v122, 0xbfb8aa3b, v122
	v_mul_f32_e32 v125, v245, v125

	v_add_f32_e32 v120, 1.0, v120
	v_exp_f32_e32 v122, v122
	v_add_f32_e32 v123, v87, v123

	v_rcp_f32_e32 v120, v120
	v_mul_f32_e32 v123, 0xbfb8aa3b, v123
	v_mul_f32_e32 v126, v246, v126

	v_add_f32_e32 v121, 1.0, v121
	v_exp_f32_e32 v123, v123

	v_rcp_f32_e32 v121, v121
	v_add_f32_e32 v116, v84, v116
	v_mul_f32_e32 v127, v247, v127
	v_add_f32_e32 v122, 1.0, v122
	v_mul_f32_e32 v116, 0xbfb8aa3b, v116
	ds_write_b128 v153, v[124:127] offset:4160

	v_rcp_f32_e32 v122, v122
	v_exp_f32_e32 v116, v116
	v_add_f32_e32 v117, v85, v117

	v_add_f32_e32 v123, 1.0, v123
	v_mul_f32_e32 v117, 0xbfb8aa3b, v117
	v_mul_f32_e32 v120, v244, v120

	v_rcp_f32_e32 v123, v123
	v_exp_f32_e32 v117, v117
	v_add_f32_e32 v118, v86, v118

	v_mul_f32_e32 v118, 0xbfb8aa3b, v118
	v_mul_f32_e32 v121, v245, v121

	v_add_f32_e32 v116, 1.0, v116
	v_exp_f32_e32 v118, v118
	v_add_f32_e32 v119, v87, v119

	v_rcp_f32_e32 v116, v116
	v_mul_f32_e32 v119, 0xbfb8aa3b, v119
	v_mul_f32_e32 v122, v246, v122

	v_add_f32_e32 v117, 1.0, v117
	v_exp_f32_e32 v119, v119

	v_rcp_f32_e32 v117, v117
	v_mul_f32_e32 v123, v247, v123
	v_add_f32_e32 v118, 1.0, v118
	ds_write_b128 v153, v[120:123] offset:8256

	v_rcp_f32_e32 v118, v118

	v_add_f32_e32 v119, 1.0, v119
	v_mul_f32_e32 v116, v244, v116

	v_rcp_f32_e32 v119, v119

	v_mul_f32_e32 v117, v245, v117


	v_mul_f32_e32 v118, v246, v118


	v_mul_f32_e32 v119, v247, v119
	v_lshlrev_b32_e32 v133, 2, v152
	ds_write_b128 v153, v[116:119] offset:12352
	v_and_b32_e32 v116, 60, v133
	v_lshlrev_b32_e32 v132, 2, v116
	v_lshlrev_b32_e32 v116, 4, v152
	v_and_b32_e32 v117, 0xffffc000, v116
	v_add_u32_e32 v117, 0, v117
	v_and_b32_e32 v116, 0x3f00, v116
	v_add3_u32 v135, v117, v116, v132
	s_waitcnt lgkmcnt(0)
	s_barrier
	ds_read_b128 v[128:131], v135 offset:25600
	ds_read_b128 v[120:123], v135 offset:58368
	v_add_u32_e32 v134, 0, v132
	v_add_u32_e32 v136, v134, v116
	ds_read_b128 v[124:127], v136
	s_waitcnt lgkmcnt(2)
	v_mul_f32_e32 v116, 0x3fb8aa3b, v128
	v_exp_f32_e32 v116, v116
	v_add_f32_e32 v117, v128, v128
	v_cmp_nlt_f32_e32 vcc, s79, v117
	s_and_saveexec_b64 s[8:9], vcc
	s_xor_b64 s[8:9], exec, s[8:9]
	v_fma_f32 v128, -v116, v116, 1.0
	s_andn2_saveexec_b64 s[8:9], s[8:9]
	v_fmamk_f32 v118, v117, 0x3c088889, v148
	v_fmaak_f32 v118, v117, v118, 0x3e2aaaab
	v_fma_f32 v118, v117, v118, 0.5
	v_fma_f32 v118, v117, v118, 1.0
	v_mul_f32_e64 v128, v118, -v117
	s_or_b64 exec, exec, s[8:9]
	v_mul_f32_e32 v117, 0x3fb8aa3b, v129
	v_exp_f32_e32 v117, v117
	v_add_f32_e32 v118, v129, v129
	v_cmp_nlt_f32_e32 vcc, s79, v118
	s_and_saveexec_b64 s[8:9], vcc
	s_xor_b64 s[8:9], exec, s[8:9]
	v_fma_f32 v129, -v117, v117, 1.0
	s_andn2_saveexec_b64 s[8:9], s[8:9]
	v_fmamk_f32 v119, v118, 0x3c088889, v148
	v_fmaak_f32 v119, v118, v119, 0x3e2aaaab
	v_fma_f32 v119, v118, v119, 0.5
	v_fma_f32 v119, v118, v119, 1.0
	v_mul_f32_e64 v129, v119, -v118
	s_or_b64 exec, exec, s[8:9]
	v_mul_f32_e32 v118, 0x3fb8aa3b, v130
	v_exp_f32_e32 v118, v118
	v_add_f32_e32 v119, v130, v130
	v_cmp_nlt_f32_e32 vcc, s79, v119
	s_and_saveexec_b64 s[8:9], vcc
	s_xor_b64 s[8:9], exec, s[8:9]
	v_fma_f32 v130, -v118, v118, 1.0
	s_andn2_saveexec_b64 s[8:9], s[8:9]
	v_fmamk_f32 v130, v119, 0x3c088889, v148
	v_fmaak_f32 v130, v119, v130, 0x3e2aaaab
	v_fma_f32 v130, v119, v130, 0.5
	v_fma_f32 v130, v119, v130, 1.0
	v_mul_f32_e64 v130, v130, -v119
	s_or_b64 exec, exec, s[8:9]
	v_mul_f32_e32 v119, 0x3fb8aa3b, v131
	v_exp_f32_e32 v119, v119
	v_add_f32_e32 v137, v131, v131
	v_cmp_nlt_f32_e32 vcc, s79, v137
	s_and_saveexec_b64 s[8:9], vcc
	s_xor_b64 s[8:9], exec, s[8:9]
	v_fma_f32 v131, -v119, v119, 1.0
	s_andn2_saveexec_b64 s[8:9], s[8:9]
	v_fmamk_f32 v131, v137, 0x3c088889, v148
	v_fmaak_f32 v131, v137, v131, 0x3e2aaaab
	v_fma_f32 v131, v137, v131, 0.5
	v_fma_f32 v131, v137, v131, 1.0
	v_mul_f32_e64 v131, v131, -v137
	s_or_b64 exec, exec, s[8:9]
	v_max_f32_e32 v128, v128, v128
	v_max_f32_e32 v128, 0, v128
	v_sqrt_f32_e32 v128, v128
	v_max_f32_e32 v129, v129, v129
	v_max_f32_e32 v129, 0, v129
	v_sqrt_f32_e32 v129, v129
	s_waitcnt lgkmcnt(1)
	v_mul_f32_e32 v120, v120, v128
	s_waitcnt lgkmcnt(0)
	v_mul_f32_e32 v120, v124, v120
	v_max_f32_e32 v124, v130, v130
	v_max_f32_e32 v128, v131, v131
	v_max_f32_e32 v124, 0, v124
	v_max_f32_e32 v128, 0, v128
	v_sqrt_f32_e32 v124, v124
	v_sqrt_f32_e32 v128, v128
	v_mul_f32_e32 v121, v121, v129
	v_mul_f32_e32 v121, v125, v121
	v_mul_f32_e32 v122, v122, v124
	v_mul_f32_e32 v123, v123, v128
	v_mul_f32_e32 v122, v126, v122
	v_mul_f32_e32 v123, v127, v123
	ds_write_b128 v135, v[116:119] offset:25600
	ds_write_b128 v135, v[120:123] offset:58368
	v_add_u32_e32 v116, 0x800, v133
	v_and_b32_e32 v117, 0x3ffff000, v116
	v_and_b32_e32 v116, 0xfc0, v116
	v_lshl_add_u32 v117, v117, 2, 0
	v_lshlrev_b32_e32 v116, 2, v116
	v_add3_u32 v137, v117, v116, v132
	ds_read_b128 v[128:131], v137 offset:25600
	ds_read_b128 v[120:123], v137 offset:58368
	v_add_u32_e32 v116, v134, v116
	ds_read_b128 v[124:127], v116
	s_waitcnt lgkmcnt(2)
	v_mul_f32_e32 v116, 0x3fb8aa3b, v128
	v_exp_f32_e32 v116, v116
	v_add_f32_e32 v117, v128, v128
	v_cmp_nlt_f32_e32 vcc, s79, v117
	s_and_saveexec_b64 s[8:9], vcc
	s_xor_b64 s[8:9], exec, s[8:9]
	v_fma_f32 v128, -v116, v116, 1.0
	s_andn2_saveexec_b64 s[8:9], s[8:9]
	v_fmamk_f32 v118, v117, 0x3c088889, v148
	v_fmaak_f32 v118, v117, v118, 0x3e2aaaab
	v_fma_f32 v118, v117, v118, 0.5
	v_fma_f32 v118, v117, v118, 1.0
	v_mul_f32_e64 v128, v118, -v117
	s_or_b64 exec, exec, s[8:9]
	v_mul_f32_e32 v117, 0x3fb8aa3b, v129
	v_exp_f32_e32 v117, v117
	v_add_f32_e32 v118, v129, v129
	v_cmp_nlt_f32_e32 vcc, s79, v118
	s_and_saveexec_b64 s[8:9], vcc
	s_xor_b64 s[8:9], exec, s[8:9]
	v_fma_f32 v129, -v117, v117, 1.0
	s_andn2_saveexec_b64 s[8:9], s[8:9]
	v_fmamk_f32 v119, v118, 0x3c088889, v148
	v_fmaak_f32 v119, v118, v119, 0x3e2aaaab
	v_fma_f32 v119, v118, v119, 0.5
	v_fma_f32 v119, v118, v119, 1.0
	v_mul_f32_e64 v129, v119, -v118
	s_or_b64 exec, exec, s[8:9]
	v_mul_f32_e32 v118, 0x3fb8aa3b, v130
	v_exp_f32_e32 v118, v118
	v_add_f32_e32 v119, v130, v130
	v_cmp_nlt_f32_e32 vcc, s79, v119
	s_and_saveexec_b64 s[8:9], vcc
	s_xor_b64 s[8:9], exec, s[8:9]
	v_fma_f32 v130, -v118, v118, 1.0
	s_andn2_saveexec_b64 s[8:9], s[8:9]
	v_fmamk_f32 v130, v119, 0x3c088889, v148
	v_fmaak_f32 v130, v119, v130, 0x3e2aaaab
	v_fma_f32 v130, v119, v130, 0.5
	v_fma_f32 v130, v119, v130, 1.0
	v_mul_f32_e64 v130, v130, -v119
	s_or_b64 exec, exec, s[8:9]
	v_mul_f32_e32 v119, 0x3fb8aa3b, v131
	v_exp_f32_e32 v119, v119
	v_add_f32_e32 v138, v131, v131
	v_cmp_nlt_f32_e32 vcc, s79, v138
	s_and_saveexec_b64 s[8:9], vcc
	s_xor_b64 s[8:9], exec, s[8:9]
	v_fma_f32 v131, -v119, v119, 1.0
	s_andn2_saveexec_b64 s[8:9], s[8:9]
	v_fmamk_f32 v131, v138, 0x3c088889, v148
	v_fmaak_f32 v131, v138, v131, 0x3e2aaaab
	v_fma_f32 v131, v138, v131, 0.5
	v_fma_f32 v131, v138, v131, 1.0
	v_mul_f32_e64 v131, v131, -v138
	s_or_b64 exec, exec, s[8:9]
	v_max_f32_e32 v128, v128, v128
	v_max_f32_e32 v128, 0, v128
	v_sqrt_f32_e32 v128, v128
	v_max_f32_e32 v129, v129, v129
	v_max_f32_e32 v129, 0, v129
	v_sqrt_f32_e32 v129, v129
	s_waitcnt lgkmcnt(1)
	v_mul_f32_e32 v120, v120, v128
	s_waitcnt lgkmcnt(0)
	v_mul_f32_e32 v120, v124, v120
	v_max_f32_e32 v124, v130, v130
	v_max_f32_e32 v128, v131, v131
	v_max_f32_e32 v124, 0, v124
	v_max_f32_e32 v128, 0, v128
	v_sqrt_f32_e32 v124, v124
	v_sqrt_f32_e32 v128, v128
	v_mul_f32_e32 v121, v121, v129
	v_mul_f32_e32 v121, v125, v121
	v_mul_f32_e32 v122, v122, v124
	v_mul_f32_e32 v123, v123, v128
	v_mul_f32_e32 v122, v126, v122
	v_mul_f32_e32 v123, v127, v123
	ds_write_b128 v137, v[116:119] offset:25600
	ds_write_b128 v137, v[120:123] offset:58368
	ds_read_b128 v[128:131], v135 offset:41984
	v_add_u32_e32 v137, 0xe400, v135
	ds_read_b128 v[120:123], v137 offset:16384
	ds_read_b128 v[124:127], v136
	s_waitcnt lgkmcnt(2)
	v_mul_f32_e32 v116, 0x3fb8aa3b, v128
	v_exp_f32_e32 v116, v116
	v_add_f32_e32 v117, v128, v128
	v_cmp_nlt_f32_e32 vcc, s79, v117
	s_and_saveexec_b64 s[8:9], vcc
	s_xor_b64 s[8:9], exec, s[8:9]
	v_fma_f32 v128, -v116, v116, 1.0
	s_andn2_saveexec_b64 s[8:9], s[8:9]
	v_fmamk_f32 v118, v117, 0x3c088889, v148
	v_fmaak_f32 v118, v117, v118, 0x3e2aaaab
	v_fma_f32 v118, v117, v118, 0.5
	v_fma_f32 v118, v117, v118, 1.0
	v_mul_f32_e64 v128, v118, -v117
	s_or_b64 exec, exec, s[8:9]
	v_mul_f32_e32 v117, 0x3fb8aa3b, v129
	v_exp_f32_e32 v117, v117
	v_add_f32_e32 v118, v129, v129
	v_cmp_nlt_f32_e32 vcc, s79, v118
	s_and_saveexec_b64 s[8:9], vcc
	s_xor_b64 s[8:9], exec, s[8:9]
	v_fma_f32 v129, -v117, v117, 1.0
	s_andn2_saveexec_b64 s[8:9], s[8:9]
	v_fmamk_f32 v119, v118, 0x3c088889, v148
	v_fmaak_f32 v119, v118, v119, 0x3e2aaaab
	v_fma_f32 v119, v118, v119, 0.5
	v_fma_f32 v119, v118, v119, 1.0
	v_mul_f32_e64 v129, v119, -v118
	s_or_b64 exec, exec, s[8:9]
	v_mul_f32_e32 v118, 0x3fb8aa3b, v130
	v_exp_f32_e32 v118, v118
	v_add_f32_e32 v119, v130, v130
	v_cmp_nlt_f32_e32 vcc, s79, v119
	s_and_saveexec_b64 s[8:9], vcc
	s_xor_b64 s[8:9], exec, s[8:9]
	v_fma_f32 v130, -v118, v118, 1.0
	s_andn2_saveexec_b64 s[8:9], s[8:9]
	v_fmamk_f32 v130, v119, 0x3c088889, v148
	v_fmaak_f32 v130, v119, v130, 0x3e2aaaab
	v_fma_f32 v130, v119, v130, 0.5
	v_fma_f32 v130, v119, v130, 1.0
	v_mul_f32_e64 v130, v130, -v119
	s_or_b64 exec, exec, s[8:9]
	v_mul_f32_e32 v119, 0x3fb8aa3b, v131
	v_exp_f32_e32 v119, v119
	v_add_f32_e32 v136, v131, v131
	v_cmp_nlt_f32_e32 vcc, s79, v136
	s_and_saveexec_b64 s[8:9], vcc
	s_xor_b64 s[8:9], exec, s[8:9]
	v_fma_f32 v131, -v119, v119, 1.0
	s_andn2_saveexec_b64 s[8:9], s[8:9]
	v_fmamk_f32 v131, v136, 0x3c088889, v148
	v_fmaak_f32 v131, v136, v131, 0x3e2aaaab
	v_fma_f32 v131, v136, v131, 0.5
	v_fma_f32 v131, v136, v131, 1.0
	v_mul_f32_e64 v131, v131, -v136
	s_or_b64 exec, exec, s[8:9]
	v_max_f32_e32 v128, v128, v128
	v_max_f32_e32 v128, 0, v128
	v_sqrt_f32_e32 v128, v128
	v_max_f32_e32 v129, v129, v129
	v_max_f32_e32 v129, 0, v129
	v_sqrt_f32_e32 v129, v129
	s_waitcnt lgkmcnt(1)
	v_mul_f32_e32 v120, v120, v128
	s_waitcnt lgkmcnt(0)
	v_mul_f32_e32 v120, v124, v120
	v_max_f32_e32 v124, v130, v130
	v_max_f32_e32 v128, v131, v131
	v_max_f32_e32 v124, 0, v124
	v_max_f32_e32 v128, 0, v128
	v_sqrt_f32_e32 v124, v124
	v_sqrt_f32_e32 v128, v128
	v_mul_f32_e32 v121, v121, v129
	v_mul_f32_e32 v121, v125, v121
	v_mul_f32_e32 v122, v122, v124
	v_mul_f32_e32 v123, v123, v128
	v_mul_f32_e32 v122, v126, v122
	v_mul_f32_e32 v123, v127, v123
	ds_write_b128 v135, v[116:119] offset:41984
	ds_write_b128 v137, v[120:123] offset:16384
	v_add_u32_e32 v116, 0x1800, v133
	v_and_b32_e32 v117, 0x3ffff000, v116
	v_and_b32_e32 v116, 0xfc0, v116
	v_lshl_add_u32 v117, v117, 2, 0
	v_lshlrev_b32_e32 v116, 2, v116
	v_add3_u32 v132, v117, v116, v132
	ds_read_b128 v[128:131], v132 offset:25600
	ds_read_b128 v[120:123], v132 offset:58368
	v_add_u32_e32 v116, v134, v116
	ds_read_b128 v[124:127], v116
	s_waitcnt lgkmcnt(2)
	v_mul_f32_e32 v116, 0x3fb8aa3b, v128
	v_exp_f32_e32 v116, v116
	v_add_f32_e32 v117, v128, v128
	v_cmp_nlt_f32_e32 vcc, s79, v117
	s_and_saveexec_b64 s[8:9], vcc
	s_xor_b64 s[8:9], exec, s[8:9]
	v_fma_f32 v128, -v116, v116, 1.0
	s_andn2_saveexec_b64 s[8:9], s[8:9]
	v_fmamk_f32 v118, v117, 0x3c088889, v148
	v_fmaak_f32 v118, v117, v118, 0x3e2aaaab
	v_fma_f32 v118, v117, v118, 0.5
	v_fma_f32 v118, v117, v118, 1.0
	v_mul_f32_e64 v128, v118, -v117
	s_or_b64 exec, exec, s[8:9]
	v_mul_f32_e32 v117, 0x3fb8aa3b, v129
	v_exp_f32_e32 v117, v117
	v_add_f32_e32 v118, v129, v129
	v_cmp_nlt_f32_e32 vcc, s79, v118
	s_and_saveexec_b64 s[8:9], vcc
	s_xor_b64 s[8:9], exec, s[8:9]
	v_fma_f32 v129, -v117, v117, 1.0
	s_andn2_saveexec_b64 s[8:9], s[8:9]
	v_fmamk_f32 v119, v118, 0x3c088889, v148
	v_fmaak_f32 v119, v118, v119, 0x3e2aaaab
	v_fma_f32 v119, v118, v119, 0.5
	v_fma_f32 v119, v118, v119, 1.0
	v_mul_f32_e64 v129, v119, -v118
	s_or_b64 exec, exec, s[8:9]
	v_mul_f32_e32 v118, 0x3fb8aa3b, v130
	v_exp_f32_e32 v118, v118
	v_add_f32_e32 v119, v130, v130
	v_cmp_nlt_f32_e32 vcc, s79, v119
	s_and_saveexec_b64 s[8:9], vcc
	s_xor_b64 s[8:9], exec, s[8:9]
	v_fma_f32 v130, -v118, v118, 1.0
	s_andn2_saveexec_b64 s[8:9], s[8:9]
	v_fmamk_f32 v130, v119, 0x3c088889, v148
	v_fmaak_f32 v130, v119, v130, 0x3e2aaaab
	v_fma_f32 v130, v119, v130, 0.5
	v_fma_f32 v130, v119, v130, 1.0
	v_mul_f32_e64 v130, v130, -v119
	s_or_b64 exec, exec, s[8:9]
	v_mul_f32_e32 v119, 0x3fb8aa3b, v131
	v_exp_f32_e32 v119, v119
	v_add_f32_e32 v133, v131, v131
	v_cmp_nlt_f32_e32 vcc, s79, v133
	s_and_saveexec_b64 s[8:9], vcc
	s_xor_b64 s[8:9], exec, s[8:9]
	v_fma_f32 v131, -v119, v119, 1.0
	s_andn2_saveexec_b64 s[8:9], s[8:9]
	v_fmamk_f32 v131, v133, 0x3c088889, v148
	v_fmaak_f32 v131, v133, v131, 0x3e2aaaab
	v_fma_f32 v131, v133, v131, 0.5
	v_fma_f32 v131, v133, v131, 1.0
	v_mul_f32_e64 v131, v131, -v133
	s_or_b64 exec, exec, s[8:9]
	v_max_f32_e32 v128, v128, v128
	v_max_f32_e32 v128, 0, v128
	v_sqrt_f32_e32 v128, v128
	v_max_f32_e32 v129, v129, v129
	v_max_f32_e32 v129, 0, v129
	v_sqrt_f32_e32 v129, v129
	s_waitcnt lgkmcnt(1)
	v_mul_f32_e32 v120, v120, v128
	v_max_f32_e32 v128, v130, v130
	s_waitcnt lgkmcnt(0)
	v_mul_f32_e32 v120, v124, v120
	v_max_f32_e32 v124, v131, v131
	v_max_f32_e32 v128, 0, v128
	v_max_f32_e32 v124, 0, v124
	v_sqrt_f32_e32 v128, v128
	v_sqrt_f32_e32 v124, v124
	v_ashrrev_i32_e32 v156, 7, v152
	v_mul_f32_e32 v121, v121, v129
	v_mul_f32_e32 v122, v122, v128
	v_and_b32_e32 v172, 0x7f, v152
	v_mul_f32_e32 v123, v123, v124
	v_lshlrev_b32_e32 v146, 4, v156
	v_mul_f32_e32 v121, v125, v121
	v_mul_f32_e32 v122, v126, v122
	v_bfe_u32 v153, v152, 6, 1
	v_mul_f32_e32 v123, v127, v123
	ds_write_b128 v132, v[116:119] offset:25600
	ds_write_b128 v132, v[120:123] offset:58368
	v_and_b32_e32 v154, 63, v152
	v_sub_u32_e32 v116, 63, v146
	v_cmp_gt_u32_e32 vcc, 64, v172
	v_or_b32_e32 v118, 1, v146
	v_lshl_or_b32 v147, v153, 12, v154
	v_cndmask_b32_e32 v155, v116, v146, vcc
	v_sub_u32_e32 v119, 63, v118
	v_or_b32_e32 v120, 2, v146
	v_lshl_add_u32 v116, v155, 6, v147
	v_cndmask_b32_e32 v157, v119, v118, vcc
	v_sub_u32_e32 v121, 63, v120
	v_or_b32_e32 v122, 3, v146
	v_lshl_add_u32 v116, v116, 2, 0
	v_lshl_add_u32 v118, v157, 6, v147
	v_cndmask_b32_e32 v158, v121, v120, vcc
	v_sub_u32_e32 v123, 63, v122
	v_or_b32_e32 v124, 4, v146
	s_waitcnt lgkmcnt(0)
	s_barrier
	ds_read2st64_b32 v[116:117], v116 offset0:100 offset1:228
	v_lshl_add_u32 v118, v118, 2, 0
	v_lshl_add_u32 v120, v158, 6, v147
	v_cndmask_b32_e32 v159, v123, v122, vcc
	v_sub_u32_e32 v125, 63, v124
	v_or_b32_e32 v126, 5, v146
	ds_read2st64_b32 v[118:119], v118 offset0:100 offset1:228
	v_lshl_add_u32 v120, v120, 2, 0
	v_lshl_add_u32 v122, v159, 6, v147
	v_cndmask_b32_e32 v160, v125, v124, vcc
	v_sub_u32_e32 v127, 63, v126
	v_or_b32_e32 v128, 6, v146
	ds_read2st64_b32 v[120:121], v120 offset0:100 offset1:228
	v_lshl_add_u32 v122, v122, 2, 0
	v_lshl_add_u32 v124, v160, 6, v147
	v_cndmask_b32_e32 v161, v127, v126, vcc
	v_sub_u32_e32 v129, 63, v128
	v_or_b32_e32 v130, 7, v146
	ds_read2st64_b32 v[122:123], v122 offset0:100 offset1:228
	v_lshl_add_u32 v124, v124, 2, 0
	v_lshl_add_u32 v126, v161, 6, v147
	v_cndmask_b32_e32 v162, v129, v128, vcc
	v_sub_u32_e32 v131, 63, v130
	v_or_b32_e32 v132, 8, v146
	ds_read2st64_b32 v[124:125], v124 offset0:100 offset1:228
	v_lshl_add_u32 v126, v126, 2, 0
	v_lshl_add_u32 v128, v162, 6, v147
	v_cndmask_b32_e32 v163, v131, v130, vcc
	v_sub_u32_e32 v133, 63, v132
	v_or_b32_e32 v134, 9, v146
	ds_read2st64_b32 v[126:127], v126 offset0:100 offset1:228
	v_lshl_add_u32 v128, v128, 2, 0
	v_lshl_add_u32 v130, v163, 6, v147
	v_cndmask_b32_e32 v164, v133, v132, vcc
	v_sub_u32_e32 v135, 63, v134
	v_or_b32_e32 v136, 10, v146
	s_waitcnt lgkmcnt(5)
	v_fma_f32 v173, 0, v116, v117
	ds_read2st64_b32 v[128:129], v128 offset0:100 offset1:228
	v_lshl_add_u32 v130, v130, 2, 0
	v_lshl_add_u32 v132, v164, 6, v147
	v_cndmask_b32_e32 v165, v135, v134, vcc
	v_sub_u32_e32 v137, 63, v136
	v_or_b32_e32 v138, 11, v146
	s_waitcnt lgkmcnt(5)
	v_fma_f32 v173, v173, v118, v119
	ds_read2st64_b32 v[130:131], v130 offset0:100 offset1:228
	v_lshl_add_u32 v132, v132, 2, 0
	v_lshl_add_u32 v134, v165, 6, v147
	v_cndmask_b32_e32 v166, v137, v136, vcc
	v_sub_u32_e32 v139, 63, v138
	v_or_b32_e32 v140, 12, v146
	v_mul_f32_e32 v174, v116, v118
	s_waitcnt lgkmcnt(5)
	v_fma_f32 v173, v173, v120, v121
	ds_read2st64_b32 v[132:133], v132 offset0:100 offset1:228
	v_lshl_add_u32 v134, v134, 2, 0
	v_lshl_add_u32 v136, v166, 6, v147
	v_cndmask_b32_e32 v167, v139, v138, vcc
	v_sub_u32_e32 v141, 63, v140
	v_or_b32_e32 v142, 13, v146
	v_mul_f32_e32 v174, v174, v120
	s_waitcnt lgkmcnt(5)
	v_fma_f32 v173, v173, v122, v123
	ds_read2st64_b32 v[134:135], v134 offset0:100 offset1:228
	v_lshl_add_u32 v136, v136, 2, 0
	v_lshl_add_u32 v138, v167, 6, v147
	v_cndmask_b32_e32 v168, v141, v140, vcc
	v_sub_u32_e32 v143, 63, v142
	v_or_b32_e32 v144, 14, v146
	v_mul_f32_e32 v174, v174, v122
	s_waitcnt lgkmcnt(5)
	v_fma_f32 v173, v173, v124, v125
	ds_read2st64_b32 v[136:137], v136 offset0:100 offset1:228
	v_lshl_add_u32 v138, v138, 2, 0
	v_lshl_add_u32 v140, v168, 6, v147
	v_cndmask_b32_e32 v169, v143, v142, vcc
	v_sub_u32_e32 v145, 63, v144
	v_or_b32_e32 v146, 15, v146
	v_mul_f32_e32 v174, v174, v124
	s_waitcnt lgkmcnt(5)
	v_fma_f32 v173, v173, v126, v127
	ds_read2st64_b32 v[138:139], v138 offset0:100 offset1:228
	v_lshl_add_u32 v140, v140, 2, 0
	v_lshl_add_u32 v142, v169, 6, v147
	v_cndmask_b32_e32 v170, v145, v144, vcc
	v_sub_u32_e32 v171, 63, v146
	v_mul_f32_e32 v174, v174, v126
	s_waitcnt lgkmcnt(5)
	v_fma_f32 v173, v173, v128, v129
	ds_read2st64_b32 v[140:141], v140 offset0:100 offset1:228
	v_lshl_add_u32 v142, v142, 2, 0
	v_lshl_add_u32 v144, v170, 6, v147
	v_cndmask_b32_e32 v171, v171, v146, vcc
	v_mul_f32_e32 v174, v174, v128
	s_waitcnt lgkmcnt(5)
	v_fma_f32 v173, v173, v130, v131
	ds_read2st64_b32 v[142:143], v142 offset0:100 offset1:228
	v_lshl_add_u32 v144, v144, 2, 0
	v_lshl_add_u32 v146, v171, 6, v147
	v_mul_f32_e32 v174, v174, v130
	s_waitcnt lgkmcnt(5)
	v_fma_f32 v173, v173, v132, v133
	ds_read2st64_b32 v[144:145], v144 offset0:100 offset1:228
	v_lshl_add_u32 v146, v146, 2, 0
	v_mul_f32_e32 v174, v174, v132
	s_waitcnt lgkmcnt(5)
	v_fma_f32 v173, v173, v134, v135
	ds_read2st64_b32 v[146:147], v146 offset0:100 offset1:228
	v_mul_f32_e32 v174, v174, v134
	s_waitcnt lgkmcnt(5)
	v_fma_f32 v173, v173, v136, v137
	v_mul_f32_e32 v174, v174, v136
	s_waitcnt lgkmcnt(4)
	v_fma_f32 v173, v173, v138, v139
	v_mul_f32_e32 v174, v174, v138
	s_waitcnt lgkmcnt(3)
	v_fma_f32 v173, v173, v140, v141
	v_mul_f32_e32 v174, v174, v140
	s_waitcnt lgkmcnt(2)
	v_fma_f32 v173, v173, v142, v143
	v_mul_f32_e32 v174, v174, v142
	s_waitcnt lgkmcnt(1)
	v_fma_f32 v173, v173, v144, v145
	v_lshl_add_u32 v152, v152, 2, 0
	v_mul_f32_e32 v174, v174, v144
	s_waitcnt lgkmcnt(0)
	v_fma_f32 v173, v173, v146, v147
	v_add_u32_e32 v175, 0x16400, v152
	v_add_u32_e32 v152, 0x16c00, v152
	v_mul_f32_e32 v174, v174, v146
	ds_write_b32 v152, v173
	v_cmp_lt_i32_e32 vcc, 0, v156
	v_lshl_add_u32 v172, v172, 2, 0
	v_mov_b32_e32 v152, v149
	ds_write_b32 v175, v174
	s_waitcnt lgkmcnt(0)
	s_barrier
	s_and_saveexec_b64 s[8:9], vcc
	s_cbranch_execnz .LBB0_772
	s_or_b64 exec, exec, s[8:9]
	v_cmp_lt_i32_e32 vcc, 1, v156
	s_and_saveexec_b64 s[8:9], vcc
	s_cbranch_execnz .LBB0_773

.LBB0_703:
	s_and_b64 vcc, exec, s[6:7]
	s_cbranch_vccnz .LBB0_705
	v_mov_b32_e32 v1, v204
	s_and_b32 s2, s50, 7
	s_lshl_b32 s62, s2, 8
	v_lshlrev_b32_e32 v2, 5, v1
	v_and_b32_e32 v2, 0xe0, v2
	v_or_b32_e32 v2, s62, v2
	v_mov_b32_e32 v3, v0
	v_lshl_add_u64 v[12:13], s[24:25], 0, v[2:3]
	v_add_co_u32_e32 v24, vcc, s48, v12
	global_load_dwordx4 v[4:7], v2, s[24:25] offset:2064
	global_load_dwordx4 v[8:11], v2, s[24:25] offset:2048
	v_addc_co_u32_e32 v25, vcc, 0, v13, vcc
	global_load_dwordx4 v[12:15], v2, s[54:55]
	global_load_dwordx4 v[16:19], v2, s[56:57]
	global_load_dwordx4 v[20:23], v[24:25], off offset:16
	global_load_dwordx4 v[32:35], v[24:25], off offset:2064
	s_nop 0
	global_load_dwordx4 v[24:27], v2, s[24:25] offset:16
	global_load_dwordx4 v[44:47], v2, s[26:27] offset:16
	global_load_dwordx4 v[36:39], v2, s[24:25]
	global_load_dwordx4 v[48:51], v2, s[26:27]
	v_ashrrev_i32_e32 v56, 7, v1
	v_lshrrev_b32_e32 v2, 1, v1
	v_and_b32_e32 v82, 32, v2
	v_lshl_or_b32 v2, v56, 3, s2
	v_lshlrev_b32_e32 v56, 11, v56
	v_ashrrev_i32_e32 v3, 31, v2
	v_and_b32_e32 v74, 0x800, v56
	v_mov_b32_e32 v75, v0
	v_lshlrev_b64 v[2:3], 13, v[2:3]
	v_lshl_add_u64 v[56:57], s[52:53], 0, v[74:75]
	v_lshl_add_u64 v[2:3], s[58:59], 0, v[2:3]
	v_and_b32_e32 v72, 48, v1
	v_mov_b32_e32 v73, v0
	v_lshl_add_u64 v[76:77], v[56:57], 0, s[62:63]
	v_and_or_b32 v56, v1, 15, v82
	v_lshl_add_u64 v[2:3], v[2:3], 0, v[72:73]
	v_lshlrev_b32_e32 v78, 7, v56
	v_mov_b32_e32 v79, v0
	v_lshl_add_u64 v[64:65], v[2:3], 0, v[78:79]
	v_mov_b32_e32 v73, s37
	v_mov_b32_e32 v79, s15
	v_cmp_gt_u32_e32 vcc, s49, v1
	v_mov_b32_e32 v1, s36
	v_lshl_or_b32 v72, v82, 2, v72
	v_cndmask_b32_e32 v81, v73, v79, vcc
	v_mov_b32_e32 v73, s14
	v_cndmask_b32_e32 v80, v1, v73, vcc
	v_lshl_add_u64 v[74:75], v[80:81], 0, v[74:75]
	v_lshl_add_u64 v[74:75], v[74:75], 0, s[62:63]
	v_mov_b32_e32 v73, v0
	v_lshl_add_u64 v[84:85], v[74:75], 0, v[72:73]
	v_lshl_add_u64 v[92:93], v[76:77], 0, v[72:73]
	v_or_b32_e32 v72, 0x800, v78
	v_lshl_add_u64 v[2:3], v[2:3], 0, v[72:73]
	global_load_dwordx4 v[56:59], v[64:65], off
	s_nop 0
	global_load_dwordx4 v[64:67], v[64:65], off offset:64
	s_nop 0
	global_load_dwordx4 v[72:75], v[2:3], off
	global_load_dwordx4 v[76:79], v[2:3], off offset:64
	global_load_dwordx4 v[80:83], v[84:85], off
	s_nop 0
	global_load_dwordx4 v[84:87], v[84:85], off offset:64
	s_nop 0
	global_load_dwordx4 v[88:91], v[92:93], off
	s_nop 0
	global_load_dwordx4 v[92:95], v[92:93], off offset:64
	s_waitcnt vmcnt(0)
	v_cmp_gt_u32_e64 s[98:99], s49, v204
	v_mul_f32_e32 v240, 0xc1000000, v88
	v_mul_f32_e32 v241, 0xc1000000, v89
	v_mul_f32_e32 v242, 0xc1000000, v90
	v_mul_f32_e32 v243, 0xc1000000, v91
	v_mul_f32_e32 v244, 0xc1000000, v92
	v_mul_f32_e32 v245, 0xc1000000, v93
	v_mul_f32_e32 v246, 0xc1000000, v94
	v_mul_f32_e32 v247, 0xc1000000, v95
	v_cndmask_b32_e64 v240, 1.0, v240, s[98:99]
	v_cndmask_b32_e64 v241, 1.0, v241, s[98:99]
	v_cndmask_b32_e64 v242, 1.0, v242, s[98:99]
	v_cndmask_b32_e64 v243, 1.0, v243, s[98:99]
	v_cndmask_b32_e64 v244, 1.0, v244, s[98:99]
	v_cndmask_b32_e64 v245, 1.0, v245, s[98:99]
	v_cndmask_b32_e64 v246, 1.0, v246, s[98:99]
	v_cndmask_b32_e64 v247, 1.0, v247, s[98:99]
.LBB0_705:
	v_lshlrev_b32_e32 v2, 16, v68
	v_and_b32_e32 v3, 0xffff0000, v68
	s_nop 0
	v_pk_fma_f32 v[2:3], v[36:37], v[2:3], v[48:49]
	v_lshlrev_b32_e32 v116, 16, v96
	v_and_b32_e32 v117, 0xffff0000, v96
	v_pk_fma_f32 v[2:3], v[8:9], v[116:117], v[2:3]
	v_lshlrev_b32_e32 v116, 16, v104
	v_and_b32_e32 v117, 0xffff0000, v104
	v_pk_fma_f32 v[2:3], v[12:13], v[116:117], v[2:3]
	v_lshlrev_b32_e32 v116, 16, v108
	v_and_b32_e32 v117, 0xffff0000, v108
	v_pk_fma_f32 v[116:117], v[16:17], v[116:117], v[2:3]
	v_lshlrev_b32_e32 v2, 16, v70
	v_and_b32_e32 v3, 0xffff0000, v70
	v_pk_fma_f32 v[2:3], v[24:25], v[2:3], v[44:45]
	v_lshlrev_b32_e32 v118, 16, v98
	v_and_b32_e32 v119, 0xffff0000, v98
	v_pk_fma_f32 v[2:3], v[4:5], v[118:119], v[2:3]
	v_lshlrev_b32_e32 v118, 16, v106
	v_and_b32_e32 v119, 0xffff0000, v106
	v_pk_fma_f32 v[2:3], v[20:21], v[118:119], v[2:3]
	v_lshlrev_b32_e32 v118, 16, v110
	v_and_b32_e32 v119, 0xffff0000, v110
	v_pk_fma_f32 v[120:121], v[32:33], v[118:119], v[2:3]
	v_lshlrev_b32_e32 v2, 16, v69
	v_and_b32_e32 v3, 0xffff0000, v69
	v_pk_fma_f32 v[2:3], v[38:39], v[2:3], v[50:51]
	v_lshlrev_b32_e32 v118, 16, v97
	v_and_b32_e32 v119, 0xffff0000, v97
	v_pk_fma_f32 v[2:3], v[10:11], v[118:119], v[2:3]
	v_lshlrev_b32_e32 v118, 16, v105
	v_and_b32_e32 v119, 0xffff0000, v105
	v_pk_fma_f32 v[2:3], v[14:15], v[118:119], v[2:3]
	v_lshlrev_b32_e32 v118, 16, v109
	v_and_b32_e32 v119, 0xffff0000, v109
	v_pk_fma_f32 v[118:119], v[18:19], v[118:119], v[2:3]
	v_lshlrev_b32_e32 v2, 16, v71
	v_and_b32_e32 v3, 0xffff0000, v71
	v_pk_fma_f32 v[2:3], v[26:27], v[2:3], v[46:47]
	v_lshlrev_b32_e32 v122, 16, v99
	v_and_b32_e32 v123, 0xffff0000, v99
	v_pk_fma_f32 v[2:3], v[6:7], v[122:123], v[2:3]
	v_lshlrev_b32_e32 v122, 16, v107
	v_and_b32_e32 v123, 0xffff0000, v107
	v_mov_b32_e32 v152, v204
	v_pk_fma_f32 v[2:3], v[22:23], v[122:123], v[2:3]
	v_lshlrev_b32_e32 v122, 16, v111
	v_and_b32_e32 v123, 0xffff0000, v111
	v_pk_fma_f32 v[122:123], v[34:35], v[122:123], v[2:3]
	v_lshlrev_b32_e32 v1, 3, v152
	v_ashrrev_i32_e32 v2, 3, v152
	v_and_b32_e32 v1, 56, v1
	v_lshl_add_u32 v151, v2, 8, 0
	v_lshl_add_u32 v3, v1, 2, v151
	ds_write_b128 v3, v[116:119]
	ds_write_b128 v3, v[120:123] offset:16
	v_cvt_pk_bf16_f32 v116, v116, v117
	v_cvt_pk_bf16_f32 v117, v118, v119
	v_cvt_pk_bf16_f32 v118, v120, v121
	v_mul_lo_u32 v120, v2, s1
	v_lshlrev_b32_e32 v121, 1, v1
	v_and_b32_e32 v162, 15, v152
	v_cvt_pk_bf16_f32 v119, v122, v123
	v_add3_u32 v120, v151, v120, v121
	v_and_b32_e32 v153, 48, v152
	ds_write_b128 v120, v[116:119] offset:16384
	v_mul_u32_u24_e32 v116, 0x90, v162
	v_add3_u32 v163, 0, v153, v116
	s_waitcnt lgkmcnt(0)
	s_barrier
	ds_read_b128 v[128:131], v163 offset:20992
	s_waitcnt lgkmcnt(0)
	v_mfma_f32_16x16x32_bf16 v[136:139], v[56:59], v[128:131], 0
	ds_read_b128 v[116:119], v163 offset:16384
	ds_read_b128 v[124:127], v163 offset:18688
	v_cmp_gt_u32_e32 vcc, s49, v152
	s_nop 0
	v_mfma_f32_16x16x32_bf16 v[140:143], v[72:75], v[128:131], 0
	ds_read_b128 v[128:131], v163 offset:23296
	s_waitcnt lgkmcnt(0)
	v_mfma_f32_16x16x32_bf16 v[144:147], v[56:59], v[128:131], 0
	v_mfma_f32_16x16x32_bf16 v[154:157], v[72:75], v[128:131], 0
	ds_read_b128 v[128:131], v163 offset:16448
	v_mfma_f32_16x16x32_bf16 v[120:123], v[56:59], v[116:119], 0
	v_mfma_f32_16x16x32_bf16 v[116:119], v[72:75], v[116:119], 0
	s_waitcnt lgkmcnt(0)
	v_mfma_f32_16x16x32_bf16 v[158:161], v[64:67], v[128:131], v[120:123]
	s_nop 0
	v_mfma_f32_16x16x32_bf16 v[128:131], v[76:79], v[128:131], v[116:119]
	s_nop 3
	ds_read_b128 v[116:119], v163 offset:18752
	v_mfma_f32_16x16x32_bf16 v[132:135], v[56:59], v[124:127], 0
	s_nop 0
	s_nop 0
	v_add_f32_e32 v128, v84, v128
	v_mul_f32_e32 v128, 0xbfb8aa3b, v128
	v_exp_f32_e32 v128, v128
	v_mfma_f32_16x16x32_bf16 v[124:127], v[72:75], v[124:127], 0
	v_add_f32_e32 v129, v85, v129
	v_mul_f32_e32 v129, 0xbfb8aa3b, v129
	v_exp_f32_e32 v129, v129
	s_waitcnt lgkmcnt(0)
	v_mfma_f32_16x16x32_bf16 v[132:135], v[64:67], v[116:119], v[132:135]
	v_add_f32_e32 v130, v86, v130
	v_mul_f32_e32 v130, 0xbfb8aa3b, v130
	v_add_f32_e32 v128, 1.0, v128
	v_mfma_f32_16x16x32_bf16 v[124:127], v[76:79], v[116:119], v[124:127]
	ds_read_b128 v[116:119], v163 offset:21056
	s_nop 2
	v_add_f32_e32 v132, v80, v132
	v_mul_f32_e32 v132, 0xbfb8aa3b, v132
	s_waitcnt lgkmcnt(0)
	v_mfma_f32_16x16x32_bf16 v[136:139], v[64:67], v[116:119], v[136:139]
	v_exp_f32_e32 v132, v132
	v_add_f32_e32 v133, v81, v133
	v_mul_f32_e32 v133, 0xbfb8aa3b, v133
	v_mfma_f32_16x16x32_bf16 v[120:123], v[76:79], v[116:119], v[140:143]
	ds_read_b128 v[116:119], v163 offset:23360
	v_exp_f32_e32 v133, v133
	v_add_f32_e32 v134, v82, v134
	s_waitcnt lgkmcnt(0)
	v_mfma_f32_16x16x32_bf16 v[140:143], v[64:67], v[116:119], v[144:147]
	v_mul_f32_e32 v134, 0xbfb8aa3b, v134
	s_nop 1
	v_mov_b32_e32 v144, s51
	v_mov_b32_e32 v145, s81
	v_cndmask_b32_e32 v144, v144, v145, vcc
	v_lshlrev_b32_e32 v145, 7, v152
	v_and_b32_e32 v145, 0x4000, v145
	v_lshlrev_b32_e32 v146, 8, v162
	v_add3_u32 v144, v144, v145, v146
	v_add_f32_e32 v146, v80, v158
	v_mul_f32_e32 v146, 0xbfb8aa3b, v146
	v_add_f32_e32 v147, v81, v159
	v_exp_f32_e32 v146, v146
	v_mul_f32_e32 v147, 0xbfb8aa3b, v147
	v_exp_f32_e32 v147, v147
	v_lshlrev_b32_e32 v145, 1, v152
	v_and_b32_e32 v145, 0x80, v145
	v_add_f32_e32 v146, 1.0, v146
	v_rcp_f32_e32 v146, v146
	v_add3_u32 v153, v144, v145, v153
	v_add_f32_e32 v144, 1.0, v147
	v_add_f32_e32 v147, v82, v160
	v_mul_f32_e32 v147, 0xbfb8aa3b, v147
	v_mfma_f32_16x16x32_bf16 v[116:119], v[76:79], v[116:119], v[154:157]
	v_rcp_f32_e32 v145, v144
	v_exp_f32_e32 v147, v147

	s_nop 0
	v_add_f32_e32 v154, v83, v161
	v_mul_f32_e32 v154, 0xbfb8aa3b, v154
	v_exp_f32_e32 v154, v154
	s_nop 0

	v_mul_f32_e32 v144, v240, v146

	v_add_f32_e32 v147, 1.0, v147

	v_rcp_f32_e32 v147, v147
	v_mul_f32_e32 v145, v241, v145
	v_add_f32_e32 v146, 1.0, v154
	v_rcp_f32_e32 v154, v146

	v_add_f32_e32 v132, 1.0, v132
	v_exp_f32_e32 v134, v134
	v_add_f32_e32 v135, v83, v135

	v_rcp_f32_e32 v132, v132
	v_mul_f32_e32 v135, 0xbfb8aa3b, v135
	v_mul_f32_e32 v146, v242, v147

	v_add_f32_e32 v133, 1.0, v133
	v_exp_f32_e32 v135, v135

	v_rcp_f32_e32 v133, v133
	v_mul_f32_e32 v147, v243, v154
	v_add_f32_e32 v134, 1.0, v134
	v_add_f32_e32 v136, v80, v136
	ds_write_b128 v153, v[144:147]

	v_rcp_f32_e32 v134, v134
	v_mul_f32_e32 v136, 0xbfb8aa3b, v136

	v_add_f32_e32 v135, 1.0, v135
	v_exp_f32_e32 v136, v136
	v_mul_f32_e32 v132, v240, v132

	v_rcp_f32_e32 v135, v135

	v_add_f32_e32 v137, v81, v137
	v_mul_f32_e32 v133, v241, v133

	v_mul_f32_e32 v137, 0xbfb8aa3b, v137

	v_exp_f32_e32 v137, v137
	v_add_f32_e32 v136, 1.0, v136
	v_mul_f32_e32 v134, v242, v134

	v_rcp_f32_e32 v136, v136

	v_mul_f32_e32 v135, v243, v135
	ds_write_b128 v153, v[132:135] offset:4096
	v_add_f32_e32 v132, 1.0, v137
	v_rcp_f32_e32 v133, v132

	v_add_f32_e32 v135, v82, v138

	v_mul_f32_e32 v135, 0xbfb8aa3b, v135
	v_mul_f32_e32 v132, v240, v136
	v_exp_f32_e32 v135, v135
	v_add_f32_e32 v136, v83, v139
	v_mul_f32_e32 v136, 0xbfb8aa3b, v136
	v_exp_f32_e32 v136, v136

	v_add_f32_e32 v135, 1.0, v135

	v_rcp_f32_e32 v135, v135
	v_mul_f32_e32 v133, v241, v133
	v_add_f32_e32 v134, 1.0, v136
	v_rcp_f32_e32 v136, v134


	v_mul_f32_e32 v134, v242, v135


	v_mul_f32_e32 v135, v243, v136
	v_add_f32_e32 v136, v80, v140
	v_mul_f32_e32 v136, 0xbfb8aa3b, v136
	v_exp_f32_e32 v136, v136
	v_add_f32_e32 v137, v81, v141
	v_mul_f32_e32 v137, 0xbfb8aa3b, v137
	v_exp_f32_e32 v137, v137
	v_add_f32_e32 v136, 1.0, v136
	v_rcp_f32_e32 v136, v136
	ds_write_b128 v153, v[132:135] offset:8192
	v_add_f32_e32 v132, 1.0, v137
	v_rcp_f32_e32 v133, v132

	v_add_f32_e32 v135, v82, v142

	v_mul_f32_e32 v135, 0xbfb8aa3b, v135
	v_mul_f32_e32 v132, v240, v136
	v_exp_f32_e32 v135, v135
	v_add_f32_e32 v136, v83, v143
	v_mul_f32_e32 v136, 0xbfb8aa3b, v136
	v_exp_f32_e32 v136, v136

	v_add_f32_e32 v135, 1.0, v135

	v_rcp_f32_e32 v135, v135
	v_mul_f32_e32 v133, v241, v133
	v_add_f32_e32 v134, 1.0, v136
	v_rcp_f32_e32 v136, v134

	v_exp_f32_e32 v130, v130
	v_add_f32_e32 v131, v87, v131

	v_rcp_f32_e32 v128, v128
	v_mul_f32_e32 v131, 0xbfb8aa3b, v131
	v_mul_f32_e32 v134, v242, v135

	v_add_f32_e32 v129, 1.0, v129
	v_exp_f32_e32 v131, v131

	v_rcp_f32_e32 v129, v129
	v_add_f32_e32 v124, v84, v124
	v_mul_f32_e32 v135, v243, v136
	v_add_f32_e32 v130, 1.0, v130
	v_mul_f32_e32 v124, 0xbfb8aa3b, v124
	ds_write_b128 v153, v[132:135] offset:12288

	v_rcp_f32_e32 v130, v130
	v_exp_f32_e32 v124, v124
	v_add_f32_e32 v125, v85, v125
	s_nop 0

	v_add_f32_e32 v131, 1.0, v131
	v_mul_f32_e32 v125, 0xbfb8aa3b, v125
	v_mul_f32_e32 v128, v244, v128

	v_rcp_f32_e32 v131, v131
	v_exp_f32_e32 v125, v125
	v_add_f32_e32 v126, v86, v126

	v_mul_f32_e32 v126, 0xbfb8aa3b, v126
	v_mul_f32_e32 v129, v245, v129

	v_add_f32_e32 v124, 1.0, v124
	v_exp_f32_e32 v126, v126
	v_add_f32_e32 v127, v87, v127

	v_rcp_f32_e32 v124, v124
	v_mul_f32_e32 v127, 0xbfb8aa3b, v127
	v_mul_f32_e32 v130, v246, v130

	v_add_f32_e32 v125, 1.0, v125
	v_exp_f32_e32 v127, v127

	v_rcp_f32_e32 v125, v125
	v_add_f32_e32 v120, v84, v120
	v_mul_f32_e32 v131, v247, v131
	v_add_f32_e32 v126, 1.0, v126
	v_mul_f32_e32 v120, 0xbfb8aa3b, v120
	ds_write_b128 v153, v[128:131] offset:64

	v_rcp_f32_e32 v126, v126
	v_exp_f32_e32 v120, v120
	v_add_f32_e32 v121, v85, v121

	v_add_f32_e32 v127, 1.0, v127
	v_mul_f32_e32 v121, 0xbfb8aa3b, v121
	v_mul_f32_e32 v124, v244, v124

	v_rcp_f32_e32 v127, v127
	v_exp_f32_e32 v121, v121
	v_add_f32_e32 v122, v86, v122

	v_mul_f32_e32 v122, 0xbfb8aa3b, v122
	v_mul_f32_e32 v125, v245, v125

	v_add_f32_e32 v120, 1.0, v120
	v_exp_f32_e32 v122, v122
	v_add_f32_e32 v123, v87, v123

	v_rcp_f32_e32 v120, v120
	v_mul_f32_e32 v123, 0xbfb8aa3b, v123
	v_mul_f32_e32 v126, v246, v126

	v_add_f32_e32 v121, 1.0, v121
	v_exp_f32_e32 v123, v123

	v_rcp_f32_e32 v121, v121
	v_add_f32_e32 v116, v84, v116
	v_mul_f32_e32 v127, v247, v127
	v_add_f32_e32 v122, 1.0, v122
	v_mul_f32_e32 v116, 0xbfb8aa3b, v116
	ds_write_b128 v153, v[124:127] offset:4160

	v_rcp_f32_e32 v122, v122
	v_exp_f32_e32 v116, v116
	v_add_f32_e32 v117, v85, v117

	v_add_f32_e32 v123, 1.0, v123
	v_mul_f32_e32 v117, 0xbfb8aa3b, v117
	v_mul_f32_e32 v120, v244, v120

	v_rcp_f32_e32 v123, v123
	v_exp_f32_e32 v117, v117
	v_add_f32_e32 v118, v86, v118

	v_mul_f32_e32 v118, 0xbfb8aa3b, v118
	v_mul_f32_e32 v121, v245, v121

	v_add_f32_e32 v116, 1.0, v116
	v_exp_f32_e32 v118, v118
	v_add_f32_e32 v119, v87, v119

	v_rcp_f32_e32 v116, v116
	v_mul_f32_e32 v119, 0xbfb8aa3b, v119
	v_mul_f32_e32 v122, v246, v122

	v_add_f32_e32 v117, 1.0, v117
	v_exp_f32_e32 v119, v119

	v_rcp_f32_e32 v117, v117
	v_mul_f32_e32 v123, v247, v123
	v_add_f32_e32 v118, 1.0, v118
	ds_write_b128 v153, v[120:123] offset:8256

	v_rcp_f32_e32 v118, v118

	v_add_f32_e32 v119, 1.0, v119
	v_mul_f32_e32 v116, v244, v116

	v_rcp_f32_e32 v119, v119

	v_mul_f32_e32 v117, v245, v117


	v_mul_f32_e32 v118, v246, v118


	v_mul_f32_e32 v119, v247, v119
	v_lshlrev_b32_e32 v133, 2, v152
	ds_write_b128 v153, v[116:119] offset:12352
	v_and_b32_e32 v116, 60, v133
	v_lshlrev_b32_e32 v132, 2, v116
	v_lshlrev_b32_e32 v116, 4, v152
	v_and_b32_e32 v117, 0xffffc000, v116
	v_add_u32_e32 v117, 0, v117
	v_and_b32_e32 v116, 0x3f00, v116
	v_add3_u32 v135, v117, v116, v132
	s_waitcnt lgkmcnt(0)
	s_barrier
	ds_read_b128 v[128:131], v135 offset:25600
	ds_read_b128 v[120:123], v135 offset:58368
	v_add_u32_e32 v134, 0, v132
	v_add_u32_e32 v136, v134, v116
	ds_read_b128 v[124:127], v136
	s_waitcnt lgkmcnt(2)
	v_mul_f32_e32 v116, 0x3fb8aa3b, v128
	v_exp_f32_e32 v116, v116
	v_add_f32_e32 v117, v128, v128
	v_cmp_nlt_f32_e32 vcc, s79, v117
	s_and_saveexec_b64 s[6:7], vcc
	s_xor_b64 s[6:7], exec, s[6:7]
	v_fma_f32 v128, -v116, v116, 1.0
	s_andn2_saveexec_b64 s[6:7], s[6:7]
	v_fmamk_f32 v118, v117, 0x3c088889, v148
	v_fmaak_f32 v118, v117, v118, 0x3e2aaaab
	v_fma_f32 v118, v117, v118, 0.5
	v_fma_f32 v118, v117, v118, 1.0
	v_mul_f32_e64 v128, v118, -v117
	s_or_b64 exec, exec, s[6:7]
	v_mul_f32_e32 v117, 0x3fb8aa3b, v129
	v_exp_f32_e32 v117, v117
	v_add_f32_e32 v118, v129, v129
	v_cmp_nlt_f32_e32 vcc, s79, v118
	s_and_saveexec_b64 s[6:7], vcc
	s_xor_b64 s[6:7], exec, s[6:7]
	v_fma_f32 v129, -v117, v117, 1.0
	s_andn2_saveexec_b64 s[6:7], s[6:7]
	v_fmamk_f32 v119, v118, 0x3c088889, v148
	v_fmaak_f32 v119, v118, v119, 0x3e2aaaab
	v_fma_f32 v119, v118, v119, 0.5
	v_fma_f32 v119, v118, v119, 1.0
	v_mul_f32_e64 v129, v119, -v118
	s_or_b64 exec, exec, s[6:7]
	v_mul_f32_e32 v118, 0x3fb8aa3b, v130
	v_exp_f32_e32 v118, v118
	v_add_f32_e32 v119, v130, v130
	v_cmp_nlt_f32_e32 vcc, s79, v119
	s_and_saveexec_b64 s[6:7], vcc
	s_xor_b64 s[6:7], exec, s[6:7]
	v_fma_f32 v130, -v118, v118, 1.0
	s_andn2_saveexec_b64 s[6:7], s[6:7]
	v_fmamk_f32 v130, v119, 0x3c088889, v148
	v_fmaak_f32 v130, v119, v130, 0x3e2aaaab
	v_fma_f32 v130, v119, v130, 0.5
	v_fma_f32 v130, v119, v130, 1.0
	v_mul_f32_e64 v130, v130, -v119
	s_or_b64 exec, exec, s[6:7]
	v_mul_f32_e32 v119, 0x3fb8aa3b, v131
	v_exp_f32_e32 v119, v119
	v_add_f32_e32 v137, v131, v131
	v_cmp_nlt_f32_e32 vcc, s79, v137
	s_and_saveexec_b64 s[6:7], vcc
	s_xor_b64 s[6:7], exec, s[6:7]
	v_fma_f32 v131, -v119, v119, 1.0
	s_andn2_saveexec_b64 s[6:7], s[6:7]
	v_fmamk_f32 v131, v137, 0x3c088889, v148
	v_fmaak_f32 v131, v137, v131, 0x3e2aaaab
	v_fma_f32 v131, v137, v131, 0.5
	v_fma_f32 v131, v137, v131, 1.0
	v_mul_f32_e64 v131, v131, -v137
	s_or_b64 exec, exec, s[6:7]
	v_max_f32_e32 v128, v128, v128
	v_max_f32_e32 v128, 0, v128
	v_sqrt_f32_e32 v128, v128
	v_max_f32_e32 v129, v129, v129
	v_max_f32_e32 v129, 0, v129
	v_sqrt_f32_e32 v129, v129
	s_waitcnt lgkmcnt(1)
	v_mul_f32_e32 v120, v120, v128
	s_waitcnt lgkmcnt(0)
	v_mul_f32_e32 v120, v124, v120
	v_max_f32_e32 v124, v130, v130
	v_max_f32_e32 v128, v131, v131
	v_max_f32_e32 v124, 0, v124
	v_max_f32_e32 v128, 0, v128
	v_sqrt_f32_e32 v124, v124
	v_sqrt_f32_e32 v128, v128
	v_mul_f32_e32 v121, v121, v129
	v_mul_f32_e32 v121, v125, v121
	v_mul_f32_e32 v122, v122, v124
	v_mul_f32_e32 v123, v123, v128
	v_mul_f32_e32 v122, v126, v122
	v_mul_f32_e32 v123, v127, v123
	ds_write_b128 v135, v[116:119] offset:25600
	ds_write_b128 v135, v[120:123] offset:58368
	v_add_u32_e32 v116, 0x800, v133
	v_and_b32_e32 v117, 0x3ffff000, v116
	v_and_b32_e32 v116, 0xfc0, v116
	v_lshl_add_u32 v117, v117, 2, 0
	v_lshlrev_b32_e32 v116, 2, v116
	v_add3_u32 v137, v117, v116, v132
	ds_read_b128 v[128:131], v137 offset:25600
	ds_read_b128 v[120:123], v137 offset:58368
	v_add_u32_e32 v116, v134, v116
	ds_read_b128 v[124:127], v116
	s_waitcnt lgkmcnt(2)
	v_mul_f32_e32 v116, 0x3fb8aa3b, v128
	v_exp_f32_e32 v116, v116
	v_add_f32_e32 v117, v128, v128
	v_cmp_nlt_f32_e32 vcc, s79, v117
	s_and_saveexec_b64 s[6:7], vcc
	s_xor_b64 s[6:7], exec, s[6:7]
	v_fma_f32 v128, -v116, v116, 1.0
	s_andn2_saveexec_b64 s[6:7], s[6:7]
	v_fmamk_f32 v118, v117, 0x3c088889, v148
	v_fmaak_f32 v118, v117, v118, 0x3e2aaaab
	v_fma_f32 v118, v117, v118, 0.5
	v_fma_f32 v118, v117, v118, 1.0
	v_mul_f32_e64 v128, v118, -v117
	s_or_b64 exec, exec, s[6:7]
	v_mul_f32_e32 v117, 0x3fb8aa3b, v129
	v_exp_f32_e32 v117, v117
	v_add_f32_e32 v118, v129, v129
	v_cmp_nlt_f32_e32 vcc, s79, v118
	s_and_saveexec_b64 s[6:7], vcc
	s_xor_b64 s[6:7], exec, s[6:7]
	v_fma_f32 v129, -v117, v117, 1.0
	s_andn2_saveexec_b64 s[6:7], s[6:7]
	v_fmamk_f32 v119, v118, 0x3c088889, v148
	v_fmaak_f32 v119, v118, v119, 0x3e2aaaab
	v_fma_f32 v119, v118, v119, 0.5
	v_fma_f32 v119, v118, v119, 1.0
	v_mul_f32_e64 v129, v119, -v118
	s_or_b64 exec, exec, s[6:7]
	v_mul_f32_e32 v118, 0x3fb8aa3b, v130
	v_exp_f32_e32 v118, v118
	v_add_f32_e32 v119, v130, v130
	v_cmp_nlt_f32_e32 vcc, s79, v119
	s_and_saveexec_b64 s[6:7], vcc
	s_xor_b64 s[6:7], exec, s[6:7]
	v_fma_f32 v130, -v118, v118, 1.0
	s_andn2_saveexec_b64 s[6:7], s[6:7]
	v_fmamk_f32 v130, v119, 0x3c088889, v148
	v_fmaak_f32 v130, v119, v130, 0x3e2aaaab
	v_fma_f32 v130, v119, v130, 0.5
	v_fma_f32 v130, v119, v130, 1.0
	v_mul_f32_e64 v130, v130, -v119
	s_or_b64 exec, exec, s[6:7]
	v_mul_f32_e32 v119, 0x3fb8aa3b, v131
	v_exp_f32_e32 v119, v119
	v_add_f32_e32 v138, v131, v131
	v_cmp_nlt_f32_e32 vcc, s79, v138
	s_and_saveexec_b64 s[6:7], vcc
	s_xor_b64 s[6:7], exec, s[6:7]
	v_fma_f32 v131, -v119, v119, 1.0
	s_andn2_saveexec_b64 s[6:7], s[6:7]
	v_fmamk_f32 v131, v138, 0x3c088889, v148
	v_fmaak_f32 v131, v138, v131, 0x3e2aaaab
	v_fma_f32 v131, v138, v131, 0.5
	v_fma_f32 v131, v138, v131, 1.0
	v_mul_f32_e64 v131, v131, -v138
	s_or_b64 exec, exec, s[6:7]
	v_max_f32_e32 v128, v128, v128
	v_max_f32_e32 v128, 0, v128
	v_sqrt_f32_e32 v128, v128
	v_max_f32_e32 v129, v129, v129
	v_max_f32_e32 v129, 0, v129
	v_sqrt_f32_e32 v129, v129
	s_waitcnt lgkmcnt(1)
	v_mul_f32_e32 v120, v120, v128
	s_waitcnt lgkmcnt(0)
	v_mul_f32_e32 v120, v124, v120
	v_max_f32_e32 v124, v130, v130
	v_max_f32_e32 v128, v131, v131
	v_max_f32_e32 v124, 0, v124
	v_max_f32_e32 v128, 0, v128
	v_sqrt_f32_e32 v124, v124
	v_sqrt_f32_e32 v128, v128
	v_mul_f32_e32 v121, v121, v129
	v_mul_f32_e32 v121, v125, v121
	v_mul_f32_e32 v122, v122, v124
	v_mul_f32_e32 v123, v123, v128
	v_mul_f32_e32 v122, v126, v122
	v_mul_f32_e32 v123, v127, v123
	ds_write_b128 v137, v[116:119] offset:25600
	ds_write_b128 v137, v[120:123] offset:58368
	ds_read_b128 v[128:131], v135 offset:41984
	v_add_u32_e32 v137, 0xe400, v135
	ds_read_b128 v[120:123], v137 offset:16384
	ds_read_b128 v[124:127], v136
	s_waitcnt lgkmcnt(2)
	v_mul_f32_e32 v116, 0x3fb8aa3b, v128
	v_exp_f32_e32 v116, v116
	v_add_f32_e32 v117, v128, v128
	v_cmp_nlt_f32_e32 vcc, s79, v117
	s_and_saveexec_b64 s[6:7], vcc
	s_xor_b64 s[6:7], exec, s[6:7]
	v_fma_f32 v128, -v116, v116, 1.0
	s_andn2_saveexec_b64 s[6:7], s[6:7]
	v_fmamk_f32 v118, v117, 0x3c088889, v148
	v_fmaak_f32 v118, v117, v118, 0x3e2aaaab
	v_fma_f32 v118, v117, v118, 0.5
	v_fma_f32 v118, v117, v118, 1.0
	v_mul_f32_e64 v128, v118, -v117
	s_or_b64 exec, exec, s[6:7]
	v_mul_f32_e32 v117, 0x3fb8aa3b, v129
	v_exp_f32_e32 v117, v117
	v_add_f32_e32 v118, v129, v129
	v_cmp_nlt_f32_e32 vcc, s79, v118
	s_and_saveexec_b64 s[6:7], vcc
	s_xor_b64 s[6:7], exec, s[6:7]
	v_fma_f32 v129, -v117, v117, 1.0
	s_andn2_saveexec_b64 s[6:7], s[6:7]
	v_fmamk_f32 v119, v118, 0x3c088889, v148
	v_fmaak_f32 v119, v118, v119, 0x3e2aaaab
	v_fma_f32 v119, v118, v119, 0.5
	v_fma_f32 v119, v118, v119, 1.0
	v_mul_f32_e64 v129, v119, -v118
	s_or_b64 exec, exec, s[6:7]
	v_mul_f32_e32 v118, 0x3fb8aa3b, v130
	v_exp_f32_e32 v118, v118
	v_add_f32_e32 v119, v130, v130
	v_cmp_nlt_f32_e32 vcc, s79, v119
	s_and_saveexec_b64 s[6:7], vcc
	s_xor_b64 s[6:7], exec, s[6:7]
	v_fma_f32 v130, -v118, v118, 1.0
	s_andn2_saveexec_b64 s[6:7], s[6:7]
	v_fmamk_f32 v130, v119, 0x3c088889, v148
	v_fmaak_f32 v130, v119, v130, 0x3e2aaaab
	v_fma_f32 v130, v119, v130, 0.5
	v_fma_f32 v130, v119, v130, 1.0
	v_mul_f32_e64 v130, v130, -v119
	s_or_b64 exec, exec, s[6:7]
	v_mul_f32_e32 v119, 0x3fb8aa3b, v131
	v_exp_f32_e32 v119, v119
	v_add_f32_e32 v136, v131, v131
	v_cmp_nlt_f32_e32 vcc, s79, v136
	s_and_saveexec_b64 s[6:7], vcc
	s_xor_b64 s[6:7], exec, s[6:7]
	v_fma_f32 v131, -v119, v119, 1.0
	s_andn2_saveexec_b64 s[6:7], s[6:7]
	v_fmamk_f32 v131, v136, 0x3c088889, v148
	v_fmaak_f32 v131, v136, v131, 0x3e2aaaab
	v_fma_f32 v131, v136, v131, 0.5
	v_fma_f32 v131, v136, v131, 1.0
	v_mul_f32_e64 v131, v131, -v136
	s_or_b64 exec, exec, s[6:7]
	v_max_f32_e32 v128, v128, v128
	v_max_f32_e32 v128, 0, v128
	v_sqrt_f32_e32 v128, v128
	v_max_f32_e32 v129, v129, v129
	v_max_f32_e32 v129, 0, v129
	v_sqrt_f32_e32 v129, v129
	s_waitcnt lgkmcnt(1)
	v_mul_f32_e32 v120, v120, v128
	s_waitcnt lgkmcnt(0)
	v_mul_f32_e32 v120, v124, v120
	v_max_f32_e32 v124, v130, v130
	v_max_f32_e32 v128, v131, v131
	v_max_f32_e32 v124, 0, v124
	v_max_f32_e32 v128, 0, v128
	v_sqrt_f32_e32 v124, v124
	v_sqrt_f32_e32 v128, v128
	v_mul_f32_e32 v121, v121, v129
	v_mul_f32_e32 v121, v125, v121
	v_mul_f32_e32 v122, v122, v124
	v_mul_f32_e32 v123, v123, v128
	v_mul_f32_e32 v122, v126, v122
	v_mul_f32_e32 v123, v127, v123
	ds_write_b128 v135, v[116:119] offset:41984
	ds_write_b128 v137, v[120:123] offset:16384
	v_add_u32_e32 v116, 0x1800, v133
	v_and_b32_e32 v117, 0x3ffff000, v116
	v_and_b32_e32 v116, 0xfc0, v116
	v_lshl_add_u32 v117, v117, 2, 0
	v_lshlrev_b32_e32 v116, 2, v116
	v_add3_u32 v132, v117, v116, v132
	ds_read_b128 v[128:131], v132 offset:25600
	ds_read_b128 v[120:123], v132 offset:58368
	v_add_u32_e32 v116, v134, v116
	ds_read_b128 v[124:127], v116
	s_waitcnt lgkmcnt(2)
	v_mul_f32_e32 v116, 0x3fb8aa3b, v128
	v_exp_f32_e32 v116, v116
	v_add_f32_e32 v117, v128, v128
	v_cmp_nlt_f32_e32 vcc, s79, v117
	s_and_saveexec_b64 s[6:7], vcc
	s_xor_b64 s[6:7], exec, s[6:7]
	v_fma_f32 v128, -v116, v116, 1.0
	s_andn2_saveexec_b64 s[6:7], s[6:7]
	v_fmamk_f32 v118, v117, 0x3c088889, v148
	v_fmaak_f32 v118, v117, v118, 0x3e2aaaab
	v_fma_f32 v118, v117, v118, 0.5
	v_fma_f32 v118, v117, v118, 1.0
	v_mul_f32_e64 v128, v118, -v117
	s_or_b64 exec, exec, s[6:7]
	v_mul_f32_e32 v117, 0x3fb8aa3b, v129
	v_exp_f32_e32 v117, v117
	v_add_f32_e32 v118, v129, v129
	v_cmp_nlt_f32_e32 vcc, s79, v118
	s_and_saveexec_b64 s[6:7], vcc
	s_xor_b64 s[6:7], exec, s[6:7]
	v_fma_f32 v129, -v117, v117, 1.0
	s_andn2_saveexec_b64 s[6:7], s[6:7]
	v_fmamk_f32 v119, v118, 0x3c088889, v148
	v_fmaak_f32 v119, v118, v119, 0x3e2aaaab
	v_fma_f32 v119, v118, v119, 0.5
	v_fma_f32 v119, v118, v119, 1.0
	v_mul_f32_e64 v129, v119, -v118
	s_or_b64 exec, exec, s[6:7]
	v_mul_f32_e32 v118, 0x3fb8aa3b, v130
	v_exp_f32_e32 v118, v118
	v_add_f32_e32 v119, v130, v130
	v_cmp_nlt_f32_e32 vcc, s79, v119
	s_and_saveexec_b64 s[6:7], vcc
	s_xor_b64 s[6:7], exec, s[6:7]
	v_fma_f32 v130, -v118, v118, 1.0
	s_andn2_saveexec_b64 s[6:7], s[6:7]
	v_fmamk_f32 v130, v119, 0x3c088889, v148
	v_fmaak_f32 v130, v119, v130, 0x3e2aaaab
	v_fma_f32 v130, v119, v130, 0.5
	v_fma_f32 v130, v119, v130, 1.0
	v_mul_f32_e64 v130, v130, -v119
	s_or_b64 exec, exec, s[6:7]
	v_mul_f32_e32 v119, 0x3fb8aa3b, v131
	v_exp_f32_e32 v119, v119
	v_add_f32_e32 v133, v131, v131
	v_cmp_nlt_f32_e32 vcc, s79, v133
	s_and_saveexec_b64 s[6:7], vcc
	s_xor_b64 s[6:7], exec, s[6:7]
	v_fma_f32 v131, -v119, v119, 1.0
	s_andn2_saveexec_b64 s[6:7], s[6:7]
	v_fmamk_f32 v131, v133, 0x3c088889, v148
	v_fmaak_f32 v131, v133, v131, 0x3e2aaaab
	v_fma_f32 v131, v133, v131, 0.5
	v_fma_f32 v131, v133, v131, 1.0
	v_mul_f32_e64 v131, v131, -v133
	s_or_b64 exec, exec, s[6:7]
	v_max_f32_e32 v128, v128, v128
	v_max_f32_e32 v128, 0, v128
	v_sqrt_f32_e32 v128, v128
	v_max_f32_e32 v129, v129, v129
	v_max_f32_e32 v129, 0, v129
	v_sqrt_f32_e32 v129, v129
	s_waitcnt lgkmcnt(1)
	v_mul_f32_e32 v120, v120, v128
	v_max_f32_e32 v128, v130, v130
	s_waitcnt lgkmcnt(0)
	v_mul_f32_e32 v120, v124, v120
	v_max_f32_e32 v124, v131, v131
	v_max_f32_e32 v128, 0, v128
	v_max_f32_e32 v124, 0, v124
	v_sqrt_f32_e32 v128, v128
	v_sqrt_f32_e32 v124, v124
	v_ashrrev_i32_e32 v156, 7, v152
	v_mul_f32_e32 v121, v121, v129
	v_mul_f32_e32 v122, v122, v128
	v_and_b32_e32 v172, 0x7f, v152
	v_mul_f32_e32 v123, v123, v124
	v_lshlrev_b32_e32 v146, 4, v156
	v_mul_f32_e32 v121, v125, v121
	v_mul_f32_e32 v122, v126, v122
	v_bfe_u32 v153, v152, 6, 1
	v_mul_f32_e32 v123, v127, v123
	ds_write_b128 v132, v[116:119] offset:25600
	ds_write_b128 v132, v[120:123] offset:58368
	v_and_b32_e32 v154, 63, v152
	v_sub_u32_e32 v116, 63, v146
	v_cmp_gt_u32_e32 vcc, 64, v172
	v_or_b32_e32 v118, 1, v146
	v_lshl_or_b32 v147, v153, 12, v154
	v_cndmask_b32_e32 v155, v116, v146, vcc
	v_sub_u32_e32 v119, 63, v118
	v_or_b32_e32 v120, 2, v146
	v_lshl_add_u32 v116, v155, 6, v147
	v_cndmask_b32_e32 v157, v119, v118, vcc
	v_sub_u32_e32 v121, 63, v120
	v_or_b32_e32 v122, 3, v146
	v_lshl_add_u32 v116, v116, 2, 0
	v_lshl_add_u32 v118, v157, 6, v147
	v_cndmask_b32_e32 v158, v121, v120, vcc
	v_sub_u32_e32 v123, 63, v122
	v_or_b32_e32 v124, 4, v146
	s_waitcnt lgkmcnt(0)
	s_barrier
	ds_read2st64_b32 v[116:117], v116 offset0:100 offset1:228
	v_lshl_add_u32 v118, v118, 2, 0
	v_lshl_add_u32 v120, v158, 6, v147
	v_cndmask_b32_e32 v159, v123, v122, vcc
	v_sub_u32_e32 v125, 63, v124
	v_or_b32_e32 v126, 5, v146
	ds_read2st64_b32 v[118:119], v118 offset0:100 offset1:228
	v_lshl_add_u32 v120, v120, 2, 0
	v_lshl_add_u32 v122, v159, 6, v147
	v_cndmask_b32_e32 v160, v125, v124, vcc
	v_sub_u32_e32 v127, 63, v126
	v_or_b32_e32 v128, 6, v146
	ds_read2st64_b32 v[120:121], v120 offset0:100 offset1:228
	v_lshl_add_u32 v122, v122, 2, 0
	v_lshl_add_u32 v124, v160, 6, v147
	v_cndmask_b32_e32 v161, v127, v126, vcc
	v_sub_u32_e32 v129, 63, v128
	v_or_b32_e32 v130, 7, v146
	ds_read2st64_b32 v[122:123], v122 offset0:100 offset1:228
	v_lshl_add_u32 v124, v124, 2, 0
	v_lshl_add_u32 v126, v161, 6, v147
	v_cndmask_b32_e32 v162, v129, v128, vcc
	v_sub_u32_e32 v131, 63, v130
	v_or_b32_e32 v132, 8, v146
	ds_read2st64_b32 v[124:125], v124 offset0:100 offset1:228
	v_lshl_add_u32 v126, v126, 2, 0
	v_lshl_add_u32 v128, v162, 6, v147
	v_cndmask_b32_e32 v163, v131, v130, vcc
	v_sub_u32_e32 v133, 63, v132
	v_or_b32_e32 v134, 9, v146
	ds_read2st64_b32 v[126:127], v126 offset0:100 offset1:228
	v_lshl_add_u32 v128, v128, 2, 0
	v_lshl_add_u32 v130, v163, 6, v147
	v_cndmask_b32_e32 v164, v133, v132, vcc
	v_sub_u32_e32 v135, 63, v134
	v_or_b32_e32 v136, 10, v146
	s_waitcnt lgkmcnt(5)
	v_fma_f32 v173, 0, v116, v117
	ds_read2st64_b32 v[128:129], v128 offset0:100 offset1:228
	v_lshl_add_u32 v130, v130, 2, 0
	v_lshl_add_u32 v132, v164, 6, v147
	v_cndmask_b32_e32 v165, v135, v134, vcc
	v_sub_u32_e32 v137, 63, v136
	v_or_b32_e32 v138, 11, v146
	s_waitcnt lgkmcnt(5)
	v_fma_f32 v173, v173, v118, v119
	ds_read2st64_b32 v[130:131], v130 offset0:100 offset1:228
	v_lshl_add_u32 v132, v132, 2, 0
	v_lshl_add_u32 v134, v165, 6, v147
	v_cndmask_b32_e32 v166, v137, v136, vcc
	v_sub_u32_e32 v139, 63, v138
	v_or_b32_e32 v140, 12, v146
	v_mul_f32_e32 v174, v116, v118
	s_waitcnt lgkmcnt(5)
	v_fma_f32 v173, v173, v120, v121
	ds_read2st64_b32 v[132:133], v132 offset0:100 offset1:228
	v_lshl_add_u32 v134, v134, 2, 0
	v_lshl_add_u32 v136, v166, 6, v147
	v_cndmask_b32_e32 v167, v139, v138, vcc
	v_sub_u32_e32 v141, 63, v140
	v_or_b32_e32 v142, 13, v146
	v_mul_f32_e32 v174, v174, v120
	s_waitcnt lgkmcnt(5)
	v_fma_f32 v173, v173, v122, v123
	ds_read2st64_b32 v[134:135], v134 offset0:100 offset1:228
	v_lshl_add_u32 v136, v136, 2, 0
	v_lshl_add_u32 v138, v167, 6, v147
	v_cndmask_b32_e32 v168, v141, v140, vcc
	v_sub_u32_e32 v143, 63, v142
	v_or_b32_e32 v144, 14, v146
	v_mul_f32_e32 v174, v174, v122
	s_waitcnt lgkmcnt(5)
	v_fma_f32 v173, v173, v124, v125
	ds_read2st64_b32 v[136:137], v136 offset0:100 offset1:228
	v_lshl_add_u32 v138, v138, 2, 0
	v_lshl_add_u32 v140, v168, 6, v147
	v_cndmask_b32_e32 v169, v143, v142, vcc
	v_sub_u32_e32 v145, 63, v144
	v_or_b32_e32 v146, 15, v146
	v_mul_f32_e32 v174, v174, v124
	s_waitcnt lgkmcnt(5)
	v_fma_f32 v173, v173, v126, v127
	ds_read2st64_b32 v[138:139], v138 offset0:100 offset1:228
	v_lshl_add_u32 v140, v140, 2, 0
	v_lshl_add_u32 v142, v169, 6, v147
	v_cndmask_b32_e32 v170, v145, v144, vcc
	v_sub_u32_e32 v171, 63, v146
	v_mul_f32_e32 v174, v174, v126
	s_waitcnt lgkmcnt(5)
	v_fma_f32 v173, v173, v128, v129
	ds_read2st64_b32 v[140:141], v140 offset0:100 offset1:228
	v_lshl_add_u32 v142, v142, 2, 0
	v_lshl_add_u32 v144, v170, 6, v147
	v_cndmask_b32_e32 v171, v171, v146, vcc
	v_mul_f32_e32 v174, v174, v128
	s_waitcnt lgkmcnt(5)
	v_fma_f32 v173, v173, v130, v131
	ds_read2st64_b32 v[142:143], v142 offset0:100 offset1:228
	v_lshl_add_u32 v144, v144, 2, 0
	v_lshl_add_u32 v146, v171, 6, v147
	v_mul_f32_e32 v174, v174, v130
	s_waitcnt lgkmcnt(5)
	v_fma_f32 v173, v173, v132, v133
	ds_read2st64_b32 v[144:145], v144 offset0:100 offset1:228
	v_lshl_add_u32 v146, v146, 2, 0
	v_mul_f32_e32 v174, v174, v132
	s_waitcnt lgkmcnt(5)
	v_fma_f32 v173, v173, v134, v135
	ds_read2st64_b32 v[146:147], v146 offset0:100 offset1:228
	v_mul_f32_e32 v174, v174, v134
	s_waitcnt lgkmcnt(5)
	v_fma_f32 v173, v173, v136, v137
	v_mul_f32_e32 v174, v174, v136
	s_waitcnt lgkmcnt(4)
	v_fma_f32 v173, v173, v138, v139
	v_mul_f32_e32 v174, v174, v138
	s_waitcnt lgkmcnt(3)
	v_fma_f32 v173, v173, v140, v141
	v_mul_f32_e32 v174, v174, v140
	s_waitcnt lgkmcnt(2)
	v_fma_f32 v173, v173, v142, v143
	v_mul_f32_e32 v174, v174, v142
	s_waitcnt lgkmcnt(1)
	v_fma_f32 v173, v173, v144, v145
	v_lshl_add_u32 v152, v152, 2, 0
	v_mul_f32_e32 v174, v174, v144
	s_waitcnt lgkmcnt(0)
	v_fma_f32 v173, v173, v146, v147
	v_add_u32_e32 v175, 0x16400, v152
	v_add_u32_e32 v152, 0x16c00, v152
	v_mul_f32_e32 v174, v174, v146
	ds_write_b32 v152, v173
	v_cmp_lt_i32_e32 vcc, 0, v156
	v_lshl_add_u32 v172, v172, 2, 0
	v_mov_b32_e32 v152, v150
	ds_write_b32 v175, v174
	s_waitcnt lgkmcnt(0)
	s_barrier
	s_and_saveexec_b64 s[6:7], vcc
	s_cbranch_execnz .LBB0_774
	s_or_b64 exec, exec, s[6:7]
	v_cmp_lt_i32_e32 vcc, 1, v156
	s_and_saveexec_b64 s[6:7], vcc
	s_cbranch_execnz .LBB0_775
